# on top of v20: load-interval address prefixes hoisted into the preceding MFMA run, one per gap from the 2nd MFMA (24 sites, 90 instr)
# baseline (speedup 1.0000x reference)
; #define PG8_STAGE(bufoff, gbase) do { _Pragma("unroll") for (int _i = 0; _i < 2; ++_i) \
;         __builtin_amdgcn_global_load_lds((const unsigned*)((const char*)(gbase) + voff[_i]), (LAS unsigned*)(lds + (bufoff) + ldsw + _i * 8192), 16, 0, 0); } while (0)
; #define PG8_LDA(dst, b, h) do { _Pragma("unroll") for (int m = 0; m < 4; ++m) _Pragma("unroll") for (int k = 0; k < 2; ++k) dst[m][k] = *(const LAS bf16x8*)(lds + PG8_SA(b, h) + aoff + m * 2048 + k * 1024); } while (0)
; #define PG8_LDB(dst, b, h) do { _Pragma("unroll") for (int n = 0; n < 2; ++n) _Pragma("unroll") for (int k = 0; k < 2; ++k) dst[n][k] = *(const LAS bf16x8*)(lds + PG8_SB(b, h) + boff + n * 2048 + k * 1024); } while (0)
; #define PG8_MMA(ai, bj, At, Bt) do { __builtin_amdgcn_s_setprio(1); _Pragma("unroll") for (int m = 0; m < 4; ++m) _Pragma("unroll") for (int n = 0; n < 2; ++n) _Pragma("unroll") for (int k = 0; k < 2; ++k) \
;         acc[ai][bj][m][n] = __builtin_amdgcn_mfma_f32_16x16x32_bf16(Bt[n][k], At[m][k], acc[ai][bj][m][n], 0, 0, 0); __builtin_amdgcn_s_setprio(0); } while (0)
; #define PG8_WAIT_V(n) asm volatile("s_waitcnt vmcnt(" #n ")" ::: "memory")
; #define PG8_WAIT_L(n) asm volatile("s_waitcnt lgkmcnt(" #n ")" ::: "memory")
; #define PG8_BAR __builtin_amdgcn_s_barrier()
; #define PG8_SCHED __builtin_amdgcn_sched_barrier(0)
; template <class Epi>
; DI void gemm_phase(LAS unsigned char* lds, const Gemm g, const StaticOrder& S, const Epi& E) {
;     ...
;         for (int t = 0; t < nt; t += 2) {
;             const bool last = (t == nt - 2);
;             const char* a1 = cA + (size_t)(t + 1) * kstep;
;             const char* a2 = last ? nA : cA + (size_t)(t + 2) * kstep; const char* b2 = last ? nB : cB + (size_t)(t + 2) * kstep;
;             const char* a3 = a2 + kstep; const char* b3 = b2 + kstep;
;             PG8_LDB(B0, 0, 0); PG8_SCHED; PG8_LDA(At, 0, 0); PG8_STAGE(PG8_SA(1, 1), a1 + hstep);
;             PG8_WAIT_L(8); PG8_BAR; PG8_WAIT_L(0); PG8_MMA(0, 0, At, B0); PG8_BAR; PG8_SCHED;
;             PG8_LDB(B1, 0, 1); PG8_STAGE(PG8_SB(0, 0), b2);
;             PG8_BAR; PG8_WAIT_L(0); PG8_MMA(0, 1, At, B1); PG8_BAR;
;             PG8_LDA(At, 0, 1); PG8_STAGE(PG8_SA(0, 0), a2);
;             PG8_BAR; PG8_WAIT_L(0); PG8_MMA(1, 0, At, B0); PG8_BAR; PG8_SCHED;
;             PG8_STAGE(PG8_SB(0, 1), b2 + hstep);
;             PG8_WAIT_V(6); PG8_BAR; PG8_MMA(1, 1, At, B1); PG8_BAR;
.LBB0_37:
	s_add_u32 s20, s18, 0xfff80080
	s_addc_u32 s21, s19, -1
	s_add_i32 s39, 0, 0x10000
	v_add_u32_e32 v150, s39, v135
	ds_read_b128 v[138:141], v150
	ds_read_b128 v[142:145], v150 offset:1024
	ds_read_b128 v[146:149], v150 offset:2048
	ds_read_b128 v[150:153], v150 offset:3072
	s_cmp_eq_u32 s38, 28
	s_cselect_b32 s23, s4, s21
	s_cselect_b32 s22, s5, s20
	s_cselect_b32 s21, s9, s37
	s_cselect_b32 s20, s11, s33
	v_lshl_add_u64 v[154:155], s[18:19], 0, v[130:131]
	s_add_i32 m0, s28, 0xc000
	ds_read_b128 v[186:189], v137
	ds_read_b128 v[190:193], v137 offset:1024
	ds_read_b128 v[194:197], v137 offset:2048
	ds_read_b128 v[198:201], v137 offset:3072
	ds_read_b128 v[202:205], v137 offset:4096
	ds_read_b128 v[206:209], v137 offset:5120
	ds_read_b128 v[210:213], v137 offset:6144
	ds_read_b128 v[214:217], v137 offset:7168
	global_load_lds_dwordx4 v[154:155], off
	v_lshl_add_u64 v[154:155], s[18:19], 0, v[132:133]
	s_add_i32 m0, s28, 0xe000
	s_nop 0
	global_load_lds_dwordx4 v[154:155], off
	s_waitcnt lgkmcnt(8)
	s_setprio 1
	s_barrier
	s_waitcnt lgkmcnt(0)
	v_mfma_f32_16x16x32_bf16 v[124:127], v[138:141], v[186:189], v[124:127]
	v_mfma_f32_16x16x32_bf16 v[120:123], v[146:149], v[186:189], v[120:123]
	s_add_i32 s42, 0, 0x14000
	v_mfma_f32_16x16x32_bf16 v[108:111], v[138:141], v[194:197], v[108:111]
	v_add_u32_e32 v154, s42, v135
	v_mfma_f32_16x16x32_bf16 v[104:107], v[146:149], v[194:197], v[104:107]
	s_add_i32 s39, s39, s27
	v_mfma_f32_16x16x32_bf16 v[92:95], v[138:141], v[202:205], v[92:95]
	v_mfma_f32_16x16x32_bf16 v[88:91], v[146:149], v[202:205], v[88:91]
	v_mfma_f32_16x16x32_bf16 v[76:79], v[138:141], v[210:213], v[76:79]
	v_mfma_f32_16x16x32_bf16 v[72:75], v[146:149], v[210:213], v[72:75]
	v_mfma_f32_16x16x32_bf16 v[124:127], v[142:145], v[190:193], v[124:127]
	v_mfma_f32_16x16x32_bf16 v[120:123], v[150:153], v[190:193], v[120:123]
	v_mfma_f32_16x16x32_bf16 v[108:111], v[142:145], v[198:201], v[108:111]
	v_mfma_f32_16x16x32_bf16 v[104:107], v[150:153], v[198:201], v[104:107]
	v_mfma_f32_16x16x32_bf16 v[92:95], v[142:145], v[206:209], v[92:95]
	v_mfma_f32_16x16x32_bf16 v[88:91], v[150:153], v[206:209], v[88:91]
	v_mfma_f32_16x16x32_bf16 v[76:79], v[142:145], v[214:217], v[76:79]
	v_mfma_f32_16x16x32_bf16 v[72:75], v[150:153], v[214:217], v[72:75]
	s_setprio 0
	s_barrier
	ds_read_b128 v[226:229], v154
	ds_read_b128 v[230:233], v154 offset:1024
	ds_read_b128 v[234:237], v154 offset:2048
	ds_read_b128 v[238:241], v154 offset:3072
	v_lshl_add_u64 v[154:155], s[20:21], 0, v[158:159]
	s_mov_b32 m0, s39
	v_lshl_add_u64 v[218:219], s[20:21], 0, v[128:129]
	global_load_lds_dwordx4 v[154:155], off
	s_add_i32 m0, s39, 0x2000
	s_nop 0
	global_load_lds_dwordx4 v[218:219], off
	s_waitcnt lgkmcnt(0)
	s_setprio 1
	s_barrier
	v_mfma_f32_16x16x32_bf16 v[116:119], v[226:229], v[186:189], v[116:119]
	v_mfma_f32_16x16x32_bf16 v[112:115], v[234:237], v[186:189], v[112:115]
	v_mfma_f32_16x16x32_bf16 v[100:103], v[226:229], v[194:197], v[100:103]
	v_mfma_f32_16x16x32_bf16 v[96:99], v[234:237], v[194:197], v[96:99]
	v_mfma_f32_16x16x32_bf16 v[84:87], v[226:229], v[202:205], v[84:87]
	v_mfma_f32_16x16x32_bf16 v[80:83], v[234:237], v[202:205], v[80:83]
	v_mfma_f32_16x16x32_bf16 v[68:71], v[226:229], v[210:213], v[68:71]
	v_mfma_f32_16x16x32_bf16 v[64:67], v[234:237], v[210:213], v[64:67]
	v_mfma_f32_16x16x32_bf16 v[116:119], v[230:233], v[190:193], v[116:119]
	s_mov_b32 m0, s28
	v_mfma_f32_16x16x32_bf16 v[112:115], v[238:241], v[190:193], v[112:115]
	v_lshl_add_u64 v[220:221], s[22:23], 0, v[158:159]
	v_mfma_f32_16x16x32_bf16 v[100:103], v[230:233], v[198:201], v[100:103]
	v_mfma_f32_16x16x32_bf16 v[96:99], v[238:241], v[198:201], v[96:99]
	v_mfma_f32_16x16x32_bf16 v[84:87], v[230:233], v[206:209], v[84:87]
	v_mfma_f32_16x16x32_bf16 v[80:83], v[238:241], v[206:209], v[80:83]
	v_mfma_f32_16x16x32_bf16 v[68:71], v[230:233], v[214:217], v[68:71]
	v_mfma_f32_16x16x32_bf16 v[64:67], v[238:241], v[214:217], v[64:67]
	s_setprio 0
	s_barrier
	ds_read_b128 v[186:189], v137 offset:16384
	ds_read_b128 v[190:193], v137 offset:17408
	ds_read_b128 v[194:197], v137 offset:18432
	ds_read_b128 v[198:201], v137 offset:19456
	ds_read_b128 v[202:205], v137 offset:20480
	ds_read_b128 v[206:209], v137 offset:21504
	ds_read_b128 v[210:213], v137 offset:22528
	ds_read_b128 v[214:217], v137 offset:23552
	global_load_lds_dwordx4 v[220:221], off
	v_lshl_add_u64 v[242:243], s[22:23], 0, v[128:129]
	s_mov_b32 m0, s29
	s_nop 0
	global_load_lds_dwordx4 v[242:243], off
	s_waitcnt lgkmcnt(0)
	s_setprio 1
	s_barrier
	v_mfma_f32_16x16x32_bf16 v[60:63], v[138:141], v[186:189], v[60:63]
	v_mfma_f32_16x16x32_bf16 v[56:59], v[146:149], v[186:189], v[56:59]
	s_add_u32 s40, s20, 0x80000
	v_mfma_f32_16x16x32_bf16 v[44:47], v[138:141], v[194:197], v[44:47]
	s_addc_u32 s41, s21, 0
	v_mfma_f32_16x16x32_bf16 v[40:43], v[146:149], v[194:197], v[40:43]
	s_add_i32 s39, s42, s27
	v_mfma_f32_16x16x32_bf16 v[28:31], v[138:141], v[202:205], v[28:31]
	v_mfma_f32_16x16x32_bf16 v[24:27], v[146:149], v[202:205], v[24:27]
	v_mfma_f32_16x16x32_bf16 v[12:15], v[138:141], v[210:213], v[12:15]
	v_mfma_f32_16x16x32_bf16 v[8:11], v[146:149], v[210:213], v[8:11]
	v_mfma_f32_16x16x32_bf16 v[60:63], v[142:145], v[190:193], v[60:63]
	v_mfma_f32_16x16x32_bf16 v[56:59], v[150:153], v[190:193], v[56:59]
	v_mfma_f32_16x16x32_bf16 v[44:47], v[142:145], v[198:201], v[44:47]
	v_mfma_f32_16x16x32_bf16 v[40:43], v[150:153], v[198:201], v[40:43]
	v_mfma_f32_16x16x32_bf16 v[28:31], v[142:145], v[206:209], v[28:31]
	v_mfma_f32_16x16x32_bf16 v[24:27], v[150:153], v[206:209], v[24:27]
	v_mfma_f32_16x16x32_bf16 v[12:15], v[142:145], v[214:217], v[12:15]
	v_mfma_f32_16x16x32_bf16 v[8:11], v[150:153], v[214:217], v[8:11]
	s_setprio 0
	s_barrier
; #define PG8_STAGE(bufoff, gbase) do { _Pragma("unroll") for (int _i = 0; _i < 2; ++_i) \
;         __builtin_amdgcn_global_load_lds((const unsigned*)((const char*)(gbase) + voff[_i]), (LAS unsigned*)(lds + (bufoff) + ldsw + _i * 8192), 16, 0, 0); } while (0)
; #define PG8_LDA(dst, b, h) do { _Pragma("unroll") for (int m = 0; m < 4; ++m) _Pragma("unroll") for (int k = 0; k < 2; ++k) dst[m][k] = *(const LAS bf16x8*)(lds + PG8_SA(b, h) + aoff + m * 2048 + k * 1024); } while (0)
; #define PG8_LDB(dst, b, h) do { _Pragma("unroll") for (int n = 0; n < 2; ++n) _Pragma("unroll") for (int k = 0; k < 2; ++k) dst[n][k] = *(const LAS bf16x8*)(lds + PG8_SB(b, h) + boff + n * 2048 + k * 1024); } while (0)
; #define PG8_MMA(ai, bj, At, Bt) do { __builtin_amdgcn_s_setprio(1); _Pragma("unroll") for (int m = 0; m < 4; ++m) _Pragma("unroll") for (int n = 0; n < 2; ++n) _Pragma("unroll") for (int k = 0; k < 2; ++k) \
;         acc[ai][bj][m][n] = __builtin_amdgcn_mfma_f32_16x16x32_bf16(Bt[n][k], At[m][k], acc[ai][bj][m][n], 0, 0, 0); __builtin_amdgcn_s_setprio(0); } while (0)
; #define PG8_WAIT_V(n) asm volatile("s_waitcnt vmcnt(" #n ")" ::: "memory")
; #define PG8_WAIT_L(n) asm volatile("s_waitcnt lgkmcnt(" #n ")" ::: "memory")
; #define PG8_BAR __builtin_amdgcn_s_barrier()
; #define PG8_SCHED __builtin_amdgcn_sched_barrier(0)
; template <class Epi>
; DI void gemm_phase(LAS unsigned char* lds, const Gemm g, const StaticOrder& S, const Epi& E) {
;     ...
;             PG8_STAGE(PG8_SB(0, 1), b2 + hstep);
;             PG8_WAIT_V(6); PG8_BAR; PG8_MMA(1, 1, At, B1); PG8_BAR;
;             PG8_LDB(B0, 1, 0); PG8_SCHED; PG8_LDA(At, 1, 0); PG8_STAGE(PG8_SA(0, 1), a2 + hstep);
;             PG8_WAIT_L(8); PG8_BAR; PG8_WAIT_L(0); PG8_MMA(0, 0, At, B0); PG8_BAR; PG8_SCHED;
;             PG8_LDB(B1, 1, 1); PG8_STAGE(PG8_SB(1, 0), b3);
;             PG8_BAR; PG8_WAIT_L(0); PG8_MMA(0, 1, At, B1); PG8_BAR;
;             PG8_LDA(At, 1, 1); PG8_STAGE(PG8_SA(1, 0), a3);
;             PG8_BAR; PG8_WAIT_L(0); PG8_MMA(1, 0, At, B0); PG8_BAR; PG8_SCHED;
	v_lshl_add_u64 v[138:139], s[40:41], 0, v[158:159]
	s_mov_b32 m0, s39
	s_nop 0
	global_load_lds_dwordx4 v[138:139], off
	v_lshl_add_u64 v[138:139], s[40:41], 0, v[128:129]
	s_add_i32 m0, s39, 0x2000
	s_nop 0
	global_load_lds_dwordx4 v[138:139], off
	s_waitcnt vmcnt(6)
	s_setprio 1
	s_barrier
	v_mfma_f32_16x16x32_bf16 v[52:55], v[226:229], v[186:189], v[52:55]
	v_mfma_f32_16x16x32_bf16 v[48:51], v[234:237], v[186:189], v[48:51]
	v_mfma_f32_16x16x32_bf16 v[36:39], v[226:229], v[194:197], v[36:39]
	v_mfma_f32_16x16x32_bf16 v[32:35], v[234:237], v[194:197], v[32:35]
	v_mfma_f32_16x16x32_bf16 v[20:23], v[226:229], v[202:205], v[20:23]
	v_mfma_f32_16x16x32_bf16 v[16:19], v[234:237], v[202:205], v[16:19]
	v_mfma_f32_16x16x32_bf16 v[4:7], v[226:229], v[210:213], v[4:7]
	v_mfma_f32_16x16x32_bf16 v[0:3], v[234:237], v[210:213], v[0:3]
	v_mfma_f32_16x16x32_bf16 v[52:55], v[230:233], v[190:193], v[52:55]
	s_add_i32 s39, 0, 0x18000
	v_mfma_f32_16x16x32_bf16 v[48:51], v[238:241], v[190:193], v[48:51]
	v_add_u32_e32 v150, s39, v135
	v_mfma_f32_16x16x32_bf16 v[36:39], v[230:233], v[198:201], v[36:39]
	v_mfma_f32_16x16x32_bf16 v[32:35], v[238:241], v[198:201], v[32:35]
	v_mfma_f32_16x16x32_bf16 v[20:23], v[230:233], v[206:209], v[20:23]
	v_mfma_f32_16x16x32_bf16 v[16:19], v[238:241], v[206:209], v[16:19]
	v_mfma_f32_16x16x32_bf16 v[4:7], v[230:233], v[214:217], v[4:7]
	v_mfma_f32_16x16x32_bf16 v[0:3], v[238:241], v[214:217], v[0:3]
	s_setprio 0
	s_barrier
	ds_read_b128 v[138:141], v150
	ds_read_b128 v[142:145], v150 offset:1024
	ds_read_b128 v[146:149], v150 offset:2048
	ds_read_b128 v[150:153], v150 offset:3072
	s_add_u32 s22, s22, 0x80000
	s_addc_u32 s23, s23, 0
	s_mov_b32 m0, s30
	v_lshl_add_u64 v[226:227], s[22:23], 0, v[158:159]
	ds_read_b128 v[186:189], v137 offset:32768
	ds_read_b128 v[190:193], v137 offset:33792
	ds_read_b128 v[194:197], v137 offset:34816
	ds_read_b128 v[198:201], v137 offset:35840
	ds_read_b128 v[202:205], v137 offset:36864
	ds_read_b128 v[206:209], v137 offset:37888
	ds_read_b128 v[210:213], v137 offset:38912
	ds_read_b128 v[214:217], v137 offset:39936
	global_load_lds_dwordx4 v[226:227], off
	v_lshl_add_u64 v[226:227], s[22:23], 0, v[128:129]
	s_mov_b32 m0, s31
	s_nop 0
	global_load_lds_dwordx4 v[226:227], off
	s_waitcnt lgkmcnt(8)
	s_setprio 1
	s_barrier
	s_waitcnt lgkmcnt(0)
	v_mfma_f32_16x16x32_bf16 v[124:127], v[138:141], v[186:189], v[124:127]
	v_mfma_f32_16x16x32_bf16 v[120:123], v[146:149], v[186:189], v[120:123]
	s_add_i32 s22, 0, 0x1c000
	v_mfma_f32_16x16x32_bf16 v[108:111], v[138:141], v[194:197], v[108:111]
	s_add_i32 s23, s39, s27
	v_mfma_f32_16x16x32_bf16 v[104:107], v[146:149], v[194:197], v[104:107]
	v_add_u32_e32 v225, s22, v135
	v_mfma_f32_16x16x32_bf16 v[92:95], v[138:141], v[202:205], v[92:95]
	v_lshl_add_u64 v[154:155], v[154:155], 0, s[94:95]
	v_mfma_f32_16x16x32_bf16 v[88:91], v[146:149], v[202:205], v[88:91]
	s_mov_b32 m0, s23
	v_mfma_f32_16x16x32_bf16 v[76:79], v[138:141], v[210:213], v[76:79]
	v_mfma_f32_16x16x32_bf16 v[72:75], v[146:149], v[210:213], v[72:75]
	v_mfma_f32_16x16x32_bf16 v[124:127], v[142:145], v[190:193], v[124:127]
	v_mfma_f32_16x16x32_bf16 v[120:123], v[150:153], v[190:193], v[120:123]
	v_mfma_f32_16x16x32_bf16 v[108:111], v[142:145], v[198:201], v[108:111]
	v_mfma_f32_16x16x32_bf16 v[104:107], v[150:153], v[198:201], v[104:107]
	v_mfma_f32_16x16x32_bf16 v[92:95], v[142:145], v[206:209], v[92:95]
	v_mfma_f32_16x16x32_bf16 v[88:91], v[150:153], v[206:209], v[88:91]
	v_mfma_f32_16x16x32_bf16 v[76:79], v[142:145], v[214:217], v[76:79]
	v_mfma_f32_16x16x32_bf16 v[72:75], v[150:153], v[214:217], v[72:75]
	s_setprio 0
	s_barrier
	ds_read_b128 v[226:229], v225
	ds_read_b128 v[230:233], v225 offset:1024
	ds_read_b128 v[234:237], v225 offset:2048
	ds_read_b128 v[238:241], v225 offset:3072
	global_load_lds_dwordx4 v[154:155], off
	v_lshl_add_u64 v[154:155], v[218:219], 0, s[94:95]
	s_add_i32 m0, s23, 0x2000
	s_nop 0
	global_load_lds_dwordx4 v[154:155], off
	s_waitcnt lgkmcnt(0)
	s_setprio 1
	s_barrier
	v_mfma_f32_16x16x32_bf16 v[116:119], v[226:229], v[186:189], v[116:119]
	v_mfma_f32_16x16x32_bf16 v[112:115], v[234:237], v[186:189], v[112:115]
	v_mfma_f32_16x16x32_bf16 v[100:103], v[226:229], v[194:197], v[100:103]
	v_mfma_f32_16x16x32_bf16 v[96:99], v[234:237], v[194:197], v[96:99]
	v_mfma_f32_16x16x32_bf16 v[84:87], v[226:229], v[202:205], v[84:87]
	v_mfma_f32_16x16x32_bf16 v[80:83], v[234:237], v[202:205], v[80:83]
	v_mfma_f32_16x16x32_bf16 v[68:71], v[226:229], v[210:213], v[68:71]
	v_mfma_f32_16x16x32_bf16 v[64:67], v[234:237], v[210:213], v[64:67]
	v_mfma_f32_16x16x32_bf16 v[116:119], v[230:233], v[190:193], v[116:119]
	s_mov_b32 m0, s34
	v_mfma_f32_16x16x32_bf16 v[112:115], v[238:241], v[190:193], v[112:115]
	v_lshl_add_u64 v[154:155], v[220:221], 0, s[94:95]
	v_mfma_f32_16x16x32_bf16 v[100:103], v[230:233], v[198:201], v[100:103]
	v_mfma_f32_16x16x32_bf16 v[96:99], v[238:241], v[198:201], v[96:99]
	v_mfma_f32_16x16x32_bf16 v[84:87], v[230:233], v[206:209], v[84:87]
	v_mfma_f32_16x16x32_bf16 v[80:83], v[238:241], v[206:209], v[80:83]
	v_mfma_f32_16x16x32_bf16 v[68:71], v[230:233], v[214:217], v[68:71]
	v_mfma_f32_16x16x32_bf16 v[64:67], v[238:241], v[214:217], v[64:67]
	s_setprio 0
	s_barrier
	ds_read_b128 v[186:189], v137 offset:49152
	ds_read_b128 v[190:193], v137 offset:50176
	ds_read_b128 v[194:197], v137 offset:51200
	ds_read_b128 v[198:201], v137 offset:52224
	ds_read_b128 v[202:205], v137 offset:53248
	ds_read_b128 v[206:209], v137 offset:54272
	ds_read_b128 v[210:213], v137 offset:55296
	ds_read_b128 v[214:217], v137 offset:56320
	global_load_lds_dwordx4 v[154:155], off
	v_lshl_add_u64 v[154:155], v[242:243], 0, s[94:95]
	s_mov_b32 m0, s35
	s_nop 0
	global_load_lds_dwordx4 v[154:155], off
	s_waitcnt lgkmcnt(0)
	s_setprio 1
	s_barrier
; #define PG8_STAGE(bufoff, gbase) do { _Pragma("unroll") for (int _i = 0; _i < 2; ++_i) \
;         __builtin_amdgcn_global_load_lds((const unsigned*)((const char*)(gbase) + voff[_i]), (LAS unsigned*)(lds + (bufoff) + ldsw + _i * 8192), 16, 0, 0); } while (0)
; #define PG8_MMA(ai, bj, At, Bt) do { __builtin_amdgcn_s_setprio(1); _Pragma("unroll") for (int m = 0; m < 4; ++m) _Pragma("unroll") for (int n = 0; n < 2; ++n) _Pragma("unroll") for (int k = 0; k < 2; ++k) \
;         acc[ai][bj][m][n] = __builtin_amdgcn_mfma_f32_16x16x32_bf16(Bt[n][k], At[m][k], acc[ai][bj][m][n], 0, 0, 0); __builtin_amdgcn_s_setprio(0); } while (0)
; #define PG8_WAIT_V(n) asm volatile("s_waitcnt vmcnt(" #n ")" ::: "memory")
; #define PG8_WAIT_L(n) asm volatile("s_waitcnt lgkmcnt(" #n ")" ::: "memory")
; #define PG8_BAR __builtin_amdgcn_s_barrier()
; #define PG8_SCHED __builtin_amdgcn_sched_barrier(0)
; template <class Epi>
; DI void gemm_phase(LAS unsigned char* lds, const Gemm g, const StaticOrder& S, const Epi& E) {
;     ...
;             PG8_BAR; PG8_WAIT_L(0); PG8_MMA(1, 0, At, B0); PG8_BAR; PG8_SCHED;
;             PG8_STAGE(PG8_SB(1, 1), b3 + hstep);
;             PG8_WAIT_V(6); PG8_BAR; PG8_MMA(1, 1, At, B1); PG8_BAR;
;     DI void operator()(const f32x4 (&acc)[2][2][4][2], const Unit& u, int wr, int wc, int fr, int fq) const {
;     ...
;             for (int m = 0; m < 4; ++m) { float hv[8];
; #pragma unroll
;                 for (int n = 0; n < 2; ++n)
; #pragma unroll
;                     for (int e = 0; e < 4; ++e) { const float gt = acc[ai][0][m][n][e], up = acc[ai][1][m][n][e];
;                         hv[n * 4 + e] = gt * __builtin_amdgcn_rcpf(1.f + __builtin_amdgcn_exp2f(-1.4426950408889634f * gt)) * up; }
;                 *(u32x4*)(H + (size_t)(row0 + ai * HALF + m * 16) * DFF + col0) = (u32x4){pk(hv[0], hv[1]), pk(hv[2], hv[3]), pk(hv[4], hv[5]), pk(hv[6], hv[7])}; }
	v_mfma_f32_16x16x32_bf16 v[60:63], v[138:141], v[186:189], v[60:63]
	v_mfma_f32_16x16x32_bf16 v[56:59], v[146:149], v[186:189], v[56:59]
	s_add_u32 s20, s20, 0x80080
	v_mfma_f32_16x16x32_bf16 v[44:47], v[138:141], v[194:197], v[44:47]
	s_addc_u32 s21, s21, 0
	v_mfma_f32_16x16x32_bf16 v[40:43], v[146:149], v[194:197], v[40:43]
	s_add_i32 s22, s22, s27
	v_mfma_f32_16x16x32_bf16 v[28:31], v[138:141], v[202:205], v[28:31]
	v_mfma_f32_16x16x32_bf16 v[24:27], v[146:149], v[202:205], v[24:27]
	v_mfma_f32_16x16x32_bf16 v[12:15], v[138:141], v[210:213], v[12:15]
	v_mfma_f32_16x16x32_bf16 v[8:11], v[146:149], v[210:213], v[8:11]
	v_mfma_f32_16x16x32_bf16 v[60:63], v[142:145], v[190:193], v[60:63]
	v_mfma_f32_16x16x32_bf16 v[56:59], v[150:153], v[190:193], v[56:59]
	v_mfma_f32_16x16x32_bf16 v[44:47], v[142:145], v[198:201], v[44:47]
	v_mfma_f32_16x16x32_bf16 v[40:43], v[150:153], v[198:201], v[40:43]
	v_mfma_f32_16x16x32_bf16 v[28:31], v[142:145], v[206:209], v[28:31]
	v_mfma_f32_16x16x32_bf16 v[24:27], v[150:153], v[206:209], v[24:27]
	v_mfma_f32_16x16x32_bf16 v[12:15], v[142:145], v[214:217], v[12:15]
	v_mfma_f32_16x16x32_bf16 v[8:11], v[150:153], v[214:217], v[8:11]
	s_setprio 0
	s_barrier
	v_lshl_add_u64 v[138:139], s[20:21], 0, v[158:159]
	s_mov_b32 m0, s22
	s_nop 0
	global_load_lds_dwordx4 v[138:139], off
	v_lshl_add_u64 v[138:139], s[20:21], 0, v[128:129]
	s_add_i32 m0, s22, 0x2000
	s_nop 0
	global_load_lds_dwordx4 v[138:139], off
	s_waitcnt vmcnt(6)
	s_setprio 1
	s_barrier
	v_mfma_f32_16x16x32_bf16 v[52:55], v[226:229], v[186:189], v[52:55]
	v_mfma_f32_16x16x32_bf16 v[48:51], v[234:237], v[186:189], v[48:51]
	v_mfma_f32_16x16x32_bf16 v[36:39], v[226:229], v[194:197], v[36:39]
	v_mfma_f32_16x16x32_bf16 v[32:35], v[234:237], v[194:197], v[32:35]
	v_mfma_f32_16x16x32_bf16 v[20:23], v[226:229], v[202:205], v[20:23]
	v_mfma_f32_16x16x32_bf16 v[16:19], v[234:237], v[202:205], v[16:19]
	v_mfma_f32_16x16x32_bf16 v[4:7], v[226:229], v[210:213], v[4:7]
	v_mfma_f32_16x16x32_bf16 v[0:3], v[234:237], v[210:213], v[0:3]
	v_mfma_f32_16x16x32_bf16 v[52:55], v[230:233], v[190:193], v[52:55]
	s_add_i32 s38, s38, 2
	v_mfma_f32_16x16x32_bf16 v[48:51], v[238:241], v[190:193], v[48:51]
	s_add_u32 s18, s18, 0x100
	v_mfma_f32_16x16x32_bf16 v[36:39], v[230:233], v[198:201], v[36:39]
	s_addc_u32 s19, s19, 0
	v_mfma_f32_16x16x32_bf16 v[32:35], v[238:241], v[198:201], v[32:35]
	s_add_u32 s33, s33, 0x100
	v_mfma_f32_16x16x32_bf16 v[20:23], v[230:233], v[206:209], v[20:23]
	s_addc_u32 s37, s37, 0
	v_mfma_f32_16x16x32_bf16 v[16:19], v[238:241], v[206:209], v[16:19]
	s_cmp_gt_u32 s38, 29
	v_mfma_f32_16x16x32_bf16 v[4:7], v[230:233], v[214:217], v[4:7]
	v_mfma_f32_16x16x32_bf16 v[0:3], v[238:241], v[214:217], v[0:3]
	s_setprio 0
	s_barrier
	s_cbranch_scc0 .LBB0_37
	v_mul_f32_e32 v139, 0xbfb8aa3b, v124
	v_exp_f32_e32 v139, v139
	v_lshl_or_b32 v140, s2, 7, v136
	v_lshl_add_u32 v138, s3, 8, v134
	v_ashrrev_i32_e32 v141, 31, v140
	v_add_f32_e32 v139, 1.0, v139
	v_rcp_f32_e32 v142, v139
	v_mul_f32_e32 v139, 0xbfb8aa3b, v125
	v_exp_f32_e32 v139, v139
	s_movk_i32 s4, 0x2c00
	s_and_b64 vcc, exec, s[6:7]
	s_mov_b64 s[20:21], s[16:17]
	v_add_f32_e32 v139, 1.0, v139
	v_rcp_f32_e32 v143, v139
	v_mul_f32_e32 v139, 0xbfb8aa3b, v126
	v_exp_f32_e32 v139, v139
	s_mov_b64 s[18:19], s[14:15]
	v_pk_mul_f32 v[124:125], v[124:125], v[142:143]
	v_add_f32_e32 v139, 1.0, v139
	v_rcp_f32_e32 v144, v139
	v_mul_f32_e32 v139, 0xbfb8aa3b, v127
	v_exp_f32_e32 v139, v139
	v_pk_mul_f32 v[116:117], v[124:125], v[116:117]
	v_add_f32_e32 v139, 1.0, v139
	v_rcp_f32_e32 v145, v139
	v_mul_f32_e32 v139, 0xbfb8aa3b, v120
	v_exp_f32_e32 v139, v139
	v_cvt_pk_bf16_f32 v116, v116, v117
	v_pk_mul_f32 v[124:125], v[126:127], v[144:145]
	v_add_f32_e32 v139, 1.0, v139
	v_rcp_f32_e32 v146, v139
	v_mul_f32_e32 v139, 0xbfb8aa3b, v121
	v_exp_f32_e32 v139, v139
	v_pk_mul_f32 v[118:119], v[124:125], v[118:119]
	v_add_f32_e32 v139, 1.0, v139
	v_rcp_f32_e32 v147, v139
	v_mul_f32_e32 v139, 0xbfb8aa3b, v122
	v_exp_f32_e32 v139, v139
	v_cvt_pk_bf16_f32 v117, v118, v119
	v_pk_mul_f32 v[118:119], v[120:121], v[146:147]
	v_add_f32_e32 v139, 1.0, v139
	v_rcp_f32_e32 v148, v139
	v_mul_f32_e32 v139, 0xbfb8aa3b, v123
	v_exp_f32_e32 v139, v139
	v_pk_mul_f32 v[112:113], v[118:119], v[112:113]
	v_add_f32_e32 v139, 1.0, v139
	v_rcp_f32_e32 v149, v139
	v_cvt_pk_bf16_f32 v118, v112, v113
	v_pk_mul_f32 v[112:113], v[122:123], v[148:149]
	s_nop 0
	v_pk_mul_f32 v[112:113], v[112:113], v[114:115]
	v_lshlrev_b64 v[114:115], 1, v[140:141]
	v_cvt_pk_bf16_f32 v119, v112, v113
	v_mov_b64_e32 v[112:113], s[54:55]
	v_mad_i64_i32 v[120:121], s[2:3], v138, s4, v[112:113]
	v_lshl_add_u64 v[120:121], v[120:121], 0, v[114:115]
	global_store_dwordx4 v[120:121], v[116:119], off
	v_mul_f32_e32 v120, 0xbfb8aa3b, v104
	v_mul_f32_e32 v121, 0xbfb8aa3b, v105
	v_mul_f32_e32 v116, 0xbfb8aa3b, v108
	v_mul_f32_e32 v117, 0xbfb8aa3b, v109
	v_exp_f32_e32 v116, v116
	v_exp_f32_e32 v117, v117
	v_mul_f32_e32 v118, 0xbfb8aa3b, v110
	v_mul_f32_e32 v119, 0xbfb8aa3b, v111
	v_exp_f32_e32 v118, v118
	v_exp_f32_e32 v119, v119
	v_exp_f32_e32 v120, v120
	v_exp_f32_e32 v121, v121
	v_add_f32_e32 v116, 1.0, v116
	v_add_f32_e32 v117, 1.0, v117
	v_mul_f32_e32 v122, 0xbfb8aa3b, v106
	v_mul_f32_e32 v123, 0xbfb8aa3b, v107
	v_rcp_f32_e32 v116, v116
	v_rcp_f32_e32 v117, v117
	v_add_f32_e32 v118, 1.0, v118
	v_add_f32_e32 v119, 1.0, v119
	v_exp_f32_e32 v122, v122
	v_exp_f32_e32 v123, v123
	v_rcp_f32_e32 v118, v118
	v_rcp_f32_e32 v119, v119
	v_add_f32_e32 v120, 1.0, v120
	v_add_f32_e32 v121, 1.0, v121
	v_rcp_f32_e32 v120, v120
	v_rcp_f32_e32 v121, v121
	v_add_f32_e32 v122, 1.0, v122
;     DI void operator()(const f32x4 (&acc)[2][2][4][2], const Unit& u, int wr, int wc, int fr, int fq) const {
;     ...
;             for (int m = 0; m < 4; ++m) { float hv[8];
; #pragma unroll
;                 for (int n = 0; n < 2; ++n)
; #pragma unroll
;                     for (int e = 0; e < 4; ++e) { const float gt = acc[ai][0][m][n][e], up = acc[ai][1][m][n][e];
;                         hv[n * 4 + e] = gt * __builtin_amdgcn_rcpf(1.f + __builtin_amdgcn_exp2f(-1.4426950408889634f * gt)) * up; }
;                 *(u32x4*)(H + (size_t)(row0 + ai * HALF + m * 16) * DFF + col0) = (u32x4){pk(hv[0], hv[1]), pk(hv[2], hv[3]), pk(hv[4], hv[5]), pk(hv[6], hv[7])}; }
	v_add_f32_e32 v123, 1.0, v123
	v_pk_mul_f32 v[108:109], v[108:109], v[116:117]
	v_rcp_f32_e32 v122, v122
	v_rcp_f32_e32 v123, v123
	v_pk_mul_f32 v[100:101], v[108:109], v[100:101]
	v_pk_mul_f32 v[108:109], v[110:111], v[118:119]
	v_cvt_pk_bf16_f32 v100, v100, v101
	v_pk_mul_f32 v[102:103], v[108:109], v[102:103]
	s_nop 0
	v_cvt_pk_bf16_f32 v101, v102, v103
	v_pk_mul_f32 v[102:103], v[104:105], v[120:121]
	s_nop 0
	v_pk_mul_f32 v[96:97], v[102:103], v[96:97]
	s_nop 0
	v_cvt_pk_bf16_f32 v102, v96, v97
	v_pk_mul_f32 v[96:97], v[106:107], v[122:123]
	s_nop 0
	v_pk_mul_f32 v[96:97], v[96:97], v[98:99]
	v_mul_f32_e32 v98, 0xbfb8aa3b, v94
	v_cvt_pk_bf16_f32 v103, v96, v97
	v_or_b32_e32 v96, 16, v138
	v_mad_i64_i32 v[96:97], s[2:3], v96, s4, v[112:113]
	v_lshl_add_u64 v[96:97], v[96:97], 0, v[114:115]
	global_store_dwordx4 v[96:97], v[100:103], off
	v_mul_f32_e32 v96, 0xbfb8aa3b, v92
	v_mul_f32_e32 v97, 0xbfb8aa3b, v93
	v_exp_f32_e32 v96, v96
	v_exp_f32_e32 v97, v97
	v_mul_f32_e32 v99, 0xbfb8aa3b, v95
	v_exp_f32_e32 v98, v98
	v_exp_f32_e32 v99, v99
	v_mul_f32_e32 v100, 0xbfb8aa3b, v88
	v_mul_f32_e32 v101, 0xbfb8aa3b, v89
	v_exp_f32_e32 v100, v100
	v_exp_f32_e32 v101, v101
	v_add_f32_e32 v96, 1.0, v96
	v_add_f32_e32 v97, 1.0, v97
	v_mul_f32_e32 v102, 0xbfb8aa3b, v90
	v_mul_f32_e32 v103, 0xbfb8aa3b, v91
	v_rcp_f32_e32 v96, v96
	v_rcp_f32_e32 v97, v97
	v_add_f32_e32 v98, 1.0, v98
	v_add_f32_e32 v99, 1.0, v99
	v_exp_f32_e32 v102, v102
	v_exp_f32_e32 v103, v103
	v_rcp_f32_e32 v98, v98
	v_rcp_f32_e32 v99, v99
	v_add_f32_e32 v100, 1.0, v100
	v_add_f32_e32 v101, 1.0, v101
	v_rcp_f32_e32 v100, v100
	v_rcp_f32_e32 v101, v101
	v_add_f32_e32 v102, 1.0, v102
	v_add_f32_e32 v103, 1.0, v103
	v_pk_mul_f32 v[92:93], v[92:93], v[96:97]
	v_rcp_f32_e32 v102, v102
	v_rcp_f32_e32 v103, v103
	v_pk_mul_f32 v[84:85], v[92:93], v[84:85]
	v_pk_mul_f32 v[92:93], v[94:95], v[98:99]
	v_cvt_pk_bf16_f32 v84, v84, v85
	v_pk_mul_f32 v[86:87], v[92:93], v[86:87]
	s_nop 0
	v_cvt_pk_bf16_f32 v85, v86, v87
	v_pk_mul_f32 v[86:87], v[88:89], v[100:101]
	s_nop 0
	v_pk_mul_f32 v[80:81], v[86:87], v[80:81]
	s_nop 0
	v_cvt_pk_bf16_f32 v86, v80, v81
	v_pk_mul_f32 v[80:81], v[90:91], v[102:103]
	s_nop 0
	v_pk_mul_f32 v[80:81], v[80:81], v[82:83]
	v_mul_f32_e32 v82, 0xbfb8aa3b, v78
	v_cvt_pk_bf16_f32 v87, v80, v81
	v_or_b32_e32 v80, 32, v138
	v_mad_i64_i32 v[80:81], s[2:3], v80, s4, v[112:113]
	v_lshl_add_u64 v[80:81], v[80:81], 0, v[114:115]
	global_store_dwordx4 v[80:81], v[84:87], off
	v_mul_f32_e32 v80, 0xbfb8aa3b, v76
	v_mul_f32_e32 v81, 0xbfb8aa3b, v77
	v_exp_f32_e32 v80, v80
	v_exp_f32_e32 v81, v81
	v_mul_f32_e32 v83, 0xbfb8aa3b, v79
	v_exp_f32_e32 v82, v82
	v_exp_f32_e32 v83, v83
	v_mul_f32_e32 v84, 0xbfb8aa3b, v72
	v_mul_f32_e32 v85, 0xbfb8aa3b, v73
	v_exp_f32_e32 v84, v84
	v_exp_f32_e32 v85, v85
	v_add_f32_e32 v80, 1.0, v80
	v_add_f32_e32 v81, 1.0, v81
	v_mul_f32_e32 v86, 0xbfb8aa3b, v74
	v_mul_f32_e32 v87, 0xbfb8aa3b, v75
	v_rcp_f32_e32 v80, v80
	v_rcp_f32_e32 v81, v81
	v_add_f32_e32 v82, 1.0, v82
	v_add_f32_e32 v83, 1.0, v83
	v_exp_f32_e32 v86, v86
	v_exp_f32_e32 v87, v87
	v_rcp_f32_e32 v82, v82
	v_rcp_f32_e32 v83, v83
	v_add_f32_e32 v84, 1.0, v84
	v_add_f32_e32 v85, 1.0, v85
	v_rcp_f32_e32 v84, v84
	v_rcp_f32_e32 v85, v85
	v_add_f32_e32 v86, 1.0, v86
	v_add_f32_e32 v87, 1.0, v87
	v_pk_mul_f32 v[76:77], v[76:77], v[80:81]
	v_rcp_f32_e32 v86, v86
	v_rcp_f32_e32 v87, v87
	v_pk_mul_f32 v[68:69], v[76:77], v[68:69]
	v_pk_mul_f32 v[76:77], v[78:79], v[82:83]
	v_cvt_pk_bf16_f32 v68, v68, v69
	v_pk_mul_f32 v[70:71], v[76:77], v[70:71]
	s_nop 0
	v_cvt_pk_bf16_f32 v69, v70, v71
	v_pk_mul_f32 v[70:71], v[72:73], v[84:85]
	v_add_u32_e32 v72, 0x80, v138
	v_pk_mul_f32 v[64:65], v[70:71], v[64:65]
	s_nop 0
	v_cvt_pk_bf16_f32 v70, v64, v65
	v_pk_mul_f32 v[64:65], v[74:75], v[86:87]
	s_nop 0
	v_pk_mul_f32 v[64:65], v[64:65], v[66:67]
	v_mul_f32_e32 v66, 0xbfb8aa3b, v62
	v_cvt_pk_bf16_f32 v71, v64, v65
	v_or_b32_e32 v64, 48, v138
	v_mad_i64_i32 v[64:65], s[2:3], v64, s4, v[112:113]
	v_lshl_add_u64 v[64:65], v[64:65], 0, v[114:115]
	global_store_dwordx4 v[64:65], v[68:71], off
	v_mul_f32_e32 v64, 0xbfb8aa3b, v60
	v_mul_f32_e32 v65, 0xbfb8aa3b, v61
	v_exp_f32_e32 v64, v64
	v_exp_f32_e32 v65, v65
	v_mul_f32_e32 v67, 0xbfb8aa3b, v63
	v_exp_f32_e32 v66, v66
	v_exp_f32_e32 v67, v67
	v_mul_f32_e32 v68, 0xbfb8aa3b, v56
	v_mul_f32_e32 v69, 0xbfb8aa3b, v57
	v_exp_f32_e32 v68, v68
	v_exp_f32_e32 v69, v69
	v_add_f32_e32 v64, 1.0, v64
	v_add_f32_e32 v65, 1.0, v65
	v_mul_f32_e32 v70, 0xbfb8aa3b, v58
	v_mul_f32_e32 v71, 0xbfb8aa3b, v59
	v_rcp_f32_e32 v64, v64
	v_rcp_f32_e32 v65, v65
	v_add_f32_e32 v66, 1.0, v66
	v_add_f32_e32 v67, 1.0, v67
	v_exp_f32_e32 v70, v70
	v_exp_f32_e32 v71, v71
	v_rcp_f32_e32 v66, v66
	v_rcp_f32_e32 v67, v67
	v_add_f32_e32 v68, 1.0, v68
	v_add_f32_e32 v69, 1.0, v69
	v_rcp_f32_e32 v68, v68
	v_rcp_f32_e32 v69, v69
	v_add_f32_e32 v70, 1.0, v70
	v_add_f32_e32 v71, 1.0, v71
	v_pk_mul_f32 v[60:61], v[60:61], v[64:65]
	v_rcp_f32_e32 v70, v70
	v_rcp_f32_e32 v71, v71
	v_pk_mul_f32 v[52:53], v[60:61], v[52:53]
	v_pk_mul_f32 v[60:61], v[62:63], v[66:67]
	v_cvt_pk_bf16_f32 v52, v52, v53
	v_pk_mul_f32 v[54:55], v[60:61], v[54:55]
	s_nop 0
	v_cvt_pk_bf16_f32 v53, v54, v55
	v_pk_mul_f32 v[54:55], v[56:57], v[68:69]
; #define PG8_WAIT_V(n) asm volatile("s_waitcnt vmcnt(" #n ")" ::: "memory")
; #define PG8_BAR __builtin_amdgcn_s_barrier()
; template <class Epi>
; DI void gemm_phase(LAS unsigned char* lds, const Gemm g, const StaticOrder& S, const Epi& E) {
;     ...
;     PG8_WAIT_V(0);
;     if (wr == 0) PG8_BAR;
;     DI void operator()(const f32x4 (&acc)[2][2][4][2], const Unit& u, int wr, int wc, int fr, int fq) const {
;     ...
;                     for (int e = 0; e < 4; ++e) { const float gt = acc[ai][0][m][n][e], up = acc[ai][1][m][n][e];
;                         hv[n * 4 + e] = gt * __builtin_amdgcn_rcpf(1.f + __builtin_amdgcn_exp2f(-1.4426950408889634f * gt)) * up; }
;                 *(u32x4*)(H + (size_t)(row0 + ai * HALF + m * 16) * DFF + col0) = (u32x4){pk(hv[0], hv[1]), pk(hv[2], hv[3]), pk(hv[4], hv[5]), pk(hv[6], hv[7])}; }
	s_nop 0
	v_pk_mul_f32 v[48:49], v[54:55], v[48:49]
	s_nop 0
	v_cvt_pk_bf16_f32 v54, v48, v49
	v_pk_mul_f32 v[48:49], v[58:59], v[70:71]
	s_nop 0
	v_pk_mul_f32 v[48:49], v[48:49], v[50:51]
	v_mul_f32_e32 v50, 0xbfb8aa3b, v46
	v_cvt_pk_bf16_f32 v55, v48, v49
	v_mad_i64_i32 v[48:49], s[2:3], v72, s4, v[112:113]
	v_lshl_add_u64 v[48:49], v[48:49], 0, v[114:115]
	global_store_dwordx4 v[48:49], v[52:55], off
	v_mul_f32_e32 v48, 0xbfb8aa3b, v44
	v_mul_f32_e32 v49, 0xbfb8aa3b, v45
	v_exp_f32_e32 v48, v48
	v_exp_f32_e32 v49, v49
	v_mul_f32_e32 v51, 0xbfb8aa3b, v47
	v_exp_f32_e32 v50, v50
	v_exp_f32_e32 v51, v51
	v_mul_f32_e32 v52, 0xbfb8aa3b, v40
	v_mul_f32_e32 v53, 0xbfb8aa3b, v41
	v_exp_f32_e32 v52, v52
	v_exp_f32_e32 v53, v53
	v_add_f32_e32 v48, 1.0, v48
	v_add_f32_e32 v49, 1.0, v49
	v_mul_f32_e32 v54, 0xbfb8aa3b, v42
	v_mul_f32_e32 v55, 0xbfb8aa3b, v43
	v_rcp_f32_e32 v48, v48
	v_rcp_f32_e32 v49, v49
	v_add_f32_e32 v50, 1.0, v50
	v_add_f32_e32 v51, 1.0, v51
	v_exp_f32_e32 v54, v54
	v_exp_f32_e32 v55, v55
	v_rcp_f32_e32 v50, v50
	v_rcp_f32_e32 v51, v51
	v_add_f32_e32 v52, 1.0, v52
	v_add_f32_e32 v53, 1.0, v53
	v_rcp_f32_e32 v52, v52
	v_rcp_f32_e32 v53, v53
	v_add_f32_e32 v54, 1.0, v54
	v_add_f32_e32 v55, 1.0, v55
	v_pk_mul_f32 v[44:45], v[44:45], v[48:49]
	v_rcp_f32_e32 v54, v54
	v_rcp_f32_e32 v55, v55
	v_pk_mul_f32 v[36:37], v[44:45], v[36:37]
	v_pk_mul_f32 v[44:45], v[46:47], v[50:51]
	v_cvt_pk_bf16_f32 v36, v36, v37
	v_pk_mul_f32 v[38:39], v[44:45], v[38:39]
	s_nop 0
	v_cvt_pk_bf16_f32 v37, v38, v39
	v_pk_mul_f32 v[38:39], v[40:41], v[52:53]
	s_nop 0
	v_pk_mul_f32 v[32:33], v[38:39], v[32:33]
	s_nop 0
	v_cvt_pk_bf16_f32 v38, v32, v33
	v_pk_mul_f32 v[32:33], v[42:43], v[54:55]
	s_nop 0
	v_pk_mul_f32 v[32:33], v[32:33], v[34:35]
	v_mul_f32_e32 v34, 0xbfb8aa3b, v30
	v_cvt_pk_bf16_f32 v39, v32, v33
	v_add_u32_e32 v32, 0x90, v138
	v_mad_i64_i32 v[32:33], s[2:3], v32, s4, v[112:113]
	v_lshl_add_u64 v[32:33], v[32:33], 0, v[114:115]
	global_store_dwordx4 v[32:33], v[36:39], off
	v_mul_f32_e32 v32, 0xbfb8aa3b, v28
	v_mul_f32_e32 v33, 0xbfb8aa3b, v29
	v_exp_f32_e32 v32, v32
	v_exp_f32_e32 v33, v33
	v_mul_f32_e32 v35, 0xbfb8aa3b, v31
	v_exp_f32_e32 v34, v34
	v_exp_f32_e32 v35, v35
	v_mul_f32_e32 v36, 0xbfb8aa3b, v24
	v_mul_f32_e32 v37, 0xbfb8aa3b, v25
	v_exp_f32_e32 v36, v36
	v_exp_f32_e32 v37, v37
	v_add_f32_e32 v32, 1.0, v32
	v_add_f32_e32 v33, 1.0, v33
	v_mul_f32_e32 v38, 0xbfb8aa3b, v26
	v_mul_f32_e32 v39, 0xbfb8aa3b, v27
	v_rcp_f32_e32 v32, v32
	v_rcp_f32_e32 v33, v33
	v_add_f32_e32 v34, 1.0, v34
	v_add_f32_e32 v35, 1.0, v35
	v_exp_f32_e32 v38, v38
	v_exp_f32_e32 v39, v39
	v_rcp_f32_e32 v34, v34
	v_rcp_f32_e32 v35, v35
	v_add_f32_e32 v36, 1.0, v36
	v_add_f32_e32 v37, 1.0, v37
	v_rcp_f32_e32 v36, v36
	v_rcp_f32_e32 v37, v37
	v_add_f32_e32 v38, 1.0, v38
	v_add_f32_e32 v39, 1.0, v39
	v_pk_mul_f32 v[28:29], v[28:29], v[32:33]
	v_rcp_f32_e32 v38, v38
	v_rcp_f32_e32 v39, v39
	v_pk_mul_f32 v[20:21], v[28:29], v[20:21]
	v_pk_mul_f32 v[28:29], v[30:31], v[34:35]
	v_cvt_pk_bf16_f32 v20, v20, v21
	v_pk_mul_f32 v[22:23], v[28:29], v[22:23]
	s_nop 0
	v_cvt_pk_bf16_f32 v21, v22, v23
	v_pk_mul_f32 v[22:23], v[24:25], v[36:37]
	s_nop 0
	v_pk_mul_f32 v[16:17], v[22:23], v[16:17]
	s_nop 0
	v_cvt_pk_bf16_f32 v22, v16, v17
	v_pk_mul_f32 v[16:17], v[26:27], v[38:39]
	s_nop 0
	v_pk_mul_f32 v[16:17], v[16:17], v[18:19]
	v_mul_f32_e32 v18, 0xbfb8aa3b, v14
	v_cvt_pk_bf16_f32 v23, v16, v17
	v_add_u32_e32 v16, 0xa0, v138
	v_mad_i64_i32 v[16:17], s[2:3], v16, s4, v[112:113]
	v_lshl_add_u64 v[16:17], v[16:17], 0, v[114:115]
	global_store_dwordx4 v[16:17], v[20:23], off
	v_mul_f32_e32 v16, 0xbfb8aa3b, v12
	v_mul_f32_e32 v17, 0xbfb8aa3b, v13
	v_exp_f32_e32 v16, v16
	v_exp_f32_e32 v17, v17
	v_mul_f32_e32 v19, 0xbfb8aa3b, v15
	v_exp_f32_e32 v18, v18
	v_exp_f32_e32 v19, v19
	v_mul_f32_e32 v20, 0xbfb8aa3b, v8
	v_mul_f32_e32 v21, 0xbfb8aa3b, v9
	v_exp_f32_e32 v20, v20
	v_exp_f32_e32 v21, v21
	v_add_f32_e32 v16, 1.0, v16
	v_add_f32_e32 v17, 1.0, v17
	v_mul_f32_e32 v22, 0xbfb8aa3b, v10
	v_mul_f32_e32 v23, 0xbfb8aa3b, v11
	v_rcp_f32_e32 v16, v16
	v_rcp_f32_e32 v17, v17
	v_add_f32_e32 v18, 1.0, v18
	v_add_f32_e32 v19, 1.0, v19
	v_exp_f32_e32 v22, v22
	v_exp_f32_e32 v23, v23
	v_rcp_f32_e32 v18, v18
	v_rcp_f32_e32 v19, v19
	v_add_f32_e32 v20, 1.0, v20
	v_add_f32_e32 v21, 1.0, v21
	v_rcp_f32_e32 v20, v20
	v_rcp_f32_e32 v21, v21
	v_add_f32_e32 v22, 1.0, v22
	v_add_f32_e32 v23, 1.0, v23
	v_pk_mul_f32 v[12:13], v[12:13], v[16:17]
	v_rcp_f32_e32 v22, v22
	v_rcp_f32_e32 v23, v23
	v_pk_mul_f32 v[4:5], v[12:13], v[4:5]
	v_pk_mul_f32 v[12:13], v[14:15], v[18:19]
	v_cvt_pk_bf16_f32 v4, v4, v5
	v_pk_mul_f32 v[6:7], v[12:13], v[6:7]
	s_nop 0
	v_cvt_pk_bf16_f32 v5, v6, v7
	v_pk_mul_f32 v[6:7], v[8:9], v[20:21]
	s_nop 0
	v_pk_mul_f32 v[0:1], v[6:7], v[0:1]
	s_nop 0
	v_cvt_pk_bf16_f32 v6, v0, v1
	v_pk_mul_f32 v[0:1], v[10:11], v[22:23]
	s_nop 0
	v_pk_mul_f32 v[0:1], v[0:1], v[2:3]
	s_nop 0
	v_cvt_pk_bf16_f32 v7, v0, v1
	v_add_u32_e32 v0, 0xb0, v138
	v_mad_i64_i32 v[0:1], s[2:3], v0, s4, v[112:113]
	v_lshl_add_u64 v[0:1], v[0:1], 0, v[114:115]
	s_mov_b32 s2, s8
	s_mov_b32 s3, s10
	global_store_dwordx4 v[0:1], v[4:7], off
	s_cbranch_vccz .LBB0_34
	s_waitcnt vmcnt(0)
	s_cmpk_gt_u32 s24, 0xff
	s_cbranch_scc1 .LBB0_41
	s_barrier

; #define PG8_STAGE(bufoff, gbase) do { _Pragma("unroll") for (int _i = 0; _i < 2; ++_i) \
;         __builtin_amdgcn_global_load_lds((const unsigned*)((const char*)(gbase) + voff[_i]), (LAS unsigned*)(lds + (bufoff) + ldsw + _i * 8192), 16, 0, 0); } while (0)
; #define PG8_LDA(dst, b, h) do { _Pragma("unroll") for (int m = 0; m < 4; ++m) _Pragma("unroll") for (int k = 0; k < 2; ++k) dst[m][k] = *(const LAS bf16x8*)(lds + PG8_SA(b, h) + aoff + m * 2048 + k * 1024); } while (0)
; #define PG8_LDB(dst, b, h) do { _Pragma("unroll") for (int n = 0; n < 2; ++n) _Pragma("unroll") for (int k = 0; k < 2; ++k) dst[n][k] = *(const LAS bf16x8*)(lds + PG8_SB(b, h) + boff + n * 2048 + k * 1024); } while (0)
; #define PG8_MMA(ai, bj, At, Bt) do { __builtin_amdgcn_s_setprio(1); _Pragma("unroll") for (int m = 0; m < 4; ++m) _Pragma("unroll") for (int n = 0; n < 2; ++n) _Pragma("unroll") for (int k = 0; k < 2; ++k) \
;         acc[ai][bj][m][n] = __builtin_amdgcn_mfma_f32_16x16x32_bf16(Bt[n][k], At[m][k], acc[ai][bj][m][n], 0, 0, 0); __builtin_amdgcn_s_setprio(0); } while (0)
; #define PG8_WAIT_L(n) asm volatile("s_waitcnt lgkmcnt(" #n ")" ::: "memory")
; #define PG8_BAR __builtin_amdgcn_s_barrier()
; #define PG8_SCHED __builtin_amdgcn_sched_barrier(0)
; template <class Epi>
; DI void gemm_phase(LAS unsigned char* lds, const Gemm g, const StaticOrder& S, const Epi& E) {
;     ...
;             const bool last = (t == nt - 2);
;             const char* a1 = cA + (size_t)(t + 1) * kstep;
;             const char* a2 = last ? nA : cA + (size_t)(t + 2) * kstep; const char* b2 = last ? nB : cB + (size_t)(t + 2) * kstep;
;             const char* a3 = a2 + kstep; const char* b3 = b2 + kstep;
;             PG8_LDB(B0, 0, 0); PG8_SCHED; PG8_LDA(At, 0, 0); PG8_STAGE(PG8_SA(1, 1), a1 + hstep);
;             PG8_WAIT_L(8); PG8_BAR; PG8_WAIT_L(0); PG8_MMA(0, 0, At, B0); PG8_BAR; PG8_SCHED;
;             PG8_LDB(B1, 0, 1); PG8_STAGE(PG8_SB(0, 0), b2);
;             PG8_BAR; PG8_WAIT_L(0); PG8_MMA(0, 1, At, B1); PG8_BAR;
;             PG8_LDA(At, 0, 1); PG8_STAGE(PG8_SA(0, 0), a2);
;             PG8_BAR; PG8_WAIT_L(0); PG8_MMA(1, 0, At, B0); PG8_BAR; PG8_SCHED;
.LBB0_77:
	s_add_u32 s22, s20, 0x100
	s_addc_u32 s23, s21, 0
	s_add_i32 s43, 0, 0x10000
	v_add_u32_e32 v140, s43, v226
	ds_read_b128 v[128:131], v140
	ds_read_b128 v[132:135], v140 offset:1024
	ds_read_b128 v[136:139], v140 offset:2048
	ds_read_b128 v[140:143], v140 offset:3072
	s_cmp_eq_u32 s33, 32
	s_cselect_b32 s27, s9, s23
	s_cselect_b32 s26, s8, s22
	s_cselect_b32 s25, s11, s5
	s_cselect_b32 s24, s10, s4
	v_lshl_add_u64 v[214:215], s[20:21], 0, v[190:191]
	s_add_i32 m0, s34, 0xc000
	ds_read_b128 v[144:147], v228
	ds_read_b128 v[148:151], v228 offset:1024
	ds_read_b128 v[152:155], v228 offset:2048
	ds_read_b128 v[194:197], v228 offset:3072
	ds_read_b128 v[198:201], v228 offset:4096
	ds_read_b128 v[202:205], v228 offset:5120
	ds_read_b128 v[206:209], v228 offset:6144
	ds_read_b128 v[210:213], v228 offset:7168
	global_load_lds_dwordx4 v[214:215], off
	v_lshl_add_u64 v[214:215], s[20:21], 0, v[192:193]
	s_add_i32 m0, s34, 0xe000
	s_nop 0
	global_load_lds_dwordx4 v[214:215], off
	s_waitcnt lgkmcnt(8)
	s_setprio 1
	s_barrier
	s_waitcnt lgkmcnt(0)
	v_mfma_f32_16x16x32_bf16 v[124:127], v[128:131], v[144:147], v[124:127]
	v_mfma_f32_16x16x32_bf16 v[120:123], v[136:139], v[144:147], v[120:123]
	s_add_i32 s44, 0, 0x14000
	v_mfma_f32_16x16x32_bf16 v[116:119], v[128:131], v[152:155], v[116:119]
	s_add_i32 s20, s43, s31
	v_mfma_f32_16x16x32_bf16 v[112:115], v[136:139], v[152:155], v[112:115]
	v_add_u32_e32 v158, s44, v226
	v_mfma_f32_16x16x32_bf16 v[108:111], v[128:131], v[198:201], v[108:111]
	v_lshl_add_u64 v[218:219], s[24:25], 0, v[188:189]
	v_mfma_f32_16x16x32_bf16 v[104:107], v[136:139], v[198:201], v[104:107]
	s_mov_b32 m0, s20
	v_mfma_f32_16x16x32_bf16 v[100:103], v[128:131], v[206:209], v[100:103]
	v_mfma_f32_16x16x32_bf16 v[96:99], v[136:139], v[206:209], v[96:99]
	v_mfma_f32_16x16x32_bf16 v[124:127], v[132:135], v[148:151], v[124:127]
	v_mfma_f32_16x16x32_bf16 v[120:123], v[140:143], v[148:151], v[120:123]
	v_mfma_f32_16x16x32_bf16 v[116:119], v[132:135], v[194:197], v[116:119]
	v_mfma_f32_16x16x32_bf16 v[112:115], v[140:143], v[194:197], v[112:115]
	v_mfma_f32_16x16x32_bf16 v[108:111], v[132:135], v[202:205], v[108:111]
	v_mfma_f32_16x16x32_bf16 v[104:107], v[140:143], v[202:205], v[104:107]
	v_mfma_f32_16x16x32_bf16 v[100:103], v[132:135], v[210:213], v[100:103]
	v_mfma_f32_16x16x32_bf16 v[96:99], v[140:143], v[210:213], v[96:99]
	s_setprio 0
	s_barrier
	ds_read_b128 v[214:217], v158
	ds_read_b128 v[230:233], v158 offset:1024
	ds_read_b128 v[234:237], v158 offset:2048
	ds_read_b128 v[238:241], v158 offset:3072
	global_load_lds_dwordx4 v[218:219], off
	v_lshl_add_u64 v[220:221], s[24:25], 0, v[186:187]
	s_add_i32 m0, s20, 0x2000
	s_nop 0
	global_load_lds_dwordx4 v[220:221], off
	s_waitcnt lgkmcnt(0)
	s_setprio 1
	s_barrier
	v_mfma_f32_16x16x32_bf16 v[60:63], v[214:217], v[144:147], v[60:63]
	v_mfma_f32_16x16x32_bf16 v[56:59], v[234:237], v[144:147], v[56:59]
	v_mfma_f32_16x16x32_bf16 v[52:55], v[214:217], v[152:155], v[52:55]
	v_mfma_f32_16x16x32_bf16 v[48:51], v[234:237], v[152:155], v[48:51]
	v_mfma_f32_16x16x32_bf16 v[44:47], v[214:217], v[198:201], v[44:47]
	v_mfma_f32_16x16x32_bf16 v[40:43], v[234:237], v[198:201], v[40:43]
	v_mfma_f32_16x16x32_bf16 v[36:39], v[214:217], v[206:209], v[36:39]
	v_mfma_f32_16x16x32_bf16 v[32:35], v[234:237], v[206:209], v[32:35]
	v_mfma_f32_16x16x32_bf16 v[60:63], v[230:233], v[148:151], v[60:63]
	s_mov_b32 m0, s34
	v_mfma_f32_16x16x32_bf16 v[56:59], v[238:241], v[148:151], v[56:59]
	v_lshl_add_u64 v[242:243], s[26:27], 0, v[188:189]
	v_mfma_f32_16x16x32_bf16 v[52:55], v[230:233], v[194:197], v[52:55]
	v_mfma_f32_16x16x32_bf16 v[48:51], v[238:241], v[194:197], v[48:51]
	v_mfma_f32_16x16x32_bf16 v[44:47], v[230:233], v[202:205], v[44:47]
	v_mfma_f32_16x16x32_bf16 v[40:43], v[238:241], v[202:205], v[40:43]
	v_mfma_f32_16x16x32_bf16 v[36:39], v[230:233], v[210:213], v[36:39]
	v_mfma_f32_16x16x32_bf16 v[32:35], v[238:241], v[210:213], v[32:35]
	s_setprio 0
	s_barrier
	ds_read_b128 v[144:147], v228 offset:16384
	ds_read_b128 v[148:151], v228 offset:17408
	ds_read_b128 v[152:155], v228 offset:18432
	ds_read_b128 v[194:197], v228 offset:19456
	ds_read_b128 v[198:201], v228 offset:20480
	ds_read_b128 v[202:205], v228 offset:21504
	ds_read_b128 v[206:209], v228 offset:22528
	ds_read_b128 v[210:213], v228 offset:23552
	global_load_lds_dwordx4 v[242:243], off
	v_lshl_add_u64 v[244:245], s[26:27], 0, v[186:187]
	s_mov_b32 m0, s35
	s_nop 0
	global_load_lds_dwordx4 v[244:245], off
	s_waitcnt lgkmcnt(0)
	s_setprio 1
	s_barrier
	v_mfma_f32_16x16x32_bf16 v[92:95], v[128:131], v[144:147], v[92:95]
	v_mfma_f32_16x16x32_bf16 v[88:91], v[136:139], v[144:147], v[88:91]
	s_add_u32 s20, s24, 0x90000
	v_mfma_f32_16x16x32_bf16 v[84:87], v[128:131], v[152:155], v[84:87]
	s_addc_u32 s21, s25, 0
	v_mfma_f32_16x16x32_bf16 v[80:83], v[136:139], v[152:155], v[80:83]
	s_add_i32 s43, s44, s31
	v_mfma_f32_16x16x32_bf16 v[76:79], v[128:131], v[198:201], v[76:79]
	v_mfma_f32_16x16x32_bf16 v[72:75], v[136:139], v[198:201], v[72:75]
	v_mfma_f32_16x16x32_bf16 v[68:71], v[128:131], v[206:209], v[68:71]
	v_mfma_f32_16x16x32_bf16 v[64:67], v[136:139], v[206:209], v[64:67]
	v_mfma_f32_16x16x32_bf16 v[92:95], v[132:135], v[148:151], v[92:95]
	v_mfma_f32_16x16x32_bf16 v[88:91], v[140:143], v[148:151], v[88:91]
	v_mfma_f32_16x16x32_bf16 v[84:87], v[132:135], v[194:197], v[84:87]
	v_mfma_f32_16x16x32_bf16 v[80:83], v[140:143], v[194:197], v[80:83]
	v_mfma_f32_16x16x32_bf16 v[76:79], v[132:135], v[202:205], v[76:79]
	v_mfma_f32_16x16x32_bf16 v[72:75], v[140:143], v[202:205], v[72:75]
	v_mfma_f32_16x16x32_bf16 v[68:71], v[132:135], v[210:213], v[68:71]
	v_mfma_f32_16x16x32_bf16 v[64:67], v[140:143], v[210:213], v[64:67]
	s_setprio 0
	s_barrier
; #define PG8_STAGE(bufoff, gbase) do { _Pragma("unroll") for (int _i = 0; _i < 2; ++_i) \
;         __builtin_amdgcn_global_load_lds((const unsigned*)((const char*)(gbase) + voff[_i]), (LAS unsigned*)(lds + (bufoff) + ldsw + _i * 8192), 16, 0, 0); } while (0)
; #define PG8_LDA(dst, b, h) do { _Pragma("unroll") for (int m = 0; m < 4; ++m) _Pragma("unroll") for (int k = 0; k < 2; ++k) dst[m][k] = *(const LAS bf16x8*)(lds + PG8_SA(b, h) + aoff + m * 2048 + k * 1024); } while (0)
; #define PG8_LDB(dst, b, h) do { _Pragma("unroll") for (int n = 0; n < 2; ++n) _Pragma("unroll") for (int k = 0; k < 2; ++k) dst[n][k] = *(const LAS bf16x8*)(lds + PG8_SB(b, h) + boff + n * 2048 + k * 1024); } while (0)
; #define PG8_MMA(ai, bj, At, Bt) do { __builtin_amdgcn_s_setprio(1); _Pragma("unroll") for (int m = 0; m < 4; ++m) _Pragma("unroll") for (int n = 0; n < 2; ++n) _Pragma("unroll") for (int k = 0; k < 2; ++k) \
;         acc[ai][bj][m][n] = __builtin_amdgcn_mfma_f32_16x16x32_bf16(Bt[n][k], At[m][k], acc[ai][bj][m][n], 0, 0, 0); __builtin_amdgcn_s_setprio(0); } while (0)
; #define PG8_WAIT_V(n) asm volatile("s_waitcnt vmcnt(" #n ")" ::: "memory")
; #define PG8_WAIT_L(n) asm volatile("s_waitcnt lgkmcnt(" #n ")" ::: "memory")
; #define PG8_BAR __builtin_amdgcn_s_barrier()
; #define PG8_SCHED __builtin_amdgcn_sched_barrier(0)
; template <class Epi>
; DI void gemm_phase(LAS unsigned char* lds, const Gemm g, const StaticOrder& S, const Epi& E) {
;     ...
;             PG8_STAGE(PG8_SB(0, 1), b2 + hstep);
;             PG8_WAIT_V(6); PG8_BAR; PG8_MMA(1, 1, At, B1); PG8_BAR;
;             PG8_LDB(B0, 1, 0); PG8_SCHED; PG8_LDA(At, 1, 0); PG8_STAGE(PG8_SA(0, 1), a2 + hstep);
;             PG8_WAIT_L(8); PG8_BAR; PG8_WAIT_L(0); PG8_MMA(0, 0, At, B0); PG8_BAR; PG8_SCHED;
;             PG8_LDB(B1, 1, 1); PG8_STAGE(PG8_SB(1, 0), b3);
;             PG8_BAR; PG8_WAIT_L(0); PG8_MMA(0, 1, At, B1); PG8_BAR;
;             PG8_LDA(At, 1, 1); PG8_STAGE(PG8_SA(1, 0), a3);
	v_lshl_add_u64 v[128:129], s[20:21], 0, v[188:189]
	s_mov_b32 m0, s43
	s_nop 0
	global_load_lds_dwordx4 v[128:129], off
	v_lshl_add_u64 v[128:129], s[20:21], 0, v[186:187]
	s_add_i32 m0, s43, 0x2000
	s_nop 0
	global_load_lds_dwordx4 v[128:129], off
	s_waitcnt vmcnt(6)
	s_setprio 1
	s_barrier
	v_mfma_f32_16x16x32_bf16 v[28:31], v[214:217], v[144:147], v[28:31]
	v_mfma_f32_16x16x32_bf16 v[24:27], v[234:237], v[144:147], v[24:27]
	v_mfma_f32_16x16x32_bf16 v[20:23], v[214:217], v[152:155], v[20:23]
	v_mfma_f32_16x16x32_bf16 v[16:19], v[234:237], v[152:155], v[16:19]
	v_mfma_f32_16x16x32_bf16 v[12:15], v[214:217], v[198:201], v[12:15]
	v_mfma_f32_16x16x32_bf16 v[8:11], v[234:237], v[198:201], v[8:11]
	v_mfma_f32_16x16x32_bf16 v[4:7], v[214:217], v[206:209], v[4:7]
	v_mfma_f32_16x16x32_bf16 v[0:3], v[234:237], v[206:209], v[0:3]
	v_mfma_f32_16x16x32_bf16 v[28:31], v[230:233], v[148:151], v[28:31]
	s_add_i32 s43, 0, 0x18000
	v_mfma_f32_16x16x32_bf16 v[24:27], v[238:241], v[148:151], v[24:27]
	v_add_u32_e32 v140, s43, v226
	v_mfma_f32_16x16x32_bf16 v[20:23], v[230:233], v[194:197], v[20:23]
	v_mfma_f32_16x16x32_bf16 v[16:19], v[238:241], v[194:197], v[16:19]
	v_mfma_f32_16x16x32_bf16 v[12:15], v[230:233], v[202:205], v[12:15]
	v_mfma_f32_16x16x32_bf16 v[8:11], v[238:241], v[202:205], v[8:11]
	v_mfma_f32_16x16x32_bf16 v[4:7], v[230:233], v[210:213], v[4:7]
	v_mfma_f32_16x16x32_bf16 v[0:3], v[238:241], v[210:213], v[0:3]
	s_setprio 0
	s_barrier
	ds_read_b128 v[128:131], v140
	ds_read_b128 v[132:135], v140 offset:1024
	ds_read_b128 v[136:139], v140 offset:2048
	ds_read_b128 v[140:143], v140 offset:3072
	s_add_u32 s20, s26, 0x90000
	s_addc_u32 s21, s27, 0
	s_mov_b32 m0, s36
	v_lshl_add_u64 v[214:215], s[20:21], 0, v[188:189]
	ds_read_b128 v[144:147], v228 offset:32768
	ds_read_b128 v[148:151], v228 offset:33792
	ds_read_b128 v[152:155], v228 offset:34816
	ds_read_b128 v[194:197], v228 offset:35840
	ds_read_b128 v[198:201], v228 offset:36864
	ds_read_b128 v[202:205], v228 offset:37888
	ds_read_b128 v[206:209], v228 offset:38912
	ds_read_b128 v[210:213], v228 offset:39936
	global_load_lds_dwordx4 v[214:215], off
	v_lshl_add_u64 v[214:215], s[20:21], 0, v[186:187]
	s_mov_b32 m0, s37
	s_nop 0
	global_load_lds_dwordx4 v[214:215], off
	s_waitcnt lgkmcnt(8)
	s_setprio 1
	s_barrier
	s_waitcnt lgkmcnt(0)
	v_mfma_f32_16x16x32_bf16 v[124:127], v[128:131], v[144:147], v[124:127]
	v_mfma_f32_16x16x32_bf16 v[120:123], v[136:139], v[144:147], v[120:123]
	s_add_i32 s26, 0, 0x1c000
	v_mfma_f32_16x16x32_bf16 v[116:119], v[128:131], v[152:155], v[116:119]
	s_add_i32 s20, s43, s31
	v_mfma_f32_16x16x32_bf16 v[112:115], v[136:139], v[152:155], v[112:115]
	v_add_u32_e32 v158, s26, v226
	v_mfma_f32_16x16x32_bf16 v[108:111], v[128:131], v[198:201], v[108:111]
	v_lshl_add_u64 v[218:219], v[218:219], 0, s[94:95]
	v_mfma_f32_16x16x32_bf16 v[104:107], v[136:139], v[198:201], v[104:107]
	s_mov_b32 m0, s20
	v_mfma_f32_16x16x32_bf16 v[100:103], v[128:131], v[206:209], v[100:103]
	v_mfma_f32_16x16x32_bf16 v[96:99], v[136:139], v[206:209], v[96:99]
	v_mfma_f32_16x16x32_bf16 v[124:127], v[132:135], v[148:151], v[124:127]
	v_mfma_f32_16x16x32_bf16 v[120:123], v[140:143], v[148:151], v[120:123]
	v_mfma_f32_16x16x32_bf16 v[116:119], v[132:135], v[194:197], v[116:119]
	v_mfma_f32_16x16x32_bf16 v[112:115], v[140:143], v[194:197], v[112:115]
	v_mfma_f32_16x16x32_bf16 v[108:111], v[132:135], v[202:205], v[108:111]
	v_mfma_f32_16x16x32_bf16 v[104:107], v[140:143], v[202:205], v[104:107]
	v_mfma_f32_16x16x32_bf16 v[100:103], v[132:135], v[210:213], v[100:103]
	v_mfma_f32_16x16x32_bf16 v[96:99], v[140:143], v[210:213], v[96:99]
	s_setprio 0
	s_barrier
	ds_read_b128 v[214:217], v158
	ds_read_b128 v[230:233], v158 offset:1024
	ds_read_b128 v[234:237], v158 offset:2048
	ds_read_b128 v[238:241], v158 offset:3072
	global_load_lds_dwordx4 v[218:219], off
	v_lshl_add_u64 v[218:219], v[220:221], 0, s[94:95]
	s_add_i32 m0, s20, 0x2000
	s_nop 0
	global_load_lds_dwordx4 v[218:219], off
	s_waitcnt lgkmcnt(0)
	s_setprio 1
	s_barrier
	v_mfma_f32_16x16x32_bf16 v[60:63], v[214:217], v[144:147], v[60:63]
	v_mfma_f32_16x16x32_bf16 v[56:59], v[234:237], v[144:147], v[56:59]
	v_mfma_f32_16x16x32_bf16 v[52:55], v[214:217], v[152:155], v[52:55]
	v_mfma_f32_16x16x32_bf16 v[48:51], v[234:237], v[152:155], v[48:51]
	v_mfma_f32_16x16x32_bf16 v[44:47], v[214:217], v[198:201], v[44:47]
	v_mfma_f32_16x16x32_bf16 v[40:43], v[234:237], v[198:201], v[40:43]
	v_mfma_f32_16x16x32_bf16 v[36:39], v[214:217], v[206:209], v[36:39]
	v_mfma_f32_16x16x32_bf16 v[32:35], v[234:237], v[206:209], v[32:35]
	v_mfma_f32_16x16x32_bf16 v[60:63], v[230:233], v[148:151], v[60:63]
	s_mov_b32 m0, s38
	v_mfma_f32_16x16x32_bf16 v[56:59], v[238:241], v[148:151], v[56:59]
	v_lshl_add_u64 v[218:219], v[242:243], 0, s[94:95]
	v_mfma_f32_16x16x32_bf16 v[52:55], v[230:233], v[194:197], v[52:55]
	v_mfma_f32_16x16x32_bf16 v[48:51], v[238:241], v[194:197], v[48:51]
	v_mfma_f32_16x16x32_bf16 v[44:47], v[230:233], v[202:205], v[44:47]
	v_mfma_f32_16x16x32_bf16 v[40:43], v[238:241], v[202:205], v[40:43]
	v_mfma_f32_16x16x32_bf16 v[36:39], v[230:233], v[210:213], v[36:39]
	v_mfma_f32_16x16x32_bf16 v[32:35], v[238:241], v[210:213], v[32:35]
	s_setprio 0
	s_barrier
	ds_read_b128 v[144:147], v228 offset:49152
	ds_read_b128 v[148:151], v228 offset:50176
	ds_read_b128 v[152:155], v228 offset:51200
	ds_read_b128 v[194:197], v228 offset:52224
	ds_read_b128 v[198:201], v228 offset:53248
	ds_read_b128 v[202:205], v228 offset:54272
	ds_read_b128 v[206:209], v228 offset:55296
	ds_read_b128 v[210:213], v228 offset:56320
	global_load_lds_dwordx4 v[218:219], off
	v_lshl_add_u64 v[218:219], v[244:245], 0, s[94:95]
	s_mov_b32 m0, s39
	s_nop 0
	global_load_lds_dwordx4 v[218:219], off
	s_waitcnt lgkmcnt(0)
	s_setprio 1
	s_barrier
; #define PG8_STAGE(bufoff, gbase) do { _Pragma("unroll") for (int _i = 0; _i < 2; ++_i) \
;         __builtin_amdgcn_global_load_lds((const unsigned*)((const char*)(gbase) + voff[_i]), (LAS unsigned*)(lds + (bufoff) + ldsw + _i * 8192), 16, 0, 0); } while (0)
; #define PG8_MMA(ai, bj, At, Bt) do { __builtin_amdgcn_s_setprio(1); _Pragma("unroll") for (int m = 0; m < 4; ++m) _Pragma("unroll") for (int n = 0; n < 2; ++n) _Pragma("unroll") for (int k = 0; k < 2; ++k) \
;         acc[ai][bj][m][n] = __builtin_amdgcn_mfma_f32_16x16x32_bf16(Bt[n][k], At[m][k], acc[ai][bj][m][n], 0, 0, 0); __builtin_amdgcn_s_setprio(0); } while (0)
; template <class Epi>
; DI void gemm_phase(LAS unsigned char* lds, const Gemm g, const StaticOrder& S, const Epi& E) {
;     ...
;             PG8_BAR; PG8_WAIT_L(0); PG8_MMA(1, 0, At, B0); PG8_BAR; PG8_SCHED;
;             PG8_STAGE(PG8_SB(1, 1), b3 + hstep);
;             PG8_WAIT_V(6); PG8_BAR; PG8_MMA(1, 1, At, B1); PG8_BAR;
;     template <bool LN, int BJ, int LO, int HI> DI void batch(const f32x4 (&acc)[2][2][4][2], unsigned row0, unsigned col0, const f32x4 (&gv)[2], const f32x4 (&bv)[2]) const {
;         f32x4 r[HI - LO]; float mean[(HI - LO) / 2], rstd[(HI - LO) / 2];
; #pragma unroll
;         for (int i = LO; i < HI; ++i) { const int ai = i >> 3, m = (i >> 1) & 3, n = i & 1; const unsigned row = row0 + ai * HALF + m * 16;
;             if (n == 0) { mean[(i - LO) >> 1] = 0.f; rstd[(i - LO) >> 1] = 1.f;
;                 if (LN) { const float2 st = *(const float2*)(stats + row * 2u); mean[(i - LO) >> 1] = st.x; rstd[(i - LO) >> 1] = st.y; } }
;             r[i - LO] = *(const f32x4*)(src + (row * (unsigned)DM + col0 + BJ * HALF + n * 16)); }
; #pragma unroll
;         for (int i = LO; i < HI; ++i) { const int ai = i >> 3, m = (i >> 1) & 3, n = i & 1; const unsigned row = row0 + ai * HALF + m * 16;
;             *(f32x4*)(Y + (row * (unsigned)DM + col0 + BJ * HALF + n * 16)) = acc[ai][BJ][m][n] + ((r[i - LO] - mean[(i - LO) >> 1]) * rstd[(i - LO) >> 1]) * gv[n] + bv[n]; }
;         __builtin_amdgcn_sched_barrier(0);
;     }
;     template <bool LN, int BJ> DI void load_gb(unsigned col0, f32x4 (&gv)[2], f32x4 (&bv)[2]) const {
; #pragma unroll
;         for (int n = 0; n < 2; ++n) {
;             if (LN) { gv[n] = *(const f32x4*)(gam + col0 + BJ * HALF + n * 16) * ALPHA; bv[n] = *(const f32x4*)(bet + col0 + BJ * HALF + n * 16) * ALPHA; }
	v_mfma_f32_16x16x32_bf16 v[92:95], v[128:131], v[144:147], v[92:95]
	v_mfma_f32_16x16x32_bf16 v[88:91], v[136:139], v[144:147], v[88:91]
	s_add_u32 s20, s24, 0x90080
	v_mfma_f32_16x16x32_bf16 v[84:87], v[128:131], v[152:155], v[84:87]
	s_addc_u32 s21, s25, 0
	v_mfma_f32_16x16x32_bf16 v[80:83], v[136:139], v[152:155], v[80:83]
	s_add_i32 s24, s26, s31
	v_mfma_f32_16x16x32_bf16 v[76:79], v[128:131], v[198:201], v[76:79]
	v_mfma_f32_16x16x32_bf16 v[72:75], v[136:139], v[198:201], v[72:75]
	v_mfma_f32_16x16x32_bf16 v[68:71], v[128:131], v[206:209], v[68:71]
	v_mfma_f32_16x16x32_bf16 v[64:67], v[136:139], v[206:209], v[64:67]
	v_mfma_f32_16x16x32_bf16 v[92:95], v[132:135], v[148:151], v[92:95]
	v_mfma_f32_16x16x32_bf16 v[88:91], v[140:143], v[148:151], v[88:91]
	v_mfma_f32_16x16x32_bf16 v[84:87], v[132:135], v[194:197], v[84:87]
	v_mfma_f32_16x16x32_bf16 v[80:83], v[140:143], v[194:197], v[80:83]
	v_mfma_f32_16x16x32_bf16 v[76:79], v[132:135], v[202:205], v[76:79]
	v_mfma_f32_16x16x32_bf16 v[72:75], v[140:143], v[202:205], v[72:75]
	v_mfma_f32_16x16x32_bf16 v[68:71], v[132:135], v[210:213], v[68:71]
	v_mfma_f32_16x16x32_bf16 v[64:67], v[140:143], v[210:213], v[64:67]
	s_setprio 0
	s_barrier
	v_lshl_add_u64 v[128:129], s[20:21], 0, v[188:189]
	s_mov_b32 m0, s24
	s_nop 0
	global_load_lds_dwordx4 v[128:129], off
	v_lshl_add_u64 v[128:129], s[20:21], 0, v[186:187]
	s_add_i32 m0, s24, 0x2000
	s_nop 0
	global_load_lds_dwordx4 v[128:129], off
	s_waitcnt vmcnt(6)
	s_setprio 1
	s_barrier
	v_mfma_f32_16x16x32_bf16 v[28:31], v[214:217], v[144:147], v[28:31]
	v_mfma_f32_16x16x32_bf16 v[24:27], v[234:237], v[144:147], v[24:27]
	v_mfma_f32_16x16x32_bf16 v[20:23], v[214:217], v[152:155], v[20:23]
	v_mfma_f32_16x16x32_bf16 v[16:19], v[234:237], v[152:155], v[16:19]
	v_mfma_f32_16x16x32_bf16 v[12:15], v[214:217], v[198:201], v[12:15]
	v_mfma_f32_16x16x32_bf16 v[8:11], v[234:237], v[198:201], v[8:11]
	v_mfma_f32_16x16x32_bf16 v[4:7], v[214:217], v[206:209], v[4:7]
	v_mfma_f32_16x16x32_bf16 v[0:3], v[234:237], v[206:209], v[0:3]
	v_mfma_f32_16x16x32_bf16 v[28:31], v[230:233], v[148:151], v[28:31]
	s_add_i32 s33, s33, 2
	v_mfma_f32_16x16x32_bf16 v[24:27], v[238:241], v[148:151], v[24:27]
	s_add_u32 s4, s4, 0x100
	v_mfma_f32_16x16x32_bf16 v[20:23], v[230:233], v[194:197], v[20:23]
	s_addc_u32 s5, s5, 0
	v_mfma_f32_16x16x32_bf16 v[16:19], v[238:241], v[194:197], v[16:19]
	s_cmp_gt_u32 s33, 33
	v_mfma_f32_16x16x32_bf16 v[12:15], v[230:233], v[202:205], v[12:15]
	s_mov_b64 s[20:21], s[22:23]
	v_mfma_f32_16x16x32_bf16 v[8:11], v[238:241], v[202:205], v[8:11]
	v_mfma_f32_16x16x32_bf16 v[4:7], v[230:233], v[210:213], v[4:7]
	v_mfma_f32_16x16x32_bf16 v[0:3], v[238:241], v[210:213], v[0:3]
	s_setprio 0
	s_barrier
	s_cbranch_scc0 .LBB0_77
	v_lshl_add_u32 v206, s3, 8, v225
	v_lshl_or_b32 v158, s2, 8, v227
	v_lshlrev_b32_e32 v232, 11, v206
	s_andn2_b64 vcc, exec, s[14:15]
	v_or_b32_e32 v231, 16, v158
	v_add_u32_e32 v194, v232, v158
	v_or_b32_e32 v230, 0x80, v158
	v_or_b32_e32 v229, 0x90, v158
	s_cbranch_vccnz .LBB0_80
	v_lshlrev_b64 v[132:133], 2, v[158:159]
	v_lshl_add_u64 v[140:141], s[16:17], 0, v[132:133]
	global_load_dwordx4 v[128:131], v[140:141], off
	v_lshl_add_u64 v[142:143], s[18:19], 0, v[132:133]
	v_readlane_b32 s2, v253, 8
	v_mov_b32_e32 v195, v159
	v_lshlrev_b32_e32 v136, 1, v206
	v_mov_b32_e32 v137, v159
	v_readlane_b32 s3, v253, 9
	v_lshlrev_b64 v[212:213], 2, v[194:195]
	v_add_u32_e32 v146, v232, v231
	v_lshl_add_u64 v[144:145], v[136:137], 2, s[2:3]
	v_lshl_add_u64 v[136:137], s[88:89], 0, v[212:213]
	v_mov_b32_e32 v147, v159
	v_lshl_add_u64 v[146:147], v[146:147], 2, s[88:89]
	v_or_b32_e32 v195, 16, v206
	v_mov_b32_e32 v201, v159
	v_mov_b32_e32 v209, v159
	v_lshl_add_u64 v[212:213], s[90:91], 0, v[212:213]
	s_waitcnt vmcnt(0)
	v_pk_mul_f32 v[152:153], v[130:131], s[78:79] op_sel_hi:[1,0]
	v_pk_mul_f32 v[154:155], v[128:129], s[78:79] op_sel_hi:[1,0]
	global_load_dwordx4 v[132:135], v[142:143], off
	global_load_dwordx4 v[128:131], v[140:141], off offset:64
	global_load_dwordx2 v[204:205], v[144:145], off
	global_load_dwordx4 v[196:199], v[146:147], off
	v_lshlrev_b32_e32 v146, 1, v195
	global_load_dwordx4 v[136:139], v[136:137], off
	v_lshlrev_b32_e32 v195, 11, v195
	v_mov_b32_e32 v147, v159
	v_add_u32_e32 v200, v195, v158
	v_lshl_add_u64 v[146:147], v[146:147], 2, s[2:3]
	v_lshl_add_u64 v[200:201], v[200:201], 2, s[88:89]
	global_load_dwordx2 v[214:215], v[146:147], off
	v_add_u32_e32 v208, v195, v231
	global_load_dwordx4 v[200:203], v[200:201], off
	v_lshl_add_u64 v[208:209], v[208:209], 2, s[88:89]
	global_load_dwordx4 v[208:211], v[208:209], off
	s_waitcnt vmcnt(0)
	v_pk_mul_f32 v[148:149], v[130:131], s[78:79] op_sel_hi:[1,0]
	v_pk_mul_f32 v[150:151], v[128:129], s[78:79] op_sel_hi:[1,0]
	global_load_dwordx4 v[128:131], v[142:143], off offset:64
	v_sub_f32_e32 v137, v137, v204
	v_sub_f32_e32 v136, v136, v204
	v_sub_f32_e32 v139, v139, v204
	v_sub_f32_e32 v138, v138, v204
	v_pk_mul_f32 v[138:139], v[204:205], v[138:139] op_sel:[1,0]
	v_pk_mul_f32 v[136:137], v[204:205], v[136:137] op_sel:[1,0]
	v_pk_fma_f32 v[138:139], v[152:153], v[138:139], v[126:127]
	v_pk_fma_f32 v[136:137], v[154:155], v[136:137], v[124:125]
	v_pk_fma_f32 v[138:139], v[134:135], s[78:79], v[138:139] op_sel_hi:[1,0,1]
	v_pk_fma_f32 v[136:137], v[132:133], s[78:79], v[136:137] op_sel_hi:[1,0,1]
	global_store_dwordx4 v[212:213], v[136:139], off
	s_nop 1
	v_sub_f32_e32 v137, v197, v204
	v_sub_f32_e32 v136, v196, v204
	v_sub_f32_e32 v139, v199, v204
	v_sub_f32_e32 v138, v198, v204
	v_pk_mul_f32 v[138:139], v[204:205], v[138:139] op_sel:[1,0]
	v_pk_mul_f32 v[136:137], v[204:205], v[136:137] op_sel:[1,0]
	v_pk_fma_f32 v[138:139], v[148:149], v[138:139], v[122:123]
	v_pk_fma_f32 v[136:137], v[150:151], v[136:137], v[120:121]
	v_or_b32_e32 v196, 16, v194
	v_mov_b32_e32 v197, v159
	v_lshl_add_u64 v[196:197], v[196:197], 2, s[90:91]
	s_waitcnt vmcnt(0)
;     template <bool LN, int BJ, int LO, int HI> DI void batch(const f32x4 (&acc)[2][2][4][2], unsigned row0, unsigned col0, const f32x4 (&gv)[2], const f32x4 (&bv)[2]) const {
;         f32x4 r[HI - LO]; float mean[(HI - LO) / 2], rstd[(HI - LO) / 2];
; #pragma unroll
;         for (int i = LO; i < HI; ++i) { const int ai = i >> 3, m = (i >> 1) & 3, n = i & 1; const unsigned row = row0 + ai * HALF + m * 16;
;             if (n == 0) { mean[(i - LO) >> 1] = 0.f; rstd[(i - LO) >> 1] = 1.f;
;                 if (LN) { const float2 st = *(const float2*)(stats + row * 2u); mean[(i - LO) >> 1] = st.x; rstd[(i - LO) >> 1] = st.y; } }
;             r[i - LO] = *(const f32x4*)(src + (row * (unsigned)DM + col0 + BJ * HALF + n * 16)); }
; #pragma unroll
;         for (int i = LO; i < HI; ++i) { const int ai = i >> 3, m = (i >> 1) & 3, n = i & 1; const unsigned row = row0 + ai * HALF + m * 16;
;             *(f32x4*)(Y + (row * (unsigned)DM + col0 + BJ * HALF + n * 16)) = acc[ai][BJ][m][n] + ((r[i - LO] - mean[(i - LO) >> 1]) * rstd[(i - LO) >> 1]) * gv[n] + bv[n]; }
	v_pk_fma_f32 v[138:139], v[130:131], s[78:79], v[138:139] op_sel_hi:[1,0,1]
	v_pk_fma_f32 v[136:137], v[128:129], s[78:79], v[136:137] op_sel_hi:[1,0,1]
	global_store_dwordx4 v[196:197], v[136:139], off
	v_add_u32_e32 v196, 0x8000, v194
	v_mov_b32_e32 v197, v159
	v_sub_f32_e32 v137, v201, v214
	v_sub_f32_e32 v136, v200, v214
	v_sub_f32_e32 v139, v203, v214
	v_sub_f32_e32 v138, v202, v214
	v_pk_mul_f32 v[138:139], v[214:215], v[138:139] op_sel:[1,0]
	v_pk_mul_f32 v[136:137], v[214:215], v[136:137] op_sel:[1,0]
	v_pk_fma_f32 v[138:139], v[152:153], v[138:139], v[118:119]
	v_pk_fma_f32 v[136:137], v[154:155], v[136:137], v[116:117]
	v_pk_fma_f32 v[138:139], v[134:135], s[78:79], v[138:139] op_sel_hi:[1,0,1]
	v_pk_fma_f32 v[136:137], v[132:133], s[78:79], v[136:137] op_sel_hi:[1,0,1]
	v_lshl_add_u64 v[196:197], v[196:197], 2, s[90:91]
	global_store_dwordx4 v[196:197], v[136:139], off
	v_add_u32_e32 v196, 0x8010, v194
	v_mov_b32_e32 v197, v159
	v_sub_f32_e32 v137, v209, v214
	v_sub_f32_e32 v136, v208, v214
	v_sub_f32_e32 v139, v211, v214
	v_sub_f32_e32 v138, v210, v214
	v_pk_mul_f32 v[138:139], v[214:215], v[138:139] op_sel:[1,0]
	v_pk_mul_f32 v[136:137], v[214:215], v[136:137] op_sel:[1,0]
	v_pk_fma_f32 v[138:139], v[148:149], v[138:139], v[114:115]
	v_pk_fma_f32 v[136:137], v[150:151], v[136:137], v[112:113]
	v_pk_fma_f32 v[138:139], v[130:131], s[78:79], v[138:139] op_sel_hi:[1,0,1]
	v_pk_fma_f32 v[136:137], v[128:129], s[78:79], v[136:137] op_sel_hi:[1,0,1]
	v_lshl_add_u64 v[196:197], v[196:197], 2, s[90:91]
	global_store_dwordx4 v[196:197], v[136:139], off
	s_nop 1
	v_or_b32_e32 v138, 32, v206
	v_lshlrev_b32_e32 v136, 1, v138
	v_mov_b32_e32 v137, v159
	v_lshlrev_b32_e32 v236, 11, v138
	v_lshl_add_u64 v[200:201], v[136:137], 2, s[2:3]
	v_add_u32_e32 v136, v236, v158
	v_lshl_add_u64 v[136:137], v[136:137], 2, s[88:89]
	global_load_dwordx2 v[204:205], v[200:201], off
	v_add_u32_e32 v196, v236, v231
	global_load_dwordx4 v[136:139], v[136:137], off
	v_mov_b32_e32 v197, v159
	v_lshl_add_u64 v[196:197], v[196:197], 2, s[88:89]
	global_load_dwordx4 v[196:199], v[196:197], off
	v_or_b32_e32 v207, 48, v206
	v_lshlrev_b32_e32 v235, 11, v207
	v_lshlrev_b32_e32 v202, 1, v207
	v_mov_b32_e32 v203, v159
	v_add_u32_e32 v208, v235, v158
	v_mov_b32_e32 v209, v159
	v_lshl_add_u64 v[202:203], v[202:203], 2, s[2:3]
	v_lshl_add_u64 v[208:209], v[208:209], 2, s[88:89]
	global_load_dwordx2 v[216:217], v[202:203], off
	v_add_u32_e32 v212, v235, v231
	global_load_dwordx4 v[208:211], v[208:209], off
	v_mov_b32_e32 v213, v159
	v_lshl_add_u64 v[212:213], v[212:213], 2, s[88:89]
	global_load_dwordx4 v[212:215], v[212:213], off
	v_add_u32_e32 v218, 0x10000, v194
	v_mov_b32_e32 v219, v159
	v_lshl_add_u64 v[218:219], v[218:219], 2, s[90:91]
	s_waitcnt vmcnt(0)
	v_sub_f32_e32 v137, v137, v204
	v_sub_f32_e32 v136, v136, v204
	v_sub_f32_e32 v139, v139, v204
	v_sub_f32_e32 v138, v138, v204
	v_pk_mul_f32 v[138:139], v[204:205], v[138:139] op_sel:[1,0]
	v_pk_mul_f32 v[136:137], v[204:205], v[136:137] op_sel:[1,0]
	v_pk_fma_f32 v[138:139], v[152:153], v[138:139], v[110:111]
	v_pk_fma_f32 v[136:137], v[154:155], v[136:137], v[108:109]
	v_pk_fma_f32 v[138:139], v[134:135], s[78:79], v[138:139] op_sel_hi:[1,0,1]
	v_pk_fma_f32 v[136:137], v[132:133], s[78:79], v[136:137] op_sel_hi:[1,0,1]
	global_store_dwordx4 v[218:219], v[136:139], off
	s_nop 1
	v_sub_f32_e32 v137, v197, v204
	v_sub_f32_e32 v136, v196, v204
	v_sub_f32_e32 v139, v199, v204
	v_sub_f32_e32 v138, v198, v204
	v_pk_mul_f32 v[138:139], v[204:205], v[138:139] op_sel:[1,0]
	v_pk_mul_f32 v[136:137], v[204:205], v[136:137] op_sel:[1,0]
	v_pk_fma_f32 v[138:139], v[148:149], v[138:139], v[106:107]
	v_pk_fma_f32 v[136:137], v[150:151], v[136:137], v[104:105]
	v_add_u32_e32 v196, 0x10010, v194
	v_mov_b32_e32 v197, v159
	v_pk_fma_f32 v[138:139], v[130:131], s[78:79], v[138:139] op_sel_hi:[1,0,1]
	v_pk_fma_f32 v[136:137], v[128:129], s[78:79], v[136:137] op_sel_hi:[1,0,1]
	v_lshl_add_u64 v[196:197], v[196:197], 2, s[90:91]
	global_store_dwordx4 v[196:197], v[136:139], off
	v_add_u32_e32 v196, 0x18000, v194
	v_mov_b32_e32 v197, v159
	v_sub_f32_e32 v137, v209, v216
	v_sub_f32_e32 v136, v208, v216
	v_sub_f32_e32 v139, v211, v216
	v_sub_f32_e32 v138, v210, v216
	v_pk_mul_f32 v[138:139], v[216:217], v[138:139] op_sel:[1,0]
	v_pk_mul_f32 v[136:137], v[216:217], v[136:137] op_sel:[1,0]
	v_pk_fma_f32 v[138:139], v[152:153], v[138:139], v[102:103]
	v_pk_fma_f32 v[136:137], v[154:155], v[136:137], v[100:101]
	v_pk_fma_f32 v[138:139], v[134:135], s[78:79], v[138:139] op_sel_hi:[1,0,1]
	v_pk_fma_f32 v[136:137], v[132:133], s[78:79], v[136:137] op_sel_hi:[1,0,1]
	v_lshl_add_u64 v[196:197], v[196:197], 2, s[90:91]
	global_store_dwordx4 v[196:197], v[136:139], off
	v_add_u32_e32 v196, 0x18010, v194
	v_mov_b32_e32 v197, v159
	v_sub_f32_e32 v137, v213, v216
	v_sub_f32_e32 v136, v212, v216
	v_sub_f32_e32 v139, v215, v216
	v_sub_f32_e32 v138, v214, v216
	v_pk_mul_f32 v[138:139], v[216:217], v[138:139] op_sel:[1,0]
	v_pk_mul_f32 v[136:137], v[216:217], v[136:137] op_sel:[1,0]
	v_pk_fma_f32 v[138:139], v[148:149], v[138:139], v[98:99]
	v_pk_fma_f32 v[136:137], v[150:151], v[136:137], v[96:97]
	v_pk_fma_f32 v[138:139], v[130:131], s[78:79], v[138:139] op_sel_hi:[1,0,1]
	v_pk_fma_f32 v[136:137], v[128:129], s[78:79], v[136:137] op_sel_hi:[1,0,1]
	v_lshl_add_u64 v[196:197], v[196:197], 2, s[90:91]
	global_store_dwordx4 v[196:197], v[136:139], off
	s_nop 1
	v_add_u32_e32 v138, 0x80, v206
	v_lshlrev_b32_e32 v136, 1, v138
	v_mov_b32_e32 v137, v159
	v_lshlrev_b32_e32 v233, 11, v138
	v_lshl_add_u64 v[196:197], v[136:137], 2, s[2:3]
	v_add_u32_e32 v136, v233, v158
	v_lshl_add_u64 v[136:137], v[136:137], 2, s[88:89]
	global_load_dwordx2 v[204:205], v[196:197], off
	v_add_u32_e32 v198, v233, v231
	global_load_dwordx4 v[136:139], v[136:137], off
	v_mov_b32_e32 v199, v159
	v_add_u32_e32 v207, 0x90, v206
	v_lshl_add_u64 v[198:199], v[198:199], 2, s[88:89]
	v_lshlrev_b32_e32 v234, 11, v207
	global_load_dwordx4 v[208:211], v[198:199], off
	v_add_u32_e32 v212, v234, v158
	v_mov_b32_e32 v213, v159
	v_lshl_add_u64 v[212:213], v[212:213], 2, s[88:89]
	global_load_dwordx4 v[212:215], v[212:213], off
	v_lshlrev_b32_e32 v198, 1, v207
	v_mov_b32_e32 v199, v159
	v_lshl_add_u64 v[198:199], v[198:199], 2, s[2:3]
	global_load_dwordx2 v[220:221], v[198:199], off
	v_add_u32_e32 v216, v234, v231
	v_mov_b32_e32 v217, v159
	v_lshl_add_u64 v[216:217], v[216:217], 2, s[88:89]
	global_load_dwordx4 v[216:219], v[216:217], off
	v_add_u32_e32 v238, 0x40000, v194
	v_mov_b32_e32 v239, v159
	v_lshl_add_u64 v[238:239], v[238:239], 2, s[90:91]
	s_waitcnt vmcnt(0)
;     template <bool LN, int BJ, int LO, int HI> DI void batch(const f32x4 (&acc)[2][2][4][2], unsigned row0, unsigned col0, const f32x4 (&gv)[2], const f32x4 (&bv)[2]) const {
;         f32x4 r[HI - LO]; float mean[(HI - LO) / 2], rstd[(HI - LO) / 2];
; #pragma unroll
;         for (int i = LO; i < HI; ++i) { const int ai = i >> 3, m = (i >> 1) & 3, n = i & 1; const unsigned row = row0 + ai * HALF + m * 16;
;             if (n == 0) { mean[(i - LO) >> 1] = 0.f; rstd[(i - LO) >> 1] = 1.f;
;                 if (LN) { const float2 st = *(const float2*)(stats + row * 2u); mean[(i - LO) >> 1] = st.x; rstd[(i - LO) >> 1] = st.y; } }
;             r[i - LO] = *(const f32x4*)(src + (row * (unsigned)DM + col0 + BJ * HALF + n * 16)); }
; #pragma unroll
;         for (int i = LO; i < HI; ++i) { const int ai = i >> 3, m = (i >> 1) & 3, n = i & 1; const unsigned row = row0 + ai * HALF + m * 16;
;             *(f32x4*)(Y + (row * (unsigned)DM + col0 + BJ * HALF + n * 16)) = acc[ai][BJ][m][n] + ((r[i - LO] - mean[(i - LO) >> 1]) * rstd[(i - LO) >> 1]) * gv[n] + bv[n]; }
;         __builtin_amdgcn_sched_barrier(0);
;     }
;     template <bool LN, int BJ> DI void load_gb(unsigned col0, f32x4 (&gv)[2], f32x4 (&bv)[2]) const {
; #pragma unroll
;         for (int n = 0; n < 2; ++n) {
;             if (LN) { gv[n] = *(const f32x4*)(gam + col0 + BJ * HALF + n * 16) * ALPHA; bv[n] = *(const f32x4*)(bet + col0 + BJ * HALF + n * 16) * ALPHA; }
	v_sub_f32_e32 v137, v137, v204
	v_sub_f32_e32 v136, v136, v204
	v_sub_f32_e32 v139, v139, v204
	v_sub_f32_e32 v138, v138, v204
	v_pk_mul_f32 v[138:139], v[204:205], v[138:139] op_sel:[1,0]
	v_pk_mul_f32 v[136:137], v[204:205], v[136:137] op_sel:[1,0]
	v_pk_fma_f32 v[138:139], v[152:153], v[138:139], v[94:95]
	v_pk_fma_f32 v[136:137], v[154:155], v[136:137], v[92:93]
	v_pk_fma_f32 v[138:139], v[134:135], s[78:79], v[138:139] op_sel_hi:[1,0,1]
	v_pk_fma_f32 v[136:137], v[132:133], s[78:79], v[136:137] op_sel_hi:[1,0,1]
	global_store_dwordx4 v[238:239], v[136:139], off
	s_nop 1
	v_sub_f32_e32 v137, v209, v204
	v_sub_f32_e32 v136, v208, v204
	v_sub_f32_e32 v139, v211, v204
	v_sub_f32_e32 v138, v210, v204
	v_pk_mul_f32 v[138:139], v[204:205], v[138:139] op_sel:[1,0]
	v_pk_mul_f32 v[136:137], v[204:205], v[136:137] op_sel:[1,0]
	v_pk_fma_f32 v[138:139], v[148:149], v[138:139], v[90:91]
	v_pk_fma_f32 v[136:137], v[150:151], v[136:137], v[88:89]
	v_add_u32_e32 v204, 0x40010, v194
	v_mov_b32_e32 v205, v159
	v_pk_fma_f32 v[138:139], v[130:131], s[78:79], v[138:139] op_sel_hi:[1,0,1]
	v_pk_fma_f32 v[136:137], v[128:129], s[78:79], v[136:137] op_sel_hi:[1,0,1]
	v_lshl_add_u64 v[204:205], v[204:205], 2, s[90:91]
	global_store_dwordx4 v[204:205], v[136:139], off
	v_add_u32_e32 v204, 0x48000, v194
	v_mov_b32_e32 v205, v159
	v_sub_f32_e32 v137, v213, v220
	v_sub_f32_e32 v136, v212, v220
	v_sub_f32_e32 v139, v215, v220
	v_sub_f32_e32 v138, v214, v220
	v_pk_mul_f32 v[138:139], v[220:221], v[138:139] op_sel:[1,0]
	v_pk_mul_f32 v[136:137], v[220:221], v[136:137] op_sel:[1,0]
	v_pk_fma_f32 v[138:139], v[152:153], v[138:139], v[86:87]
	v_pk_fma_f32 v[136:137], v[154:155], v[136:137], v[84:85]
	v_pk_fma_f32 v[138:139], v[134:135], s[78:79], v[138:139] op_sel_hi:[1,0,1]
	v_pk_fma_f32 v[136:137], v[132:133], s[78:79], v[136:137] op_sel_hi:[1,0,1]
	v_lshl_add_u64 v[204:205], v[204:205], 2, s[90:91]
	global_store_dwordx4 v[204:205], v[136:139], off
	v_add_u32_e32 v204, 0x48010, v194
	v_mov_b32_e32 v205, v159
	v_sub_f32_e32 v137, v217, v220
	v_sub_f32_e32 v136, v216, v220
	v_sub_f32_e32 v139, v219, v220
	v_sub_f32_e32 v138, v218, v220
	v_pk_mul_f32 v[138:139], v[220:221], v[138:139] op_sel:[1,0]
	v_pk_mul_f32 v[136:137], v[220:221], v[136:137] op_sel:[1,0]
	v_pk_fma_f32 v[138:139], v[148:149], v[138:139], v[82:83]
	v_pk_fma_f32 v[136:137], v[150:151], v[136:137], v[80:81]
	v_pk_fma_f32 v[138:139], v[130:131], s[78:79], v[138:139] op_sel_hi:[1,0,1]
	v_pk_fma_f32 v[136:137], v[128:129], s[78:79], v[136:137] op_sel_hi:[1,0,1]
	v_lshl_add_u64 v[204:205], v[204:205], 2, s[90:91]
	global_store_dwordx4 v[204:205], v[136:139], off
	s_nop 1
	v_add_u32_e32 v138, 0xa0, v206
	v_lshlrev_b32_e32 v136, 1, v138
	v_mov_b32_e32 v137, v159
	v_lshlrev_b32_e32 v237, 11, v138
	v_lshl_add_u64 v[204:205], v[136:137], 2, s[2:3]
	v_add_u32_e32 v136, v237, v158
	v_lshl_add_u64 v[136:137], v[136:137], 2, s[88:89]
	global_load_dwordx2 v[220:221], v[204:205], off
	v_add_u32_e32 v208, v237, v231
	global_load_dwordx4 v[136:139], v[136:137], off
	v_mov_b32_e32 v209, v159
	v_lshl_add_u64 v[208:209], v[208:209], 2, s[88:89]
	global_load_dwordx4 v[212:215], v[208:209], off
	v_add_u32_e32 v208, 0xb0, v206
	v_lshlrev_b32_e32 v206, 1, v208
	v_mov_b32_e32 v207, v159
	v_lshlrev_b32_e32 v238, 11, v208
	v_lshl_add_u64 v[210:211], v[206:207], 2, s[2:3]
	v_add_u32_e32 v206, v238, v158
	v_lshl_add_u64 v[206:207], v[206:207], 2, s[88:89]
	global_load_dwordx2 v[240:241], v[210:211], off
	v_add_u32_e32 v216, v238, v231
	global_load_dwordx4 v[206:209], v[206:207], off
	v_mov_b32_e32 v217, v159
	v_lshl_add_u64 v[216:217], v[216:217], 2, s[88:89]
	global_load_dwordx4 v[216:219], v[216:217], off
	v_add_u32_e32 v242, 0x50000, v194
	v_mov_b32_e32 v243, v159
	v_lshl_add_u64 v[242:243], v[242:243], 2, s[90:91]
	s_waitcnt vmcnt(0)
	v_sub_f32_e32 v137, v137, v220
	v_sub_f32_e32 v136, v136, v220
	v_sub_f32_e32 v139, v139, v220
	v_sub_f32_e32 v138, v138, v220
	v_pk_mul_f32 v[138:139], v[220:221], v[138:139] op_sel:[1,0]
	v_pk_mul_f32 v[136:137], v[220:221], v[136:137] op_sel:[1,0]
	v_pk_fma_f32 v[138:139], v[152:153], v[138:139], v[78:79]
	v_pk_fma_f32 v[136:137], v[154:155], v[136:137], v[76:77]
	v_pk_fma_f32 v[138:139], v[134:135], s[78:79], v[138:139] op_sel_hi:[1,0,1]
	v_pk_fma_f32 v[136:137], v[132:133], s[78:79], v[136:137] op_sel_hi:[1,0,1]
	global_store_dwordx4 v[242:243], v[136:139], off
	s_nop 1
	v_sub_f32_e32 v137, v213, v220
	v_sub_f32_e32 v136, v212, v220
	v_sub_f32_e32 v139, v215, v220
	v_sub_f32_e32 v138, v214, v220
	v_pk_mul_f32 v[138:139], v[220:221], v[138:139] op_sel:[1,0]
	v_pk_mul_f32 v[136:137], v[220:221], v[136:137] op_sel:[1,0]
	v_pk_fma_f32 v[138:139], v[148:149], v[138:139], v[74:75]
	v_pk_fma_f32 v[136:137], v[150:151], v[136:137], v[72:73]
	v_add_u32_e32 v212, 0x50010, v194
	v_mov_b32_e32 v213, v159
	v_pk_fma_f32 v[138:139], v[130:131], s[78:79], v[138:139] op_sel_hi:[1,0,1]
	v_pk_fma_f32 v[136:137], v[128:129], s[78:79], v[136:137] op_sel_hi:[1,0,1]
	v_lshl_add_u64 v[212:213], v[212:213], 2, s[90:91]
	global_store_dwordx4 v[212:213], v[136:139], off
	s_nop 1
	v_sub_f32_e32 v137, v207, v240
	v_sub_f32_e32 v136, v206, v240
	v_sub_f32_e32 v139, v209, v240
	v_sub_f32_e32 v138, v208, v240
	v_pk_mul_f32 v[136:137], v[240:241], v[136:137] op_sel:[1,0]
	v_pk_mul_f32 v[138:139], v[240:241], v[138:139] op_sel:[1,0]
	v_pk_fma_f32 v[136:137], v[154:155], v[136:137], v[68:69]
	v_pk_fma_f32 v[138:139], v[152:153], v[138:139], v[70:71]
	v_pk_fma_f32 v[132:133], v[132:133], s[78:79], v[136:137] op_sel_hi:[1,0,1]
	v_add_u32_e32 v136, 0x58000, v194
	v_mov_b32_e32 v137, v159
	v_pk_fma_f32 v[134:135], v[134:135], s[78:79], v[138:139] op_sel_hi:[1,0,1]
	v_lshl_add_u64 v[136:137], v[136:137], 2, s[90:91]
	global_store_dwordx4 v[136:137], v[132:135], off
	s_nop 1
	v_sub_f32_e32 v133, v217, v240
	v_sub_f32_e32 v132, v216, v240
	v_sub_f32_e32 v135, v219, v240
	v_sub_f32_e32 v134, v218, v240
	v_pk_mul_f32 v[132:133], v[240:241], v[132:133] op_sel:[1,0]
	v_pk_mul_f32 v[134:135], v[240:241], v[134:135] op_sel:[1,0]
	v_pk_fma_f32 v[132:133], v[150:151], v[132:133], v[64:65]
	v_pk_fma_f32 v[134:135], v[148:149], v[134:135], v[66:67]
	v_pk_fma_f32 v[128:129], v[128:129], s[78:79], v[132:133] op_sel_hi:[1,0,1]
	v_add_u32_e32 v132, 0x58010, v194
	v_mov_b32_e32 v133, v159
	v_pk_fma_f32 v[130:131], v[130:131], s[78:79], v[134:135] op_sel_hi:[1,0,1]
	v_lshl_add_u64 v[132:133], v[132:133], 2, s[90:91]
	global_store_dwordx4 v[132:133], v[128:131], off
	global_load_dwordx4 v[128:131], v[140:141], off offset:512
	v_add_u32_e32 v136, v232, v230
	v_mov_b32_e32 v137, v159
	v_lshl_add_u64 v[136:137], v[136:137], 2, s[88:89]
	s_waitcnt vmcnt(0)
;     template <bool LN, int BJ, int LO, int HI> DI void batch(const f32x4 (&acc)[2][2][4][2], unsigned row0, unsigned col0, const f32x4 (&gv)[2], const f32x4 (&bv)[2]) const {
;         f32x4 r[HI - LO]; float mean[(HI - LO) / 2], rstd[(HI - LO) / 2];
; #pragma unroll
;         for (int i = LO; i < HI; ++i) { const int ai = i >> 3, m = (i >> 1) & 3, n = i & 1; const unsigned row = row0 + ai * HALF + m * 16;
;             if (n == 0) { mean[(i - LO) >> 1] = 0.f; rstd[(i - LO) >> 1] = 1.f;
;                 if (LN) { const float2 st = *(const float2*)(stats + row * 2u); mean[(i - LO) >> 1] = st.x; rstd[(i - LO) >> 1] = st.y; } }
;             r[i - LO] = *(const f32x4*)(src + (row * (unsigned)DM + col0 + BJ * HALF + n * 16)); }
; #pragma unroll
;         for (int i = LO; i < HI; ++i) { const int ai = i >> 3, m = (i >> 1) & 3, n = i & 1; const unsigned row = row0 + ai * HALF + m * 16;
;             *(f32x4*)(Y + (row * (unsigned)DM + col0 + BJ * HALF + n * 16)) = acc[ai][BJ][m][n] + ((r[i - LO] - mean[(i - LO) >> 1]) * rstd[(i - LO) >> 1]) * gv[n] + bv[n]; }
	v_pk_mul_f32 v[212:213], v[130:131], s[78:79] op_sel_hi:[1,0]
	v_pk_mul_f32 v[214:215], v[128:129], s[78:79] op_sel_hi:[1,0]
	global_load_dwordx4 v[132:135], v[142:143], off offset:512
	global_load_dwordx4 v[128:131], v[140:141], off offset:576
	s_waitcnt vmcnt(0)
	v_pk_mul_f32 v[206:207], v[130:131], s[78:79] op_sel_hi:[1,0]
	v_pk_mul_f32 v[208:209], v[128:129], s[78:79] op_sel_hi:[1,0]
	global_load_dwordx4 v[128:131], v[142:143], off offset:576
	global_load_dwordx2 v[220:221], v[144:145], off
	global_load_dwordx4 v[240:243], v[136:137], off
	v_add_u32_e32 v136, v232, v229
	v_mov_b32_e32 v137, v159
	v_lshl_add_u64 v[136:137], v[136:137], 2, s[88:89]
	global_load_dwordx4 v[244:247], v[136:137], off
	global_load_dwordx2 v[218:219], v[146:147], off
	v_add_u32_e32 v136, v195, v230
	v_mov_b32_e32 v137, v159
	v_lshl_add_u64 v[136:137], v[136:137], 2, s[88:89]
	global_load_dwordx4 v[248:251], v[136:137], off
	v_add_u32_e32 v136, v195, v229
	v_mov_b32_e32 v137, v159
	v_lshl_add_u64 v[136:137], v[136:137], 2, s[88:89]
	global_load_dwordx4 v[152:155], v[136:137], off
	global_load_dwordx2 v[216:217], v[200:201], off
	v_add_u32_e32 v136, v236, v230
	v_mov_b32_e32 v137, v159
	v_lshl_add_u64 v[136:137], v[136:137], 2, s[88:89]
	global_load_dwordx4 v[148:151], v[136:137], off
	v_add_u32_e32 v136, v236, v229
	v_mov_b32_e32 v137, v159
	v_lshl_add_u64 v[136:137], v[136:137], 2, s[88:89]
	global_load_dwordx4 v[144:147], v[136:137], off
	global_load_dwordx2 v[200:201], v[202:203], off
	v_add_u32_e32 v136, v235, v230
	v_mov_b32_e32 v137, v159
	v_lshl_add_u64 v[136:137], v[136:137], 2, s[88:89]
	global_load_dwordx4 v[140:143], v[136:137], off
	v_add_u32_e32 v136, v235, v229
	v_mov_b32_e32 v137, v159
	v_lshl_add_u64 v[136:137], v[136:137], 2, s[88:89]
	global_load_dwordx4 v[136:139], v[136:137], off
	v_add_u32_e32 v202, 0x80, v194
	v_mov_b32_e32 v203, v159
	v_lshl_add_u64 v[202:203], v[202:203], 2, s[90:91]
	s_waitcnt vmcnt(0)
	v_sub_f32_e32 v241, v241, v220
	v_sub_f32_e32 v240, v240, v220
	v_sub_f32_e32 v243, v243, v220
	v_sub_f32_e32 v242, v242, v220
	v_pk_mul_f32 v[242:243], v[220:221], v[242:243] op_sel:[1,0]
	v_pk_mul_f32 v[240:241], v[220:221], v[240:241] op_sel:[1,0]
	v_pk_fma_f32 v[242:243], v[212:213], v[242:243], v[62:63]
	v_pk_fma_f32 v[240:241], v[214:215], v[240:241], v[60:61]
	v_pk_fma_f32 v[242:243], v[134:135], s[78:79], v[242:243] op_sel_hi:[1,0,1]
	v_pk_fma_f32 v[240:241], v[132:133], s[78:79], v[240:241] op_sel_hi:[1,0,1]
	global_store_dwordx4 v[202:203], v[240:243], off
	v_sub_f32_e32 v203, v245, v220
	v_sub_f32_e32 v202, v244, v220
	v_sub_f32_e32 v241, v247, v220
	v_sub_f32_e32 v240, v246, v220
	v_pk_mul_f32 v[202:203], v[220:221], v[202:203] op_sel:[1,0]
	v_pk_mul_f32 v[240:241], v[220:221], v[240:241] op_sel:[1,0]
	v_pk_fma_f32 v[202:203], v[208:209], v[202:203], v[56:57]
	v_pk_fma_f32 v[220:221], v[206:207], v[240:241], v[58:59]
	v_pk_fma_f32 v[240:241], v[128:129], s[78:79], v[202:203] op_sel_hi:[1,0,1]
	v_add_u32_e32 v202, 0x90, v194
	v_mov_b32_e32 v203, v159
	v_pk_fma_f32 v[242:243], v[130:131], s[78:79], v[220:221] op_sel_hi:[1,0,1]
	v_lshl_add_u64 v[202:203], v[202:203], 2, s[90:91]
	global_store_dwordx4 v[202:203], v[240:243], off
	v_sub_f32_e32 v203, v249, v218
	v_sub_f32_e32 v202, v248, v218
	v_sub_f32_e32 v221, v251, v218
	v_sub_f32_e32 v220, v250, v218
	v_pk_mul_f32 v[202:203], v[218:219], v[202:203] op_sel:[1,0]
	v_pk_mul_f32 v[220:221], v[218:219], v[220:221] op_sel:[1,0]
	v_pk_fma_f32 v[202:203], v[214:215], v[202:203], v[52:53]
	v_pk_fma_f32 v[220:221], v[212:213], v[220:221], v[54:55]
	v_pk_fma_f32 v[240:241], v[132:133], s[78:79], v[202:203] op_sel_hi:[1,0,1]
	v_add_u32_e32 v202, 0x8080, v194
	v_mov_b32_e32 v203, v159
	v_sub_f32_e32 v153, v153, v218
	v_sub_f32_e32 v152, v152, v218
	v_sub_f32_e32 v155, v155, v218
	v_sub_f32_e32 v154, v154, v218
	v_pk_fma_f32 v[242:243], v[134:135], s[78:79], v[220:221] op_sel_hi:[1,0,1]
	v_lshl_add_u64 v[202:203], v[202:203], 2, s[90:91]
	v_pk_mul_f32 v[154:155], v[218:219], v[154:155] op_sel:[1,0]
	v_pk_mul_f32 v[152:153], v[218:219], v[152:153] op_sel:[1,0]
	global_store_dwordx4 v[202:203], v[240:243], off
	v_pk_fma_f32 v[152:153], v[208:209], v[152:153], v[48:49]
	v_pk_fma_f32 v[154:155], v[206:207], v[154:155], v[50:51]
	v_add_u32_e32 v202, 0x8090, v194
	v_mov_b32_e32 v203, v159
	v_sub_f32_e32 v149, v149, v216
	v_sub_f32_e32 v148, v148, v216
	v_sub_f32_e32 v151, v151, v216
	v_sub_f32_e32 v150, v150, v216
	v_pk_fma_f32 v[154:155], v[130:131], s[78:79], v[154:155] op_sel_hi:[1,0,1]
	v_pk_fma_f32 v[152:153], v[128:129], s[78:79], v[152:153] op_sel_hi:[1,0,1]
	v_lshl_add_u64 v[202:203], v[202:203], 2, s[90:91]
	v_pk_mul_f32 v[150:151], v[216:217], v[150:151] op_sel:[1,0]
	v_pk_mul_f32 v[148:149], v[216:217], v[148:149] op_sel:[1,0]
	global_store_dwordx4 v[202:203], v[152:155], off
	v_pk_fma_f32 v[148:149], v[214:215], v[148:149], v[44:45]
	v_pk_fma_f32 v[150:151], v[212:213], v[150:151], v[46:47]
	v_add_u32_e32 v152, 0x10080, v194
	v_mov_b32_e32 v153, v159
	v_sub_f32_e32 v145, v145, v216
	v_sub_f32_e32 v144, v144, v216
	v_sub_f32_e32 v147, v147, v216
	v_sub_f32_e32 v146, v146, v216
	v_pk_fma_f32 v[150:151], v[134:135], s[78:79], v[150:151] op_sel_hi:[1,0,1]
	v_pk_fma_f32 v[148:149], v[132:133], s[78:79], v[148:149] op_sel_hi:[1,0,1]
	v_lshl_add_u64 v[152:153], v[152:153], 2, s[90:91]
	v_pk_mul_f32 v[146:147], v[216:217], v[146:147] op_sel:[1,0]
	v_pk_mul_f32 v[144:145], v[216:217], v[144:145] op_sel:[1,0]
	global_store_dwordx4 v[152:153], v[148:151], off
	v_pk_fma_f32 v[144:145], v[208:209], v[144:145], v[40:41]
	v_pk_fma_f32 v[146:147], v[206:207], v[146:147], v[42:43]
;     template <bool LN, int BJ, int LO, int HI> DI void batch(const f32x4 (&acc)[2][2][4][2], unsigned row0, unsigned col0, const f32x4 (&gv)[2], const f32x4 (&bv)[2]) const {
;         f32x4 r[HI - LO]; float mean[(HI - LO) / 2], rstd[(HI - LO) / 2];
; #pragma unroll
;         for (int i = LO; i < HI; ++i) { const int ai = i >> 3, m = (i >> 1) & 3, n = i & 1; const unsigned row = row0 + ai * HALF + m * 16;
;             if (n == 0) { mean[(i - LO) >> 1] = 0.f; rstd[(i - LO) >> 1] = 1.f;
;                 if (LN) { const float2 st = *(const float2*)(stats + row * 2u); mean[(i - LO) >> 1] = st.x; rstd[(i - LO) >> 1] = st.y; } }
;             r[i - LO] = *(const f32x4*)(src + (row * (unsigned)DM + col0 + BJ * HALF + n * 16)); }
; #pragma unroll
;         for (int i = LO; i < HI; ++i) { const int ai = i >> 3, m = (i >> 1) & 3, n = i & 1; const unsigned row = row0 + ai * HALF + m * 16;
;             *(f32x4*)(Y + (row * (unsigned)DM + col0 + BJ * HALF + n * 16)) = acc[ai][BJ][m][n] + ((r[i - LO] - mean[(i - LO) >> 1]) * rstd[(i - LO) >> 1]) * gv[n] + bv[n]; }
	v_add_u32_e32 v148, 0x10090, v194
	v_mov_b32_e32 v149, v159
	v_sub_f32_e32 v141, v141, v200
	v_sub_f32_e32 v140, v140, v200
	v_sub_f32_e32 v143, v143, v200
	v_sub_f32_e32 v142, v142, v200
	v_pk_fma_f32 v[146:147], v[130:131], s[78:79], v[146:147] op_sel_hi:[1,0,1]
	v_pk_fma_f32 v[144:145], v[128:129], s[78:79], v[144:145] op_sel_hi:[1,0,1]
	v_lshl_add_u64 v[148:149], v[148:149], 2, s[90:91]
	v_pk_mul_f32 v[142:143], v[200:201], v[142:143] op_sel:[1,0]
	v_pk_mul_f32 v[140:141], v[200:201], v[140:141] op_sel:[1,0]
	global_store_dwordx4 v[148:149], v[144:147], off
	v_pk_fma_f32 v[140:141], v[214:215], v[140:141], v[36:37]
	v_pk_fma_f32 v[142:143], v[212:213], v[142:143], v[38:39]
	v_add_u32_e32 v144, 0x18080, v194
	v_mov_b32_e32 v145, v159
	v_sub_f32_e32 v137, v137, v200
	v_sub_f32_e32 v136, v136, v200
	v_sub_f32_e32 v139, v139, v200
	v_sub_f32_e32 v138, v138, v200
	v_pk_fma_f32 v[142:143], v[134:135], s[78:79], v[142:143] op_sel_hi:[1,0,1]
	v_pk_fma_f32 v[140:141], v[132:133], s[78:79], v[140:141] op_sel_hi:[1,0,1]
	v_lshl_add_u64 v[144:145], v[144:145], 2, s[90:91]
	v_pk_mul_f32 v[138:139], v[200:201], v[138:139] op_sel:[1,0]
	v_pk_mul_f32 v[136:137], v[200:201], v[136:137] op_sel:[1,0]
	global_store_dwordx4 v[144:145], v[140:143], off
	v_pk_fma_f32 v[136:137], v[208:209], v[136:137], v[32:33]
	v_pk_fma_f32 v[138:139], v[206:207], v[138:139], v[34:35]
	v_add_u32_e32 v140, 0x18090, v194
	v_mov_b32_e32 v141, v159
	v_pk_fma_f32 v[138:139], v[130:131], s[78:79], v[138:139] op_sel_hi:[1,0,1]
	v_pk_fma_f32 v[136:137], v[128:129], s[78:79], v[136:137] op_sel_hi:[1,0,1]
	v_lshl_add_u64 v[140:141], v[140:141], 2, s[90:91]
	global_store_dwordx4 v[140:141], v[136:139], off
	s_nop 1
	v_add_u32_e32 v136, v233, v230
	v_mov_b32_e32 v137, v159
	v_lshl_add_u64 v[136:137], v[136:137], 2, s[88:89]
	global_load_dwordx2 v[220:221], v[196:197], off
	global_load_dwordx4 v[216:219], v[136:137], off
	v_add_u32_e32 v136, v233, v229
	v_mov_b32_e32 v137, v159
	v_lshl_add_u64 v[136:137], v[136:137], 2, s[88:89]
	global_load_dwordx4 v[240:243], v[136:137], off
	global_load_dwordx2 v[200:201], v[198:199], off
	v_add_u32_e32 v136, v234, v230
	v_mov_b32_e32 v137, v159
	v_lshl_add_u64 v[136:137], v[136:137], 2, s[88:89]
	global_load_dwordx4 v[244:247], v[136:137], off
	v_add_u32_e32 v136, v234, v229
	v_mov_b32_e32 v137, v159
	v_lshl_add_u64 v[136:137], v[136:137], 2, s[88:89]
	global_load_dwordx4 v[152:155], v[136:137], off
	global_load_dwordx2 v[198:199], v[204:205], off
	v_add_u32_e32 v136, v237, v230
	v_mov_b32_e32 v137, v159
	v_lshl_add_u64 v[136:137], v[136:137], 2, s[88:89]
	global_load_dwordx4 v[148:151], v[136:137], off
	v_add_u32_e32 v136, v237, v229
	v_mov_b32_e32 v137, v159
	v_lshl_add_u64 v[136:137], v[136:137], 2, s[88:89]
	global_load_dwordx4 v[144:147], v[136:137], off
	global_load_dwordx2 v[196:197], v[210:211], off
	v_add_u32_e32 v136, v238, v230
	v_mov_b32_e32 v137, v159
	v_lshl_add_u64 v[136:137], v[136:137], 2, s[88:89]
	global_load_dwordx4 v[140:143], v[136:137], off
	v_add_u32_e32 v136, v238, v229
	v_mov_b32_e32 v137, v159
	v_lshl_add_u64 v[136:137], v[136:137], 2, s[88:89]
	global_load_dwordx4 v[136:139], v[136:137], off
	v_add_u32_e32 v210, 0x40080, v194
	v_mov_b32_e32 v211, v159
	v_lshl_add_u64 v[210:211], v[210:211], 2, s[90:91]
	s_waitcnt vmcnt(0)
;     template <bool LN, int BJ, int LO, int HI> DI void batch(const f32x4 (&acc)[2][2][4][2], unsigned row0, unsigned col0, const f32x4 (&gv)[2], const f32x4 (&bv)[2]) const {
;         f32x4 r[HI - LO]; float mean[(HI - LO) / 2], rstd[(HI - LO) / 2];
; #pragma unroll
;         for (int i = LO; i < HI; ++i) { const int ai = i >> 3, m = (i >> 1) & 3, n = i & 1; const unsigned row = row0 + ai * HALF + m * 16;
;             if (n == 0) { mean[(i - LO) >> 1] = 0.f; rstd[(i - LO) >> 1] = 1.f;
;                 if (LN) { const float2 st = *(const float2*)(stats + row * 2u); mean[(i - LO) >> 1] = st.x; rstd[(i - LO) >> 1] = st.y; } }
;             r[i - LO] = *(const f32x4*)(src + (row * (unsigned)DM + col0 + BJ * HALF + n * 16)); }
; #pragma unroll
;         for (int i = LO; i < HI; ++i) { const int ai = i >> 3, m = (i >> 1) & 3, n = i & 1; const unsigned row = row0 + ai * HALF + m * 16;
;             *(f32x4*)(Y + (row * (unsigned)DM + col0 + BJ * HALF + n * 16)) = acc[ai][BJ][m][n] + ((r[i - LO] - mean[(i - LO) >> 1]) * rstd[(i - LO) >> 1]) * gv[n] + bv[n]; }
	v_sub_f32_e32 v203, v217, v220
	v_sub_f32_e32 v202, v216, v220
	v_sub_f32_e32 v205, v219, v220
	v_sub_f32_e32 v204, v218, v220
	v_pk_mul_f32 v[204:205], v[220:221], v[204:205] op_sel:[1,0]
	v_pk_mul_f32 v[202:203], v[220:221], v[202:203] op_sel:[1,0]
	v_pk_fma_f32 v[204:205], v[212:213], v[204:205], v[30:31]
	v_pk_fma_f32 v[202:203], v[214:215], v[202:203], v[28:29]
	v_pk_fma_f32 v[204:205], v[134:135], s[78:79], v[204:205] op_sel_hi:[1,0,1]
	v_pk_fma_f32 v[202:203], v[132:133], s[78:79], v[202:203] op_sel_hi:[1,0,1]
	global_store_dwordx4 v[210:211], v[202:205], off
	v_add_u32_e32 v210, 0x40090, v194
	v_mov_b32_e32 v211, v159
	v_sub_f32_e32 v203, v241, v220
	v_sub_f32_e32 v202, v240, v220
	v_sub_f32_e32 v205, v243, v220
	v_sub_f32_e32 v204, v242, v220
	v_pk_mul_f32 v[204:205], v[220:221], v[204:205] op_sel:[1,0]
	v_pk_mul_f32 v[202:203], v[220:221], v[202:203] op_sel:[1,0]
	v_pk_fma_f32 v[204:205], v[206:207], v[204:205], v[26:27]
	v_pk_fma_f32 v[202:203], v[208:209], v[202:203], v[24:25]
	v_pk_fma_f32 v[204:205], v[130:131], s[78:79], v[204:205] op_sel_hi:[1,0,1]
	v_pk_fma_f32 v[202:203], v[128:129], s[78:79], v[202:203] op_sel_hi:[1,0,1]
	v_lshl_add_u64 v[210:211], v[210:211], 2, s[90:91]
	global_store_dwordx4 v[210:211], v[202:205], off
	v_sub_f32_e32 v149, v149, v198
	v_sub_f32_e32 v148, v148, v198
	v_sub_f32_e32 v203, v245, v200
	v_sub_f32_e32 v202, v244, v200
	v_sub_f32_e32 v141, v141, v196
	v_sub_f32_e32 v140, v140, v196
	v_sub_f32_e32 v205, v247, v200
	v_sub_f32_e32 v204, v246, v200
	v_pk_mul_f32 v[202:203], v[200:201], v[202:203] op_sel:[1,0]
	v_sub_f32_e32 v151, v151, v198
	v_sub_f32_e32 v150, v150, v198
	v_pk_mul_f32 v[148:149], v[198:199], v[148:149] op_sel:[1,0]
	v_sub_f32_e32 v143, v143, v196
	v_sub_f32_e32 v142, v142, v196
	v_pk_mul_f32 v[140:141], v[196:197], v[140:141] op_sel:[1,0]
	v_pk_mul_f32 v[204:205], v[200:201], v[204:205] op_sel:[1,0]
	v_pk_fma_f32 v[202:203], v[214:215], v[202:203], v[20:21]
	v_sub_f32_e32 v153, v153, v200
	v_sub_f32_e32 v152, v152, v200
	v_sub_f32_e32 v155, v155, v200
	v_sub_f32_e32 v154, v154, v200
	v_pk_mul_f32 v[150:151], v[198:199], v[150:151] op_sel:[1,0]
	v_pk_fma_f32 v[148:149], v[214:215], v[148:149], v[12:13]
	v_pk_mul_f32 v[142:143], v[196:197], v[142:143] op_sel:[1,0]
	v_pk_fma_f32 v[140:141], v[214:215], v[140:141], v[4:5]
	v_pk_fma_f32 v[204:205], v[212:213], v[204:205], v[22:23]
	v_pk_fma_f32 v[202:203], v[132:133], s[78:79], v[202:203] op_sel_hi:[1,0,1]
	v_pk_mul_f32 v[154:155], v[200:201], v[154:155] op_sel:[1,0]
	v_pk_mul_f32 v[152:153], v[200:201], v[152:153] op_sel:[1,0]
	v_pk_fma_f32 v[150:151], v[212:213], v[150:151], v[14:15]
	v_pk_fma_f32 v[148:149], v[132:133], s[78:79], v[148:149] op_sel_hi:[1,0,1]
	v_pk_fma_f32 v[142:143], v[212:213], v[142:143], v[6:7]
	v_pk_fma_f32 v[132:133], v[132:133], s[78:79], v[140:141] op_sel_hi:[1,0,1]
	v_add_u32_e32 v140, 0x58080, v194
	v_mov_b32_e32 v141, v159
	v_pk_fma_f32 v[204:205], v[134:135], s[78:79], v[204:205] op_sel_hi:[1,0,1]
	v_pk_fma_f32 v[152:153], v[208:209], v[152:153], v[16:17]
	v_pk_fma_f32 v[154:155], v[206:207], v[154:155], v[18:19]
	v_add_u32_e32 v200, 0x48090, v194
	v_mov_b32_e32 v201, v159
	v_pk_fma_f32 v[150:151], v[134:135], s[78:79], v[150:151] op_sel_hi:[1,0,1]
	v_pk_fma_f32 v[134:135], v[134:135], s[78:79], v[142:143] op_sel_hi:[1,0,1]
	v_lshl_add_u64 v[140:141], v[140:141], 2, s[90:91]
	v_pk_fma_f32 v[154:155], v[130:131], s[78:79], v[154:155] op_sel_hi:[1,0,1]
	v_pk_fma_f32 v[152:153], v[128:129], s[78:79], v[152:153] op_sel_hi:[1,0,1]
	v_lshl_add_u64 v[200:201], v[200:201], 2, s[90:91]
	v_sub_f32_e32 v145, v145, v198
	v_sub_f32_e32 v144, v144, v198
	global_store_dwordx4 v[140:141], v[132:135], off
	global_store_dwordx4 v[200:201], v[152:155], off
	v_sub_f32_e32 v147, v147, v198
	v_sub_f32_e32 v133, v137, v196
	v_sub_f32_e32 v132, v136, v196
	v_add_u32_e32 v152, 0x50080, v194
	v_mov_b32_e32 v153, v159
	v_sub_f32_e32 v146, v146, v198
	v_pk_mul_f32 v[144:145], v[198:199], v[144:145] op_sel:[1,0]
	v_sub_f32_e32 v135, v139, v196
	v_sub_f32_e32 v134, v138, v196
	v_pk_mul_f32 v[132:133], v[196:197], v[132:133] op_sel:[1,0]
	v_lshl_add_u64 v[152:153], v[152:153], 2, s[90:91]
	v_pk_mul_f32 v[146:147], v[198:199], v[146:147] op_sel:[1,0]
	v_pk_fma_f32 v[144:145], v[208:209], v[144:145], v[8:9]
	v_pk_mul_f32 v[134:135], v[196:197], v[134:135] op_sel:[1,0]
	v_pk_fma_f32 v[132:133], v[208:209], v[132:133], v[0:1]
	v_add_u32_e32 v210, 0x48080, v194
	v_mov_b32_e32 v211, v159
	global_store_dwordx4 v[152:153], v[148:151], off
	v_pk_fma_f32 v[146:147], v[206:207], v[146:147], v[10:11]
	v_pk_fma_f32 v[144:145], v[128:129], s[78:79], v[144:145] op_sel_hi:[1,0,1]
	v_add_u32_e32 v148, 0x50090, v194
	v_mov_b32_e32 v149, v159
	v_pk_fma_f32 v[134:135], v[206:207], v[134:135], v[2:3]
	v_pk_fma_f32 v[128:129], v[128:129], s[78:79], v[132:133] op_sel_hi:[1,0,1]
	v_add_u32_e32 v132, 0x58090, v194
	v_mov_b32_e32 v133, v159
	v_lshl_add_u64 v[210:211], v[210:211], 2, s[90:91]
	v_pk_fma_f32 v[146:147], v[130:131], s[78:79], v[146:147] op_sel_hi:[1,0,1]
	v_lshl_add_u64 v[148:149], v[148:149], 2, s[90:91]
	v_pk_fma_f32 v[130:131], v[130:131], s[78:79], v[134:135] op_sel_hi:[1,0,1]
	v_lshl_add_u64 v[132:133], v[132:133], 2, s[90:91]
	global_store_dwordx4 v[210:211], v[202:205], off
	global_store_dwordx4 v[148:149], v[144:147], off
	global_store_dwordx4 v[132:133], v[128:131], off
	s_mov_b64 s[20:21], 0
	s_branch .LBB0_81

; #define PG8_STAGE(bufoff, gbase) do { _Pragma("unroll") for (int _i = 0; _i < 2; ++_i) \
;         __builtin_amdgcn_global_load_lds((const unsigned*)((const char*)(gbase) + voff[_i]), (LAS unsigned*)(lds + (bufoff) + ldsw + _i * 8192), 16, 0, 0); } while (0)
; #define PG8_LDA(dst, b, h) do { _Pragma("unroll") for (int m = 0; m < 4; ++m) _Pragma("unroll") for (int k = 0; k < 2; ++k) dst[m][k] = *(const LAS bf16x8*)(lds + PG8_SA(b, h) + aoff + m * 2048 + k * 1024); } while (0)
; #define PG8_LDB(dst, b, h) do { _Pragma("unroll") for (int n = 0; n < 2; ++n) _Pragma("unroll") for (int k = 0; k < 2; ++k) dst[n][k] = *(const LAS bf16x8*)(lds + PG8_SB(b, h) + boff + n * 2048 + k * 1024); } while (0)
; #define PG8_MMA(ai, bj, At, Bt) do { __builtin_amdgcn_s_setprio(1); _Pragma("unroll") for (int m = 0; m < 4; ++m) _Pragma("unroll") for (int n = 0; n < 2; ++n) _Pragma("unroll") for (int k = 0; k < 2; ++k) \
;         acc[ai][bj][m][n] = __builtin_amdgcn_mfma_f32_16x16x32_bf16(Bt[n][k], At[m][k], acc[ai][bj][m][n], 0, 0, 0); __builtin_amdgcn_s_setprio(0); } while (0)
; #define PG8_WAIT_L(n) asm volatile("s_waitcnt lgkmcnt(" #n ")" ::: "memory")
; #define PG8_BAR __builtin_amdgcn_s_barrier()
; #define PG8_SCHED __builtin_amdgcn_sched_barrier(0)
; template <class Epi>
; DI void gemm_phase(LAS unsigned char* lds, const Gemm g, const StaticOrder& S, const Epi& E) {
;     ...
;             const bool last = (t == nt - 2);
;             const char* a1 = cA + (size_t)(t + 1) * kstep;
;             const char* a2 = last ? nA : cA + (size_t)(t + 2) * kstep; const char* b2 = last ? nB : cB + (size_t)(t + 2) * kstep;
;             const char* a3 = a2 + kstep; const char* b3 = b2 + kstep;
;             PG8_LDB(B0, 0, 0); PG8_SCHED; PG8_LDA(At, 0, 0); PG8_STAGE(PG8_SA(1, 1), a1 + hstep);
;             PG8_WAIT_L(8); PG8_BAR; PG8_WAIT_L(0); PG8_MMA(0, 0, At, B0); PG8_BAR; PG8_SCHED;
;             PG8_LDB(B1, 0, 1); PG8_STAGE(PG8_SB(0, 0), b2);
;             PG8_BAR; PG8_WAIT_L(0); PG8_MMA(0, 1, At, B1); PG8_BAR;
;             PG8_LDA(At, 0, 1); PG8_STAGE(PG8_SA(0, 0), a2);
;             PG8_BAR; PG8_WAIT_L(0); PG8_MMA(1, 0, At, B0); PG8_BAR; PG8_SCHED;
.LBB0_134:
	s_add_u32 s18, s16, 0x100
	s_addc_u32 s19, s17, 0
	s_add_i32 s39, 0, 0x10000
	v_add_u32_e32 v148, s39, v199
	ds_read_b128 v[96:99], v148
	ds_read_b128 v[100:103], v148 offset:1024
	ds_read_b128 v[136:139], v148 offset:2048
	ds_read_b128 v[148:151], v148 offset:3072
	s_cmpk_eq_i32 s33, 0x54
	s_cselect_b32 s23, s9, s19
	s_cselect_b32 s22, s8, s18
	s_cselect_b32 s21, s11, s5
	s_cselect_b32 s20, s10, s4
	v_lshl_add_u64 v[218:219], s[16:17], 0, v[144:145]
	s_add_i32 m0, s28, 0xc000
	ds_read_b128 v[152:155], v201
	ds_read_b128 v[186:189], v201 offset:1024
	ds_read_b128 v[190:193], v201 offset:2048
	ds_read_b128 v[194:197], v201 offset:3072
	ds_read_b128 v[202:205], v201 offset:4096
	ds_read_b128 v[206:209], v201 offset:5120
	ds_read_b128 v[210:213], v201 offset:6144
	ds_read_b128 v[214:217], v201 offset:7168
	global_load_lds_dwordx4 v[218:219], off
	v_lshl_add_u64 v[218:219], s[16:17], 0, v[146:147]
	s_add_i32 m0, s28, 0xe000
	s_nop 0
	global_load_lds_dwordx4 v[218:219], off
	s_waitcnt lgkmcnt(8)
	s_setprio 1
	s_barrier
	s_waitcnt lgkmcnt(0)
	v_mfma_f32_16x16x32_bf16 v[132:135], v[96:99], v[152:155], v[132:135]
	v_mfma_f32_16x16x32_bf16 v[128:131], v[136:139], v[152:155], v[128:131]
	s_add_i32 s40, 0, 0x14000
	v_mfma_f32_16x16x32_bf16 v[124:127], v[96:99], v[190:193], v[124:127]
	s_add_i32 s16, s39, s27
	v_mfma_f32_16x16x32_bf16 v[120:123], v[136:139], v[190:193], v[120:123]
	v_add_u32_e32 v158, s40, v199
	v_mfma_f32_16x16x32_bf16 v[116:119], v[96:99], v[202:205], v[116:119]
	v_lshl_add_u64 v[218:219], s[20:21], 0, v[142:143]
	v_mfma_f32_16x16x32_bf16 v[112:115], v[136:139], v[202:205], v[112:115]
	s_mov_b32 m0, s16
	v_mfma_f32_16x16x32_bf16 v[108:111], v[96:99], v[210:213], v[108:111]
	v_mfma_f32_16x16x32_bf16 v[104:107], v[136:139], v[210:213], v[104:107]
	v_mfma_f32_16x16x32_bf16 v[132:135], v[100:103], v[186:189], v[132:135]
	v_mfma_f32_16x16x32_bf16 v[128:131], v[148:151], v[186:189], v[128:131]
	v_mfma_f32_16x16x32_bf16 v[124:127], v[100:103], v[194:197], v[124:127]
	v_mfma_f32_16x16x32_bf16 v[120:123], v[148:151], v[194:197], v[120:123]
	v_mfma_f32_16x16x32_bf16 v[116:119], v[100:103], v[206:209], v[116:119]
	v_mfma_f32_16x16x32_bf16 v[112:115], v[148:151], v[206:209], v[112:115]
	v_mfma_f32_16x16x32_bf16 v[108:111], v[100:103], v[214:217], v[108:111]
	v_mfma_f32_16x16x32_bf16 v[104:107], v[148:151], v[214:217], v[104:107]
	s_setprio 0
	s_barrier
	ds_read_b128 v[226:229], v158
	ds_read_b128 v[230:233], v158 offset:1024
	ds_read_b128 v[234:237], v158 offset:2048
	ds_read_b128 v[238:241], v158 offset:3072
	global_load_lds_dwordx4 v[218:219], off
	v_lshl_add_u64 v[220:221], s[20:21], 0, v[140:141]
	s_add_i32 m0, s16, 0x2000
	s_nop 0
	global_load_lds_dwordx4 v[220:221], off
	s_waitcnt lgkmcnt(0)
	s_setprio 1
	s_barrier
	v_mfma_f32_16x16x32_bf16 v[60:63], v[226:229], v[152:155], v[60:63]
	v_mfma_f32_16x16x32_bf16 v[56:59], v[234:237], v[152:155], v[56:59]
	v_mfma_f32_16x16x32_bf16 v[52:55], v[226:229], v[190:193], v[52:55]
	v_mfma_f32_16x16x32_bf16 v[48:51], v[234:237], v[190:193], v[48:51]
	v_mfma_f32_16x16x32_bf16 v[44:47], v[226:229], v[202:205], v[44:47]
	v_mfma_f32_16x16x32_bf16 v[40:43], v[234:237], v[202:205], v[40:43]
	v_mfma_f32_16x16x32_bf16 v[36:39], v[226:229], v[210:213], v[36:39]
	v_mfma_f32_16x16x32_bf16 v[32:35], v[234:237], v[210:213], v[32:35]
	v_mfma_f32_16x16x32_bf16 v[60:63], v[230:233], v[186:189], v[60:63]
	s_mov_b32 m0, s28
	v_mfma_f32_16x16x32_bf16 v[56:59], v[238:241], v[186:189], v[56:59]
	v_lshl_add_u64 v[242:243], s[22:23], 0, v[142:143]
	v_mfma_f32_16x16x32_bf16 v[52:55], v[230:233], v[194:197], v[52:55]
	v_mfma_f32_16x16x32_bf16 v[48:51], v[238:241], v[194:197], v[48:51]
	v_mfma_f32_16x16x32_bf16 v[44:47], v[230:233], v[206:209], v[44:47]
	v_mfma_f32_16x16x32_bf16 v[40:43], v[238:241], v[206:209], v[40:43]
	v_mfma_f32_16x16x32_bf16 v[36:39], v[230:233], v[214:217], v[36:39]
	v_mfma_f32_16x16x32_bf16 v[32:35], v[238:241], v[214:217], v[32:35]
	s_setprio 0
	s_barrier
	ds_read_b128 v[152:155], v201 offset:16384
	ds_read_b128 v[186:189], v201 offset:17408
	ds_read_b128 v[190:193], v201 offset:18432
	ds_read_b128 v[194:197], v201 offset:19456
	ds_read_b128 v[202:205], v201 offset:20480
	ds_read_b128 v[206:209], v201 offset:21504
	ds_read_b128 v[210:213], v201 offset:22528
	ds_read_b128 v[214:217], v201 offset:23552
	global_load_lds_dwordx4 v[242:243], off
	v_lshl_add_u64 v[244:245], s[22:23], 0, v[140:141]
	s_mov_b32 m0, s29
	s_nop 0
	global_load_lds_dwordx4 v[244:245], off
	s_waitcnt lgkmcnt(0)
	s_setprio 1
	s_barrier
	v_mfma_f32_16x16x32_bf16 v[92:95], v[96:99], v[152:155], v[92:95]
	v_mfma_f32_16x16x32_bf16 v[88:91], v[136:139], v[152:155], v[88:91]
	s_add_u32 s16, s20, 0x160000
	v_mfma_f32_16x16x32_bf16 v[84:87], v[96:99], v[190:193], v[84:87]
	s_addc_u32 s17, s21, 0
	v_mfma_f32_16x16x32_bf16 v[80:83], v[136:139], v[190:193], v[80:83]
	s_add_i32 s39, s40, s27
	v_mfma_f32_16x16x32_bf16 v[76:79], v[96:99], v[202:205], v[76:79]
	v_mfma_f32_16x16x32_bf16 v[72:75], v[136:139], v[202:205], v[72:75]
	v_mfma_f32_16x16x32_bf16 v[68:71], v[96:99], v[210:213], v[68:71]
	v_mfma_f32_16x16x32_bf16 v[64:67], v[136:139], v[210:213], v[64:67]
	v_mfma_f32_16x16x32_bf16 v[92:95], v[100:103], v[186:189], v[92:95]
	v_mfma_f32_16x16x32_bf16 v[88:91], v[148:151], v[186:189], v[88:91]
	v_mfma_f32_16x16x32_bf16 v[84:87], v[100:103], v[194:197], v[84:87]
	v_mfma_f32_16x16x32_bf16 v[80:83], v[148:151], v[194:197], v[80:83]
	v_mfma_f32_16x16x32_bf16 v[76:79], v[100:103], v[206:209], v[76:79]
	v_mfma_f32_16x16x32_bf16 v[72:75], v[148:151], v[206:209], v[72:75]
	v_mfma_f32_16x16x32_bf16 v[68:71], v[100:103], v[214:217], v[68:71]
	v_mfma_f32_16x16x32_bf16 v[64:67], v[148:151], v[214:217], v[64:67]
	s_setprio 0
	s_barrier
; #define PG8_STAGE(bufoff, gbase) do { _Pragma("unroll") for (int _i = 0; _i < 2; ++_i) \
;         __builtin_amdgcn_global_load_lds((const unsigned*)((const char*)(gbase) + voff[_i]), (LAS unsigned*)(lds + (bufoff) + ldsw + _i * 8192), 16, 0, 0); } while (0)
; #define PG8_LDA(dst, b, h) do { _Pragma("unroll") for (int m = 0; m < 4; ++m) _Pragma("unroll") for (int k = 0; k < 2; ++k) dst[m][k] = *(const LAS bf16x8*)(lds + PG8_SA(b, h) + aoff + m * 2048 + k * 1024); } while (0)
; #define PG8_LDB(dst, b, h) do { _Pragma("unroll") for (int n = 0; n < 2; ++n) _Pragma("unroll") for (int k = 0; k < 2; ++k) dst[n][k] = *(const LAS bf16x8*)(lds + PG8_SB(b, h) + boff + n * 2048 + k * 1024); } while (0)
; #define PG8_MMA(ai, bj, At, Bt) do { __builtin_amdgcn_s_setprio(1); _Pragma("unroll") for (int m = 0; m < 4; ++m) _Pragma("unroll") for (int n = 0; n < 2; ++n) _Pragma("unroll") for (int k = 0; k < 2; ++k) \
;         acc[ai][bj][m][n] = __builtin_amdgcn_mfma_f32_16x16x32_bf16(Bt[n][k], At[m][k], acc[ai][bj][m][n], 0, 0, 0); __builtin_amdgcn_s_setprio(0); } while (0)
; #define PG8_WAIT_V(n) asm volatile("s_waitcnt vmcnt(" #n ")" ::: "memory")
; #define PG8_WAIT_L(n) asm volatile("s_waitcnt lgkmcnt(" #n ")" ::: "memory")
; #define PG8_BAR __builtin_amdgcn_s_barrier()
; #define PG8_SCHED __builtin_amdgcn_sched_barrier(0)
; template <class Epi>
; DI void gemm_phase(LAS unsigned char* lds, const Gemm g, const StaticOrder& S, const Epi& E) {
;     ...
;             PG8_STAGE(PG8_SB(0, 1), b2 + hstep);
;             PG8_WAIT_V(6); PG8_BAR; PG8_MMA(1, 1, At, B1); PG8_BAR;
;             PG8_LDB(B0, 1, 0); PG8_SCHED; PG8_LDA(At, 1, 0); PG8_STAGE(PG8_SA(0, 1), a2 + hstep);
;             PG8_WAIT_L(8); PG8_BAR; PG8_WAIT_L(0); PG8_MMA(0, 0, At, B0); PG8_BAR; PG8_SCHED;
;             PG8_LDB(B1, 1, 1); PG8_STAGE(PG8_SB(1, 0), b3);
;             PG8_BAR; PG8_WAIT_L(0); PG8_MMA(0, 1, At, B1); PG8_BAR;
;             PG8_LDA(At, 1, 1); PG8_STAGE(PG8_SA(1, 0), a3);
	v_lshl_add_u64 v[96:97], s[16:17], 0, v[142:143]
	s_mov_b32 m0, s39
	s_nop 0
	global_load_lds_dwordx4 v[96:97], off
	v_lshl_add_u64 v[96:97], s[16:17], 0, v[140:141]
	s_add_i32 m0, s39, 0x2000
	s_nop 0
	global_load_lds_dwordx4 v[96:97], off
	s_waitcnt vmcnt(6)
	s_setprio 1
	s_barrier
	v_mfma_f32_16x16x32_bf16 v[28:31], v[226:229], v[152:155], v[28:31]
	v_mfma_f32_16x16x32_bf16 v[24:27], v[234:237], v[152:155], v[24:27]
	v_mfma_f32_16x16x32_bf16 v[20:23], v[226:229], v[190:193], v[20:23]
	v_mfma_f32_16x16x32_bf16 v[16:19], v[234:237], v[190:193], v[16:19]
	v_mfma_f32_16x16x32_bf16 v[12:15], v[226:229], v[202:205], v[12:15]
	v_mfma_f32_16x16x32_bf16 v[8:11], v[234:237], v[202:205], v[8:11]
	v_mfma_f32_16x16x32_bf16 v[4:7], v[226:229], v[210:213], v[4:7]
	v_mfma_f32_16x16x32_bf16 v[0:3], v[234:237], v[210:213], v[0:3]
	v_mfma_f32_16x16x32_bf16 v[28:31], v[230:233], v[186:189], v[28:31]
	s_add_i32 s39, 0, 0x18000
	v_mfma_f32_16x16x32_bf16 v[24:27], v[238:241], v[186:189], v[24:27]
	v_add_u32_e32 v148, s39, v199
	v_mfma_f32_16x16x32_bf16 v[20:23], v[230:233], v[194:197], v[20:23]
	v_mfma_f32_16x16x32_bf16 v[16:19], v[238:241], v[194:197], v[16:19]
	v_mfma_f32_16x16x32_bf16 v[12:15], v[230:233], v[206:209], v[12:15]
	v_mfma_f32_16x16x32_bf16 v[8:11], v[238:241], v[206:209], v[8:11]
	v_mfma_f32_16x16x32_bf16 v[4:7], v[230:233], v[214:217], v[4:7]
	v_mfma_f32_16x16x32_bf16 v[0:3], v[238:241], v[214:217], v[0:3]
	s_setprio 0
	s_barrier
	ds_read_b128 v[96:99], v148
	ds_read_b128 v[100:103], v148 offset:1024
	ds_read_b128 v[136:139], v148 offset:2048
	ds_read_b128 v[148:151], v148 offset:3072
	s_add_u32 s16, s22, 0x160000
	s_addc_u32 s17, s23, 0
	s_mov_b32 m0, s30
	v_lshl_add_u64 v[226:227], s[16:17], 0, v[142:143]
	ds_read_b128 v[152:155], v201 offset:32768
	ds_read_b128 v[186:189], v201 offset:33792
	ds_read_b128 v[190:193], v201 offset:34816
	ds_read_b128 v[194:197], v201 offset:35840
	ds_read_b128 v[202:205], v201 offset:36864
	ds_read_b128 v[206:209], v201 offset:37888
	ds_read_b128 v[210:213], v201 offset:38912
	ds_read_b128 v[214:217], v201 offset:39936
	global_load_lds_dwordx4 v[226:227], off
	v_lshl_add_u64 v[226:227], s[16:17], 0, v[140:141]
	s_mov_b32 m0, s31
	s_nop 0
	global_load_lds_dwordx4 v[226:227], off
	s_waitcnt lgkmcnt(8)
	s_setprio 1
	s_barrier
	s_waitcnt lgkmcnt(0)
	v_mfma_f32_16x16x32_bf16 v[132:135], v[96:99], v[152:155], v[132:135]
	v_mfma_f32_16x16x32_bf16 v[128:131], v[136:139], v[152:155], v[128:131]
	s_add_i32 s22, 0, 0x1c000
	v_mfma_f32_16x16x32_bf16 v[124:127], v[96:99], v[190:193], v[124:127]
	s_add_i32 s16, s39, s27
	v_mfma_f32_16x16x32_bf16 v[120:123], v[136:139], v[190:193], v[120:123]
	v_add_u32_e32 v158, s22, v199
	v_mfma_f32_16x16x32_bf16 v[116:119], v[96:99], v[202:205], v[116:119]
	v_lshl_add_u64 v[218:219], v[218:219], 0, s[94:95]
	v_mfma_f32_16x16x32_bf16 v[112:115], v[136:139], v[202:205], v[112:115]
	s_mov_b32 m0, s16
	v_mfma_f32_16x16x32_bf16 v[108:111], v[96:99], v[210:213], v[108:111]
	v_mfma_f32_16x16x32_bf16 v[104:107], v[136:139], v[210:213], v[104:107]
	v_mfma_f32_16x16x32_bf16 v[132:135], v[100:103], v[186:189], v[132:135]
	v_mfma_f32_16x16x32_bf16 v[128:131], v[148:151], v[186:189], v[128:131]
	v_mfma_f32_16x16x32_bf16 v[124:127], v[100:103], v[194:197], v[124:127]
	v_mfma_f32_16x16x32_bf16 v[120:123], v[148:151], v[194:197], v[120:123]
	v_mfma_f32_16x16x32_bf16 v[116:119], v[100:103], v[206:209], v[116:119]
	v_mfma_f32_16x16x32_bf16 v[112:115], v[148:151], v[206:209], v[112:115]
	v_mfma_f32_16x16x32_bf16 v[108:111], v[100:103], v[214:217], v[108:111]
	v_mfma_f32_16x16x32_bf16 v[104:107], v[148:151], v[214:217], v[104:107]
	s_setprio 0
	s_barrier
	ds_read_b128 v[226:229], v158
	ds_read_b128 v[230:233], v158 offset:1024
	ds_read_b128 v[234:237], v158 offset:2048
	ds_read_b128 v[238:241], v158 offset:3072
	global_load_lds_dwordx4 v[218:219], off
	v_lshl_add_u64 v[218:219], v[220:221], 0, s[94:95]
	s_add_i32 m0, s16, 0x2000
	s_nop 0
	global_load_lds_dwordx4 v[218:219], off
	s_waitcnt lgkmcnt(0)
	s_setprio 1
	s_barrier
	v_mfma_f32_16x16x32_bf16 v[60:63], v[226:229], v[152:155], v[60:63]
	v_mfma_f32_16x16x32_bf16 v[56:59], v[234:237], v[152:155], v[56:59]
	v_mfma_f32_16x16x32_bf16 v[52:55], v[226:229], v[190:193], v[52:55]
	v_mfma_f32_16x16x32_bf16 v[48:51], v[234:237], v[190:193], v[48:51]
	v_mfma_f32_16x16x32_bf16 v[44:47], v[226:229], v[202:205], v[44:47]
	v_mfma_f32_16x16x32_bf16 v[40:43], v[234:237], v[202:205], v[40:43]
	v_mfma_f32_16x16x32_bf16 v[36:39], v[226:229], v[210:213], v[36:39]
	v_mfma_f32_16x16x32_bf16 v[32:35], v[234:237], v[210:213], v[32:35]
	v_mfma_f32_16x16x32_bf16 v[60:63], v[230:233], v[186:189], v[60:63]
	s_mov_b32 m0, s34
	v_mfma_f32_16x16x32_bf16 v[56:59], v[238:241], v[186:189], v[56:59]
	v_lshl_add_u64 v[218:219], v[242:243], 0, s[94:95]
	v_mfma_f32_16x16x32_bf16 v[52:55], v[230:233], v[194:197], v[52:55]
	v_mfma_f32_16x16x32_bf16 v[48:51], v[238:241], v[194:197], v[48:51]
	v_mfma_f32_16x16x32_bf16 v[44:47], v[230:233], v[206:209], v[44:47]
	v_mfma_f32_16x16x32_bf16 v[40:43], v[238:241], v[206:209], v[40:43]
	v_mfma_f32_16x16x32_bf16 v[36:39], v[230:233], v[214:217], v[36:39]
	v_mfma_f32_16x16x32_bf16 v[32:35], v[238:241], v[214:217], v[32:35]
	s_setprio 0
	s_barrier
	ds_read_b128 v[152:155], v201 offset:49152
	ds_read_b128 v[186:189], v201 offset:50176
	ds_read_b128 v[190:193], v201 offset:51200
	ds_read_b128 v[194:197], v201 offset:52224
	ds_read_b128 v[202:205], v201 offset:53248
	ds_read_b128 v[206:209], v201 offset:54272
	ds_read_b128 v[210:213], v201 offset:55296
	ds_read_b128 v[214:217], v201 offset:56320
	global_load_lds_dwordx4 v[218:219], off
	v_lshl_add_u64 v[218:219], v[244:245], 0, s[94:95]
	s_mov_b32 m0, s35
	s_nop 0
	global_load_lds_dwordx4 v[218:219], off
	s_waitcnt lgkmcnt(0)
	s_setprio 1
	s_barrier
; #define PG8_STAGE(bufoff, gbase) do { _Pragma("unroll") for (int _i = 0; _i < 2; ++_i) \
;         __builtin_amdgcn_global_load_lds((const unsigned*)((const char*)(gbase) + voff[_i]), (LAS unsigned*)(lds + (bufoff) + ldsw + _i * 8192), 16, 0, 0); } while (0)
; #define PG8_MMA(ai, bj, At, Bt) do { __builtin_amdgcn_s_setprio(1); _Pragma("unroll") for (int m = 0; m < 4; ++m) _Pragma("unroll") for (int n = 0; n < 2; ++n) _Pragma("unroll") for (int k = 0; k < 2; ++k) \
;         acc[ai][bj][m][n] = __builtin_amdgcn_mfma_f32_16x16x32_bf16(Bt[n][k], At[m][k], acc[ai][bj][m][n], 0, 0, 0); __builtin_amdgcn_s_setprio(0); } while (0)
; template <class Epi>
; DI void gemm_phase(LAS unsigned char* lds, const Gemm g, const StaticOrder& S, const Epi& E) {
;     ...
;             PG8_BAR; PG8_WAIT_L(0); PG8_MMA(1, 0, At, B0); PG8_BAR; PG8_SCHED;
;             PG8_STAGE(PG8_SB(1, 1), b3 + hstep);
;             PG8_WAIT_V(6); PG8_BAR; PG8_MMA(1, 1, At, B1); PG8_BAR;
;     template <bool LN, int BJ, int LO, int HI> DI void batch(const f32x4 (&acc)[2][2][4][2], unsigned row0, unsigned col0, const f32x4 (&gv)[2], const f32x4 (&bv)[2]) const {
;         f32x4 r[HI - LO]; float mean[(HI - LO) / 2], rstd[(HI - LO) / 2];
; #pragma unroll
;         for (int i = LO; i < HI; ++i) { const int ai = i >> 3, m = (i >> 1) & 3, n = i & 1; const unsigned row = row0 + ai * HALF + m * 16;
;             if (n == 0) { mean[(i - LO) >> 1] = 0.f; rstd[(i - LO) >> 1] = 1.f;
;                 if (LN) { const float2 st = *(const float2*)(stats + row * 2u); mean[(i - LO) >> 1] = st.x; rstd[(i - LO) >> 1] = st.y; } }
;             r[i - LO] = *(const f32x4*)(src + (row * (unsigned)DM + col0 + BJ * HALF + n * 16)); }
; #pragma unroll
;         for (int i = LO; i < HI; ++i) { const int ai = i >> 3, m = (i >> 1) & 3, n = i & 1; const unsigned row = row0 + ai * HALF + m * 16;
;             *(f32x4*)(Y + (row * (unsigned)DM + col0 + BJ * HALF + n * 16)) = acc[ai][BJ][m][n] + ((r[i - LO] - mean[(i - LO) >> 1]) * rstd[(i - LO) >> 1]) * gv[n] + bv[n]; }
;         __builtin_amdgcn_sched_barrier(0);
;     }
;     template <bool LN, int BJ> DI void load_gb(unsigned col0, f32x4 (&gv)[2], f32x4 (&bv)[2]) const {
; #pragma unroll
;         for (int n = 0; n < 2; ++n) {
;             if (LN) { gv[n] = *(const f32x4*)(gam + col0 + BJ * HALF + n * 16) * ALPHA; bv[n] = *(const f32x4*)(bet + col0 + BJ * HALF + n * 16) * ALPHA; }
	v_mfma_f32_16x16x32_bf16 v[92:95], v[96:99], v[152:155], v[92:95]
	v_mfma_f32_16x16x32_bf16 v[88:91], v[136:139], v[152:155], v[88:91]
	s_add_u32 s16, s20, 0x160080
	v_mfma_f32_16x16x32_bf16 v[84:87], v[96:99], v[190:193], v[84:87]
	s_addc_u32 s17, s21, 0
	v_mfma_f32_16x16x32_bf16 v[80:83], v[136:139], v[190:193], v[80:83]
	s_add_i32 s20, s22, s27
	v_mfma_f32_16x16x32_bf16 v[76:79], v[96:99], v[202:205], v[76:79]
	v_mfma_f32_16x16x32_bf16 v[72:75], v[136:139], v[202:205], v[72:75]
	v_mfma_f32_16x16x32_bf16 v[68:71], v[96:99], v[210:213], v[68:71]
	v_mfma_f32_16x16x32_bf16 v[64:67], v[136:139], v[210:213], v[64:67]
	v_mfma_f32_16x16x32_bf16 v[92:95], v[100:103], v[186:189], v[92:95]
	v_mfma_f32_16x16x32_bf16 v[88:91], v[148:151], v[186:189], v[88:91]
	v_mfma_f32_16x16x32_bf16 v[84:87], v[100:103], v[194:197], v[84:87]
	v_mfma_f32_16x16x32_bf16 v[80:83], v[148:151], v[194:197], v[80:83]
	v_mfma_f32_16x16x32_bf16 v[76:79], v[100:103], v[206:209], v[76:79]
	v_mfma_f32_16x16x32_bf16 v[72:75], v[148:151], v[206:209], v[72:75]
	v_mfma_f32_16x16x32_bf16 v[68:71], v[100:103], v[214:217], v[68:71]
	v_mfma_f32_16x16x32_bf16 v[64:67], v[148:151], v[214:217], v[64:67]
	s_setprio 0
	s_barrier
	v_lshl_add_u64 v[96:97], s[16:17], 0, v[142:143]
	s_mov_b32 m0, s20
	s_nop 0
	global_load_lds_dwordx4 v[96:97], off
	v_lshl_add_u64 v[96:97], s[16:17], 0, v[140:141]
	s_add_i32 m0, s20, 0x2000
	s_nop 0
	global_load_lds_dwordx4 v[96:97], off
	s_waitcnt vmcnt(6)
	s_setprio 1
	s_barrier
	v_mfma_f32_16x16x32_bf16 v[28:31], v[226:229], v[152:155], v[28:31]
	v_mfma_f32_16x16x32_bf16 v[24:27], v[234:237], v[152:155], v[24:27]
	v_mfma_f32_16x16x32_bf16 v[20:23], v[226:229], v[190:193], v[20:23]
	v_mfma_f32_16x16x32_bf16 v[16:19], v[234:237], v[190:193], v[16:19]
	v_mfma_f32_16x16x32_bf16 v[12:15], v[226:229], v[202:205], v[12:15]
	v_mfma_f32_16x16x32_bf16 v[8:11], v[234:237], v[202:205], v[8:11]
	v_mfma_f32_16x16x32_bf16 v[4:7], v[226:229], v[210:213], v[4:7]
	v_mfma_f32_16x16x32_bf16 v[0:3], v[234:237], v[210:213], v[0:3]
	v_mfma_f32_16x16x32_bf16 v[28:31], v[230:233], v[186:189], v[28:31]
	s_add_i32 s33, s33, 2
	v_mfma_f32_16x16x32_bf16 v[24:27], v[238:241], v[186:189], v[24:27]
	s_add_u32 s4, s4, 0x100
	v_mfma_f32_16x16x32_bf16 v[20:23], v[230:233], v[194:197], v[20:23]
	s_addc_u32 s5, s5, 0
	v_mfma_f32_16x16x32_bf16 v[16:19], v[238:241], v[194:197], v[16:19]
	s_cmpk_gt_u32 s33, 0x55
	v_mfma_f32_16x16x32_bf16 v[12:15], v[230:233], v[206:209], v[12:15]
	s_mov_b64 s[16:17], s[18:19]
	v_mfma_f32_16x16x32_bf16 v[8:11], v[238:241], v[206:209], v[8:11]
	v_mfma_f32_16x16x32_bf16 v[4:7], v[230:233], v[214:217], v[4:7]
	v_mfma_f32_16x16x32_bf16 v[0:3], v[238:241], v[214:217], v[0:3]
	s_setprio 0
	s_barrier
	s_cbranch_scc0 .LBB0_134
	v_lshl_or_b32 v158, s2, 8, v200
	v_lshlrev_b64 v[100:101], 2, v[158:159]
	v_lshl_add_u64 v[150:151], s[12:13], 0, v[100:101]
	global_load_dwordx4 v[96:99], v[150:151], off
	v_lshl_add_u64 v[152:153], s[14:15], 0, v[100:101]
	v_lshl_add_u32 v203, s3, 8, v198
	v_lshlrev_b32_e32 v202, 11, v203
	v_add_u32_e32 v148, v202, v158
	v_mov_b32_e32 v149, v159
	v_lshlrev_b32_e32 v136, 1, v203
	v_mov_b32_e32 v137, v159
	v_lshlrev_b64 v[220:221], 2, v[148:149]
	v_lshl_add_u64 v[154:155], v[136:137], 2, s[96:97]
	v_lshl_add_u64 v[136:137], s[90:91], 0, v[220:221]
	v_or_b32_e32 v204, 16, v158
	v_or_b32_e32 v138, 16, v203
	v_lshlrev_b32_e32 v149, 11, v138
	s_waitcnt vmcnt(0)
	v_pk_mul_f32 v[192:193], v[98:99], s[78:79] op_sel_hi:[1,0]
	v_pk_mul_f32 v[194:195], v[96:97], s[78:79] op_sel_hi:[1,0]
	global_load_dwordx4 v[100:103], v[152:153], off
	global_load_dwordx4 v[96:99], v[150:151], off offset:64
	global_load_dwordx2 v[218:219], v[154:155], off
	global_load_dwordx4 v[206:209], v[136:137], off
	v_add_u32_e32 v136, v202, v204
	v_mov_b32_e32 v137, v159
	v_lshl_add_u64 v[136:137], v[136:137], 2, s[90:91]
	global_load_dwordx4 v[210:213], v[136:137], off
	v_lshlrev_b32_e32 v136, 1, v138
	v_mov_b32_e32 v137, v159
	v_lshl_add_u64 v[186:187], v[136:137], 2, s[96:97]
	v_add_u32_e32 v136, v149, v158
	v_lshl_add_u64 v[136:137], v[136:137], 2, s[90:91]
	global_load_dwordx2 v[196:197], v[186:187], off
	global_load_dwordx4 v[214:217], v[136:137], off
	v_add_u32_e32 v136, v149, v204
	v_mov_b32_e32 v137, v159
	v_lshl_add_u64 v[136:137], v[136:137], 2, s[90:91]
	global_load_dwordx4 v[136:139], v[136:137], off
	s_waitcnt vmcnt(0)
	v_pk_mul_f32 v[188:189], v[98:99], s[78:79] op_sel_hi:[1,0]
	v_pk_mul_f32 v[190:191], v[96:97], s[78:79] op_sel_hi:[1,0]
	global_load_dwordx4 v[96:99], v[152:153], off offset:64
	v_sub_f32_e32 v207, v207, v218
	v_sub_f32_e32 v206, v206, v218
	v_sub_f32_e32 v209, v209, v218
	v_sub_f32_e32 v208, v208, v218
	v_pk_mul_f32 v[208:209], v[218:219], v[208:209] op_sel:[1,0]
	v_pk_mul_f32 v[206:207], v[218:219], v[206:207] op_sel:[1,0]
	v_pk_fma_f32 v[134:135], v[192:193], v[208:209], v[134:135]
	v_pk_fma_f32 v[132:133], v[194:195], v[206:207], v[132:133]
	v_pk_fma_f32 v[134:135], v[102:103], s[78:79], v[134:135] op_sel_hi:[1,0,1]
	v_pk_fma_f32 v[132:133], v[100:101], s[78:79], v[132:133] op_sel_hi:[1,0,1]
	v_lshl_add_u64 v[206:207], s[88:89], 0, v[220:221]
	global_store_dwordx4 v[206:207], v[132:135], off
	s_nop 1
	v_sub_f32_e32 v133, v211, v218
	v_sub_f32_e32 v132, v210, v218
	v_sub_f32_e32 v135, v213, v218
	v_sub_f32_e32 v134, v212, v218
	v_pk_mul_f32 v[134:135], v[218:219], v[134:135] op_sel:[1,0]
	v_pk_mul_f32 v[132:133], v[218:219], v[132:133] op_sel:[1,0]
	v_pk_fma_f32 v[130:131], v[188:189], v[134:135], v[130:131]
	v_pk_fma_f32 v[128:129], v[190:191], v[132:133], v[128:129]
	v_or_b32_e32 v132, 16, v148
	v_mov_b32_e32 v133, v159
	v_lshl_add_u64 v[132:133], v[132:133], 2, s[88:89]
	s_waitcnt vmcnt(0)
;     template <bool LN, int BJ, int LO, int HI> DI void batch(const f32x4 (&acc)[2][2][4][2], unsigned row0, unsigned col0, const f32x4 (&gv)[2], const f32x4 (&bv)[2]) const {
;         f32x4 r[HI - LO]; float mean[(HI - LO) / 2], rstd[(HI - LO) / 2];
; #pragma unroll
;         for (int i = LO; i < HI; ++i) { const int ai = i >> 3, m = (i >> 1) & 3, n = i & 1; const unsigned row = row0 + ai * HALF + m * 16;
;             if (n == 0) { mean[(i - LO) >> 1] = 0.f; rstd[(i - LO) >> 1] = 1.f;
;                 if (LN) { const float2 st = *(const float2*)(stats + row * 2u); mean[(i - LO) >> 1] = st.x; rstd[(i - LO) >> 1] = st.y; } }
;             r[i - LO] = *(const f32x4*)(src + (row * (unsigned)DM + col0 + BJ * HALF + n * 16)); }
; #pragma unroll
;         for (int i = LO; i < HI; ++i) { const int ai = i >> 3, m = (i >> 1) & 3, n = i & 1; const unsigned row = row0 + ai * HALF + m * 16;
;             *(f32x4*)(Y + (row * (unsigned)DM + col0 + BJ * HALF + n * 16)) = acc[ai][BJ][m][n] + ((r[i - LO] - mean[(i - LO) >> 1]) * rstd[(i - LO) >> 1]) * gv[n] + bv[n]; }
	v_pk_fma_f32 v[130:131], v[98:99], s[78:79], v[130:131] op_sel_hi:[1,0,1]
	v_pk_fma_f32 v[128:129], v[96:97], s[78:79], v[128:129] op_sel_hi:[1,0,1]
	global_store_dwordx4 v[132:133], v[128:131], off
	s_nop 1
	v_sub_f32_e32 v129, v215, v196
	v_sub_f32_e32 v128, v214, v196
	v_sub_f32_e32 v131, v217, v196
	v_sub_f32_e32 v130, v216, v196
	v_pk_mul_f32 v[130:131], v[196:197], v[130:131] op_sel:[1,0]
	v_pk_mul_f32 v[128:129], v[196:197], v[128:129] op_sel:[1,0]
	v_pk_fma_f32 v[126:127], v[192:193], v[130:131], v[126:127]
	v_pk_fma_f32 v[124:125], v[194:195], v[128:129], v[124:125]
	v_add_u32_e32 v128, 0x8000, v148
	v_mov_b32_e32 v129, v159
	v_pk_fma_f32 v[126:127], v[102:103], s[78:79], v[126:127] op_sel_hi:[1,0,1]
	v_pk_fma_f32 v[124:125], v[100:101], s[78:79], v[124:125] op_sel_hi:[1,0,1]
	v_lshl_add_u64 v[128:129], v[128:129], 2, s[88:89]
	global_store_dwordx4 v[128:129], v[124:127], off
	s_nop 1
	v_sub_f32_e32 v125, v137, v196
	v_sub_f32_e32 v124, v136, v196
	v_sub_f32_e32 v127, v139, v196
	v_sub_f32_e32 v126, v138, v196
	v_pk_mul_f32 v[126:127], v[196:197], v[126:127] op_sel:[1,0]
	v_pk_mul_f32 v[124:125], v[196:197], v[124:125] op_sel:[1,0]
	v_pk_fma_f32 v[122:123], v[188:189], v[126:127], v[122:123]
	v_pk_fma_f32 v[120:121], v[190:191], v[124:125], v[120:121]
	v_add_u32_e32 v124, 0x8010, v148
	v_mov_b32_e32 v125, v159
	v_pk_fma_f32 v[122:123], v[98:99], s[78:79], v[122:123] op_sel_hi:[1,0,1]
	v_pk_fma_f32 v[120:121], v[96:97], s[78:79], v[120:121] op_sel_hi:[1,0,1]
	v_lshl_add_u64 v[124:125], v[124:125], 2, s[88:89]
	global_store_dwordx4 v[124:125], v[120:123], off
	s_nop 1
	v_or_b32_e32 v122, 32, v203
	v_lshlrev_b32_e32 v124, 11, v122
	v_lshlrev_b32_e32 v120, 1, v122
	v_mov_b32_e32 v121, v159
	v_add_u32_e32 v122, v124, v158
	v_mov_b32_e32 v123, v159
	v_lshl_add_u64 v[120:121], v[120:121], 2, s[96:97]
	v_lshl_add_u64 v[122:123], v[122:123], 2, s[90:91]
	global_load_dwordx2 v[138:139], v[120:121], off
	global_load_dwordx4 v[126:129], v[122:123], off
	v_add_u32_e32 v122, v124, v204
	v_mov_b32_e32 v123, v159
	v_lshl_add_u64 v[122:123], v[122:123], 2, s[90:91]
	global_load_dwordx4 v[130:133], v[122:123], off
	v_or_b32_e32 v125, 48, v203
	v_lshlrev_b32_e32 v122, 1, v125
	v_lshlrev_b32_e32 v125, 11, v125
	v_mov_b32_e32 v123, v159
	v_add_u32_e32 v134, v125, v158
	v_mov_b32_e32 v135, v159
	v_lshl_add_u64 v[122:123], v[122:123], 2, s[96:97]
	v_lshl_add_u64 v[134:135], v[134:135], 2, s[90:91]
	global_load_dwordx2 v[196:197], v[122:123], off
	v_add_u32_e32 v206, v125, v204
	global_load_dwordx4 v[134:137], v[134:135], off
	v_mov_b32_e32 v207, v159
	v_lshl_add_u64 v[206:207], v[206:207], 2, s[90:91]
	global_load_dwordx4 v[206:209], v[206:207], off
	s_waitcnt vmcnt(0)
	v_sub_f32_e32 v127, v127, v138
	v_sub_f32_e32 v126, v126, v138
	v_sub_f32_e32 v129, v129, v138
	v_sub_f32_e32 v128, v128, v138
	v_pk_mul_f32 v[128:129], v[138:139], v[128:129] op_sel:[1,0]
	v_pk_mul_f32 v[126:127], v[138:139], v[126:127] op_sel:[1,0]
	v_pk_fma_f32 v[118:119], v[192:193], v[128:129], v[118:119]
	v_pk_fma_f32 v[116:117], v[194:195], v[126:127], v[116:117]
	v_add_u32_e32 v126, 0x10000, v148
	v_mov_b32_e32 v127, v159
	v_pk_fma_f32 v[118:119], v[102:103], s[78:79], v[118:119] op_sel_hi:[1,0,1]
	v_pk_fma_f32 v[116:117], v[100:101], s[78:79], v[116:117] op_sel_hi:[1,0,1]
	v_lshl_add_u64 v[126:127], v[126:127], 2, s[88:89]
	global_store_dwordx4 v[126:127], v[116:119], off
	s_nop 1
	v_sub_f32_e32 v117, v131, v138
	v_sub_f32_e32 v116, v130, v138
	v_sub_f32_e32 v119, v133, v138
	v_sub_f32_e32 v118, v132, v138
	v_pk_mul_f32 v[118:119], v[138:139], v[118:119] op_sel:[1,0]
	v_pk_mul_f32 v[116:117], v[138:139], v[116:117] op_sel:[1,0]
	v_pk_fma_f32 v[114:115], v[188:189], v[118:119], v[114:115]
	v_pk_fma_f32 v[112:113], v[190:191], v[116:117], v[112:113]
	v_add_u32_e32 v116, 0x10010, v148
	v_mov_b32_e32 v117, v159
	v_pk_fma_f32 v[114:115], v[98:99], s[78:79], v[114:115] op_sel_hi:[1,0,1]
	v_pk_fma_f32 v[112:113], v[96:97], s[78:79], v[112:113] op_sel_hi:[1,0,1]
	v_lshl_add_u64 v[116:117], v[116:117], 2, s[88:89]
	global_store_dwordx4 v[116:117], v[112:115], off
	s_nop 1
	v_sub_f32_e32 v113, v135, v196
	v_sub_f32_e32 v112, v134, v196
	v_sub_f32_e32 v115, v137, v196
	v_sub_f32_e32 v114, v136, v196
	v_pk_mul_f32 v[114:115], v[196:197], v[114:115] op_sel:[1,0]
	v_pk_mul_f32 v[112:113], v[196:197], v[112:113] op_sel:[1,0]
	v_pk_fma_f32 v[110:111], v[192:193], v[114:115], v[110:111]
	v_pk_fma_f32 v[108:109], v[194:195], v[112:113], v[108:109]
	v_add_u32_e32 v112, 0x18000, v148
	v_mov_b32_e32 v113, v159
	v_pk_fma_f32 v[110:111], v[102:103], s[78:79], v[110:111] op_sel_hi:[1,0,1]
	v_pk_fma_f32 v[108:109], v[100:101], s[78:79], v[108:109] op_sel_hi:[1,0,1]
	v_lshl_add_u64 v[112:113], v[112:113], 2, s[88:89]
	global_store_dwordx4 v[112:113], v[108:111], off
	s_nop 1
	v_sub_f32_e32 v109, v207, v196
	v_sub_f32_e32 v108, v206, v196
	v_sub_f32_e32 v111, v209, v196
	v_sub_f32_e32 v110, v208, v196
	v_pk_mul_f32 v[110:111], v[196:197], v[110:111] op_sel:[1,0]
	v_pk_mul_f32 v[108:109], v[196:197], v[108:109] op_sel:[1,0]
	v_pk_fma_f32 v[106:107], v[188:189], v[110:111], v[106:107]
	v_pk_fma_f32 v[104:105], v[190:191], v[108:109], v[104:105]
	v_add_u32_e32 v108, 0x18010, v148
	v_mov_b32_e32 v109, v159
	v_pk_fma_f32 v[106:107], v[98:99], s[78:79], v[106:107] op_sel_hi:[1,0,1]
	v_pk_fma_f32 v[104:105], v[96:97], s[78:79], v[104:105] op_sel_hi:[1,0,1]
	v_lshl_add_u64 v[108:109], v[108:109], 2, s[88:89]
	global_store_dwordx4 v[108:109], v[104:107], off
	s_nop 1
	v_add_u32_e32 v106, 0x80, v203
	v_lshlrev_b32_e32 v114, 11, v106
	v_lshlrev_b32_e32 v104, 1, v106
	v_mov_b32_e32 v105, v159
	v_add_u32_e32 v106, v114, v158
	v_mov_b32_e32 v107, v159
	v_lshl_add_u64 v[104:105], v[104:105], 2, s[96:97]
	v_lshl_add_u64 v[106:107], v[106:107], 2, s[90:91]
	global_load_dwordx2 v[112:113], v[104:105], off
	global_load_dwordx4 v[108:111], v[106:107], off
	v_add_u32_e32 v106, v114, v204
	v_mov_b32_e32 v107, v159
	v_lshl_add_u64 v[106:107], v[106:107], 2, s[90:91]
	global_load_dwordx4 v[116:119], v[106:107], off
	v_add_u32_e32 v115, 0x90, v203
	v_lshlrev_b32_e32 v106, 1, v115
	v_lshlrev_b32_e32 v115, 11, v115
	v_mov_b32_e32 v107, v159
	v_add_u32_e32 v126, v115, v158
	v_mov_b32_e32 v127, v159
	v_lshl_add_u64 v[106:107], v[106:107], 2, s[96:97]
	v_lshl_add_u64 v[126:127], v[126:127], 2, s[90:91]
	global_load_dwordx2 v[134:135], v[106:107], off
	v_add_u32_e32 v130, v115, v204
	global_load_dwordx4 v[126:129], v[126:127], off
	v_mov_b32_e32 v131, v159
	v_lshl_add_u64 v[130:131], v[130:131], 2, s[90:91]
	global_load_dwordx4 v[130:133], v[130:131], off
	s_waitcnt vmcnt(0)
;     template <bool LN, int BJ, int LO, int HI> DI void batch(const f32x4 (&acc)[2][2][4][2], unsigned row0, unsigned col0, const f32x4 (&gv)[2], const f32x4 (&bv)[2]) const {
;         f32x4 r[HI - LO]; float mean[(HI - LO) / 2], rstd[(HI - LO) / 2];
; #pragma unroll
;         for (int i = LO; i < HI; ++i) { const int ai = i >> 3, m = (i >> 1) & 3, n = i & 1; const unsigned row = row0 + ai * HALF + m * 16;
;             if (n == 0) { mean[(i - LO) >> 1] = 0.f; rstd[(i - LO) >> 1] = 1.f;
;                 if (LN) { const float2 st = *(const float2*)(stats + row * 2u); mean[(i - LO) >> 1] = st.x; rstd[(i - LO) >> 1] = st.y; } }
;             r[i - LO] = *(const f32x4*)(src + (row * (unsigned)DM + col0 + BJ * HALF + n * 16)); }
; #pragma unroll
;         for (int i = LO; i < HI; ++i) { const int ai = i >> 3, m = (i >> 1) & 3, n = i & 1; const unsigned row = row0 + ai * HALF + m * 16;
;             *(f32x4*)(Y + (row * (unsigned)DM + col0 + BJ * HALF + n * 16)) = acc[ai][BJ][m][n] + ((r[i - LO] - mean[(i - LO) >> 1]) * rstd[(i - LO) >> 1]) * gv[n] + bv[n]; }
	v_sub_f32_e32 v109, v109, v112
	v_sub_f32_e32 v108, v108, v112
	v_sub_f32_e32 v111, v111, v112
	v_sub_f32_e32 v110, v110, v112
	v_pk_mul_f32 v[110:111], v[112:113], v[110:111] op_sel:[1,0]
	v_pk_mul_f32 v[108:109], v[112:113], v[108:109] op_sel:[1,0]
	v_pk_fma_f32 v[94:95], v[192:193], v[110:111], v[94:95]
	v_pk_fma_f32 v[92:93], v[194:195], v[108:109], v[92:93]
	v_add_u32_e32 v108, 0x40000, v148
	v_mov_b32_e32 v109, v159
	v_pk_fma_f32 v[94:95], v[102:103], s[78:79], v[94:95] op_sel_hi:[1,0,1]
	v_pk_fma_f32 v[92:93], v[100:101], s[78:79], v[92:93] op_sel_hi:[1,0,1]
	v_lshl_add_u64 v[108:109], v[108:109], 2, s[88:89]
	global_store_dwordx4 v[108:109], v[92:95], off
	s_nop 1
	v_sub_f32_e32 v93, v117, v112
	v_sub_f32_e32 v92, v116, v112
	v_sub_f32_e32 v95, v119, v112
	v_sub_f32_e32 v94, v118, v112
	v_pk_mul_f32 v[94:95], v[112:113], v[94:95] op_sel:[1,0]
	v_pk_mul_f32 v[92:93], v[112:113], v[92:93] op_sel:[1,0]
	v_pk_fma_f32 v[90:91], v[188:189], v[94:95], v[90:91]
	v_pk_fma_f32 v[88:89], v[190:191], v[92:93], v[88:89]
	v_add_u32_e32 v92, 0x40010, v148
	v_mov_b32_e32 v93, v159
	v_pk_fma_f32 v[90:91], v[98:99], s[78:79], v[90:91] op_sel_hi:[1,0,1]
	v_pk_fma_f32 v[88:89], v[96:97], s[78:79], v[88:89] op_sel_hi:[1,0,1]
	v_lshl_add_u64 v[92:93], v[92:93], 2, s[88:89]
	global_store_dwordx4 v[92:93], v[88:91], off
	s_nop 1
	v_sub_f32_e32 v89, v127, v134
	v_sub_f32_e32 v88, v126, v134
	v_sub_f32_e32 v91, v129, v134
	v_sub_f32_e32 v90, v128, v134
	v_pk_mul_f32 v[90:91], v[134:135], v[90:91] op_sel:[1,0]
	v_pk_mul_f32 v[88:89], v[134:135], v[88:89] op_sel:[1,0]
	v_pk_fma_f32 v[86:87], v[192:193], v[90:91], v[86:87]
	v_pk_fma_f32 v[84:85], v[194:195], v[88:89], v[84:85]
	v_add_u32_e32 v88, 0x48000, v148
	v_mov_b32_e32 v89, v159
	v_pk_fma_f32 v[86:87], v[102:103], s[78:79], v[86:87] op_sel_hi:[1,0,1]
	v_pk_fma_f32 v[84:85], v[100:101], s[78:79], v[84:85] op_sel_hi:[1,0,1]
	v_lshl_add_u64 v[88:89], v[88:89], 2, s[88:89]
	global_store_dwordx4 v[88:89], v[84:87], off
	s_nop 1
	v_sub_f32_e32 v85, v131, v134
	v_sub_f32_e32 v84, v130, v134
	v_sub_f32_e32 v87, v133, v134
	v_sub_f32_e32 v86, v132, v134
	v_pk_mul_f32 v[86:87], v[134:135], v[86:87] op_sel:[1,0]
	v_pk_mul_f32 v[84:85], v[134:135], v[84:85] op_sel:[1,0]
	v_pk_fma_f32 v[82:83], v[188:189], v[86:87], v[82:83]
	v_pk_fma_f32 v[80:81], v[190:191], v[84:85], v[80:81]
	v_add_u32_e32 v84, 0x48010, v148
	v_mov_b32_e32 v85, v159
	v_pk_fma_f32 v[82:83], v[98:99], s[78:79], v[82:83] op_sel_hi:[1,0,1]
	v_pk_fma_f32 v[80:81], v[96:97], s[78:79], v[80:81] op_sel_hi:[1,0,1]
	v_lshl_add_u64 v[84:85], v[84:85], 2, s[88:89]
	global_store_dwordx4 v[84:85], v[80:83], off
	s_nop 1
	v_add_u32_e32 v82, 0xa0, v203
	v_lshlrev_b32_e32 v80, 1, v82
	v_mov_b32_e32 v81, v159
	v_lshlrev_b32_e32 v116, 11, v82
	v_lshl_add_u64 v[108:109], v[80:81], 2, s[96:97]
	v_add_u32_e32 v80, v116, v158
	v_lshl_add_u64 v[80:81], v[80:81], 2, s[90:91]
	global_load_dwordx2 v[112:113], v[108:109], off
	v_add_u32_e32 v84, v116, v204
	global_load_dwordx4 v[80:83], v[80:81], off
	v_mov_b32_e32 v85, v159
	v_lshl_add_u64 v[84:85], v[84:85], 2, s[90:91]
	global_load_dwordx4 v[84:87], v[84:85], off
	v_add_u32_e32 v90, 0xb0, v203
	v_lshlrev_b32_e32 v88, 1, v90
	v_mov_b32_e32 v89, v159
	v_lshlrev_b32_e32 v117, 11, v90
	v_lshl_add_u64 v[110:111], v[88:89], 2, s[96:97]
	v_add_u32_e32 v88, v117, v158
	v_lshl_add_u64 v[88:89], v[88:89], 2, s[90:91]
	global_load_dwordx2 v[118:119], v[110:111], off
	v_add_u32_e32 v92, v117, v204
	global_load_dwordx4 v[88:91], v[88:89], off
	v_mov_b32_e32 v93, v159
	v_lshl_add_u64 v[92:93], v[92:93], 2, s[90:91]
	global_load_dwordx4 v[92:95], v[92:93], off
	s_waitcnt vmcnt(0)
	v_sub_f32_e32 v81, v81, v112
	v_sub_f32_e32 v80, v80, v112
	v_sub_f32_e32 v83, v83, v112
	v_sub_f32_e32 v82, v82, v112
	v_pk_mul_f32 v[82:83], v[112:113], v[82:83] op_sel:[1,0]
	v_pk_mul_f32 v[80:81], v[112:113], v[80:81] op_sel:[1,0]
	v_pk_fma_f32 v[78:79], v[192:193], v[82:83], v[78:79]
	v_pk_fma_f32 v[76:77], v[194:195], v[80:81], v[76:77]
	v_add_u32_e32 v80, 0x50000, v148
	v_mov_b32_e32 v81, v159
	v_pk_fma_f32 v[78:79], v[102:103], s[78:79], v[78:79] op_sel_hi:[1,0,1]
	v_pk_fma_f32 v[76:77], v[100:101], s[78:79], v[76:77] op_sel_hi:[1,0,1]
	v_lshl_add_u64 v[80:81], v[80:81], 2, s[88:89]
	global_store_dwordx4 v[80:81], v[76:79], off
	s_nop 1
	v_sub_f32_e32 v77, v85, v112
	v_sub_f32_e32 v76, v84, v112
	v_sub_f32_e32 v79, v87, v112
	v_sub_f32_e32 v78, v86, v112
	v_pk_mul_f32 v[78:79], v[112:113], v[78:79] op_sel:[1,0]
	v_pk_mul_f32 v[76:77], v[112:113], v[76:77] op_sel:[1,0]
	v_pk_fma_f32 v[74:75], v[188:189], v[78:79], v[74:75]
	v_pk_fma_f32 v[72:73], v[190:191], v[76:77], v[72:73]
	v_add_u32_e32 v76, 0x50010, v148
	v_mov_b32_e32 v77, v159
	v_pk_fma_f32 v[74:75], v[98:99], s[78:79], v[74:75] op_sel_hi:[1,0,1]
	v_pk_fma_f32 v[72:73], v[96:97], s[78:79], v[72:73] op_sel_hi:[1,0,1]
	v_lshl_add_u64 v[76:77], v[76:77], 2, s[88:89]
	global_store_dwordx4 v[76:77], v[72:75], off
	s_nop 1
	v_sub_f32_e32 v73, v89, v118
	v_sub_f32_e32 v72, v88, v118
	v_sub_f32_e32 v75, v91, v118
	v_sub_f32_e32 v74, v90, v118
	v_pk_mul_f32 v[74:75], v[118:119], v[74:75] op_sel:[1,0]
	v_pk_mul_f32 v[72:73], v[118:119], v[72:73] op_sel:[1,0]
	v_pk_fma_f32 v[70:71], v[192:193], v[74:75], v[70:71]
	v_pk_fma_f32 v[68:69], v[194:195], v[72:73], v[68:69]
	v_add_u32_e32 v72, 0x58000, v148
	v_mov_b32_e32 v73, v159
	v_pk_fma_f32 v[70:71], v[102:103], s[78:79], v[70:71] op_sel_hi:[1,0,1]
	v_pk_fma_f32 v[68:69], v[100:101], s[78:79], v[68:69] op_sel_hi:[1,0,1]
	v_lshl_add_u64 v[72:73], v[72:73], 2, s[88:89]
	global_store_dwordx4 v[72:73], v[68:71], off
	s_nop 1
	v_sub_f32_e32 v69, v93, v118
	v_sub_f32_e32 v68, v92, v118
	v_sub_f32_e32 v71, v95, v118
	v_sub_f32_e32 v70, v94, v118
	v_pk_mul_f32 v[70:71], v[118:119], v[70:71] op_sel:[1,0]
	v_pk_mul_f32 v[68:69], v[118:119], v[68:69] op_sel:[1,0]
	v_pk_fma_f32 v[66:67], v[188:189], v[70:71], v[66:67]
	v_pk_fma_f32 v[64:65], v[190:191], v[68:69], v[64:65]
	v_add_u32_e32 v68, 0x58010, v148
	v_mov_b32_e32 v69, v159
	v_pk_fma_f32 v[66:67], v[98:99], s[78:79], v[66:67] op_sel_hi:[1,0,1]
	v_pk_fma_f32 v[64:65], v[96:97], s[78:79], v[64:65] op_sel_hi:[1,0,1]
	v_lshl_add_u64 v[68:69], v[68:69], 2, s[88:89]
	global_store_dwordx4 v[68:69], v[64:67], off
	global_load_dwordx4 v[64:67], v[150:151], off offset:512
	v_or_b32_e32 v119, 0x80, v158
	v_add_u32_e32 v72, v202, v119
	v_mov_b32_e32 v73, v159
	v_lshl_add_u64 v[72:73], v[72:73], 2, s[90:91]
	v_or_b32_e32 v118, 0x90, v158
	v_add_u32_e32 v158, v202, v118
	s_waitcnt vmcnt(0)
;     template <bool LN, int BJ, int LO, int HI> DI void batch(const f32x4 (&acc)[2][2][4][2], unsigned row0, unsigned col0, const f32x4 (&gv)[2], const f32x4 (&bv)[2]) const {
;         f32x4 r[HI - LO]; float mean[(HI - LO) / 2], rstd[(HI - LO) / 2];
; #pragma unroll
;         for (int i = LO; i < HI; ++i) { const int ai = i >> 3, m = (i >> 1) & 3, n = i & 1; const unsigned row = row0 + ai * HALF + m * 16;
;             if (n == 0) { mean[(i - LO) >> 1] = 0.f; rstd[(i - LO) >> 1] = 1.f;
;                 if (LN) { const float2 st = *(const float2*)(stats + row * 2u); mean[(i - LO) >> 1] = st.x; rstd[(i - LO) >> 1] = st.y; } }
;             r[i - LO] = *(const f32x4*)(src + (row * (unsigned)DM + col0 + BJ * HALF + n * 16)); }
; #pragma unroll
;         for (int i = LO; i < HI; ++i) { const int ai = i >> 3, m = (i >> 1) & 3, n = i & 1; const unsigned row = row0 + ai * HALF + m * 16;
;             *(f32x4*)(Y + (row * (unsigned)DM + col0 + BJ * HALF + n * 16)) = acc[ai][BJ][m][n] + ((r[i - LO] - mean[(i - LO) >> 1]) * rstd[(i - LO) >> 1]) * gv[n] + bv[n]; }
	v_pk_mul_f32 v[96:97], v[66:67], s[78:79] op_sel_hi:[1,0]
	v_pk_mul_f32 v[98:99], v[64:65], s[78:79] op_sel_hi:[1,0]
	global_load_dwordx4 v[68:71], v[152:153], off offset:512
	global_load_dwordx4 v[64:67], v[150:151], off offset:576
	global_load_dwordx2 v[138:139], v[154:155], off
	global_load_dwordx4 v[126:129], v[72:73], off
	v_lshl_add_u64 v[72:73], v[158:159], 2, s[90:91]
	v_add_u32_e32 v158, v149, v119
	s_waitcnt vmcnt(0)
	v_pk_mul_f32 v[92:93], v[66:67], s[78:79] op_sel_hi:[1,0]
	v_pk_mul_f32 v[94:95], v[64:65], s[78:79] op_sel_hi:[1,0]
	global_load_dwordx4 v[64:67], v[152:153], off offset:576
	global_load_dwordx4 v[130:133], v[72:73], off
	global_load_dwordx2 v[112:113], v[186:187], off
	v_lshl_add_u64 v[72:73], v[158:159], 2, s[90:91]
	global_load_dwordx4 v[134:137], v[72:73], off
	v_add_u32_e32 v158, v149, v118
	v_lshl_add_u64 v[72:73], v[158:159], 2, s[90:91]
	global_load_dwordx4 v[88:91], v[72:73], off
	global_load_dwordx2 v[102:103], v[120:121], off
	v_add_u32_e32 v158, v124, v119
	v_lshl_add_u64 v[72:73], v[158:159], 2, s[90:91]
	global_load_dwordx4 v[84:87], v[72:73], off
	v_add_u32_e32 v158, v124, v118
	v_lshl_add_u64 v[72:73], v[158:159], 2, s[90:91]
	global_load_dwordx4 v[80:83], v[72:73], off
	global_load_dwordx2 v[100:101], v[122:123], off
	v_add_u32_e32 v158, v125, v119
	v_lshl_add_u64 v[72:73], v[158:159], 2, s[90:91]
	global_load_dwordx4 v[76:79], v[72:73], off
	v_add_u32_e32 v158, v125, v118
	v_lshl_add_u64 v[72:73], v[158:159], 2, s[90:91]
	global_load_dwordx4 v[72:75], v[72:73], off
	v_sub_f32_e32 v121, v127, v138
	v_sub_f32_e32 v120, v126, v138
	v_sub_f32_e32 v123, v129, v138
	v_sub_f32_e32 v122, v128, v138
	v_pk_mul_f32 v[122:123], v[138:139], v[122:123] op_sel:[1,0]
	v_pk_mul_f32 v[120:121], v[138:139], v[120:121] op_sel:[1,0]
	v_or_b32_e32 v158, 0x80, v148
	v_pk_fma_f32 v[60:61], v[98:99], v[120:121], v[60:61]
	v_pk_fma_f32 v[62:63], v[96:97], v[122:123], v[62:63]
	v_pk_fma_f32 v[60:61], v[68:69], s[78:79], v[60:61] op_sel_hi:[1,0,1]
	v_pk_fma_f32 v[62:63], v[70:71], s[78:79], v[62:63] op_sel_hi:[1,0,1]
	v_lshl_add_u64 v[120:121], v[158:159], 2, s[88:89]
	global_store_dwordx4 v[120:121], v[60:63], off
	v_or_b32_e32 v158, 0x90, v148
	s_waitcnt vmcnt(0)
	v_sub_f32_e32 v61, v131, v138
	v_sub_f32_e32 v60, v130, v138
	v_sub_f32_e32 v63, v133, v138
	v_sub_f32_e32 v62, v132, v138
	v_pk_mul_f32 v[62:63], v[138:139], v[62:63] op_sel:[1,0]
	v_pk_mul_f32 v[60:61], v[138:139], v[60:61] op_sel:[1,0]
	v_pk_fma_f32 v[58:59], v[92:93], v[62:63], v[58:59]
	v_pk_fma_f32 v[56:57], v[94:95], v[60:61], v[56:57]
	v_pk_fma_f32 v[58:59], v[66:67], s[78:79], v[58:59] op_sel_hi:[1,0,1]
	v_pk_fma_f32 v[56:57], v[64:65], s[78:79], v[56:57] op_sel_hi:[1,0,1]
	v_lshl_add_u64 v[60:61], v[158:159], 2, s[88:89]
	global_store_dwordx4 v[60:61], v[56:59], off
	v_add_u32_e32 v158, 0x8080, v148
	s_nop 0
	v_sub_f32_e32 v57, v135, v112
	v_sub_f32_e32 v56, v134, v112
	v_sub_f32_e32 v59, v137, v112
	v_sub_f32_e32 v58, v136, v112
	v_pk_mul_f32 v[58:59], v[112:113], v[58:59] op_sel:[1,0]
	v_pk_mul_f32 v[56:57], v[112:113], v[56:57] op_sel:[1,0]
	v_pk_fma_f32 v[54:55], v[96:97], v[58:59], v[54:55]
	v_pk_fma_f32 v[52:53], v[98:99], v[56:57], v[52:53]
	v_pk_fma_f32 v[54:55], v[70:71], s[78:79], v[54:55] op_sel_hi:[1,0,1]
	v_pk_fma_f32 v[52:53], v[68:69], s[78:79], v[52:53] op_sel_hi:[1,0,1]
	v_lshl_add_u64 v[56:57], v[158:159], 2, s[88:89]
	global_store_dwordx4 v[56:57], v[52:55], off
	v_add_u32_e32 v158, 0x8090, v148
	s_nop 0
	v_sub_f32_e32 v53, v89, v112
	v_sub_f32_e32 v52, v88, v112
	v_sub_f32_e32 v55, v91, v112
	v_sub_f32_e32 v54, v90, v112
	v_pk_mul_f32 v[54:55], v[112:113], v[54:55] op_sel:[1,0]
	v_pk_mul_f32 v[52:53], v[112:113], v[52:53] op_sel:[1,0]
	v_pk_fma_f32 v[50:51], v[92:93], v[54:55], v[50:51]
	v_pk_fma_f32 v[48:49], v[94:95], v[52:53], v[48:49]
	v_pk_fma_f32 v[50:51], v[66:67], s[78:79], v[50:51] op_sel_hi:[1,0,1]
	v_pk_fma_f32 v[48:49], v[64:65], s[78:79], v[48:49] op_sel_hi:[1,0,1]
	v_lshl_add_u64 v[52:53], v[158:159], 2, s[88:89]
	global_store_dwordx4 v[52:53], v[48:51], off
	v_add_u32_e32 v158, 0x10080, v148
	s_nop 0
	v_sub_f32_e32 v49, v85, v102
	v_sub_f32_e32 v48, v84, v102
	v_sub_f32_e32 v51, v87, v102
	v_sub_f32_e32 v50, v86, v102
	v_pk_mul_f32 v[50:51], v[102:103], v[50:51] op_sel:[1,0]
	v_pk_mul_f32 v[48:49], v[102:103], v[48:49] op_sel:[1,0]
	v_pk_fma_f32 v[46:47], v[96:97], v[50:51], v[46:47]
	v_pk_fma_f32 v[44:45], v[98:99], v[48:49], v[44:45]
	v_pk_fma_f32 v[46:47], v[70:71], s[78:79], v[46:47] op_sel_hi:[1,0,1]
	v_pk_fma_f32 v[44:45], v[68:69], s[78:79], v[44:45] op_sel_hi:[1,0,1]
	v_lshl_add_u64 v[48:49], v[158:159], 2, s[88:89]
	global_store_dwordx4 v[48:49], v[44:47], off
	v_add_u32_e32 v158, 0x10090, v148
	s_nop 0
	v_sub_f32_e32 v45, v81, v102
	v_sub_f32_e32 v44, v80, v102
	v_sub_f32_e32 v47, v83, v102
	v_sub_f32_e32 v46, v82, v102
	v_pk_mul_f32 v[46:47], v[102:103], v[46:47] op_sel:[1,0]
	v_pk_mul_f32 v[44:45], v[102:103], v[44:45] op_sel:[1,0]
	v_pk_fma_f32 v[42:43], v[92:93], v[46:47], v[42:43]
	v_pk_fma_f32 v[40:41], v[94:95], v[44:45], v[40:41]
	v_pk_fma_f32 v[42:43], v[66:67], s[78:79], v[42:43] op_sel_hi:[1,0,1]
	v_pk_fma_f32 v[40:41], v[64:65], s[78:79], v[40:41] op_sel_hi:[1,0,1]
	v_lshl_add_u64 v[44:45], v[158:159], 2, s[88:89]
	global_store_dwordx4 v[44:45], v[40:43], off
	v_add_u32_e32 v158, 0x18080, v148
	s_nop 0
	v_sub_f32_e32 v41, v77, v100
	v_sub_f32_e32 v40, v76, v100
	v_sub_f32_e32 v43, v79, v100
	v_sub_f32_e32 v42, v78, v100
	v_pk_mul_f32 v[42:43], v[100:101], v[42:43] op_sel:[1,0]
	v_pk_mul_f32 v[40:41], v[100:101], v[40:41] op_sel:[1,0]
	v_pk_fma_f32 v[38:39], v[96:97], v[42:43], v[38:39]
;     template <bool LN, int BJ, int LO, int HI> DI void batch(const f32x4 (&acc)[2][2][4][2], unsigned row0, unsigned col0, const f32x4 (&gv)[2], const f32x4 (&bv)[2]) const {
;         f32x4 r[HI - LO]; float mean[(HI - LO) / 2], rstd[(HI - LO) / 2];
; #pragma unroll
;         for (int i = LO; i < HI; ++i) { const int ai = i >> 3, m = (i >> 1) & 3, n = i & 1; const unsigned row = row0 + ai * HALF + m * 16;
;             if (n == 0) { mean[(i - LO) >> 1] = 0.f; rstd[(i - LO) >> 1] = 1.f;
;                 if (LN) { const float2 st = *(const float2*)(stats + row * 2u); mean[(i - LO) >> 1] = st.x; rstd[(i - LO) >> 1] = st.y; } }
;             r[i - LO] = *(const f32x4*)(src + (row * (unsigned)DM + col0 + BJ * HALF + n * 16)); }
; #pragma unroll
;         for (int i = LO; i < HI; ++i) { const int ai = i >> 3, m = (i >> 1) & 3, n = i & 1; const unsigned row = row0 + ai * HALF + m * 16;
;             *(f32x4*)(Y + (row * (unsigned)DM + col0 + BJ * HALF + n * 16)) = acc[ai][BJ][m][n] + ((r[i - LO] - mean[(i - LO) >> 1]) * rstd[(i - LO) >> 1]) * gv[n] + bv[n]; }
	v_pk_fma_f32 v[36:37], v[98:99], v[40:41], v[36:37]
	v_pk_fma_f32 v[38:39], v[70:71], s[78:79], v[38:39] op_sel_hi:[1,0,1]
	v_pk_fma_f32 v[36:37], v[68:69], s[78:79], v[36:37] op_sel_hi:[1,0,1]
	v_lshl_add_u64 v[40:41], v[158:159], 2, s[88:89]
	global_store_dwordx4 v[40:41], v[36:39], off
	v_add_u32_e32 v158, 0x18090, v148
	s_nop 0
	v_sub_f32_e32 v37, v73, v100
	v_sub_f32_e32 v36, v72, v100
	v_sub_f32_e32 v39, v75, v100
	v_sub_f32_e32 v38, v74, v100
	v_pk_mul_f32 v[38:39], v[100:101], v[38:39] op_sel:[1,0]
	v_pk_mul_f32 v[36:37], v[100:101], v[36:37] op_sel:[1,0]
	v_pk_fma_f32 v[34:35], v[92:93], v[38:39], v[34:35]
	v_pk_fma_f32 v[32:33], v[94:95], v[36:37], v[32:33]
	v_pk_fma_f32 v[34:35], v[66:67], s[78:79], v[34:35] op_sel_hi:[1,0,1]
	v_pk_fma_f32 v[32:33], v[64:65], s[78:79], v[32:33] op_sel_hi:[1,0,1]
	v_lshl_add_u64 v[36:37], v[158:159], 2, s[88:89]
	global_store_dwordx4 v[36:37], v[32:35], off
	v_add_u32_e32 v158, v114, v119
	s_nop 0
	v_lshl_add_u64 v[32:33], v[158:159], 2, s[90:91]
	global_load_dwordx2 v[62:63], v[104:105], off
	global_load_dwordx4 v[54:57], v[32:33], off
	v_add_u32_e32 v158, v114, v118
	v_lshl_add_u64 v[32:33], v[158:159], 2, s[90:91]
	global_load_dwordx4 v[58:61], v[32:33], off
	global_load_dwordx2 v[52:53], v[106:107], off
	v_add_u32_e32 v158, v115, v119
	v_lshl_add_u64 v[32:33], v[158:159], 2, s[90:91]
	global_load_dwordx4 v[72:75], v[32:33], off
	v_add_u32_e32 v158, v115, v118
	v_lshl_add_u64 v[32:33], v[158:159], 2, s[90:91]
	global_load_dwordx4 v[76:79], v[32:33], off
	global_load_dwordx2 v[50:51], v[108:109], off
	v_add_u32_e32 v158, v116, v119
	v_lshl_add_u64 v[32:33], v[158:159], 2, s[90:91]
	global_load_dwordx4 v[44:47], v[32:33], off
	v_add_u32_e32 v158, v116, v118
	v_lshl_add_u64 v[32:33], v[158:159], 2, s[90:91]
	global_load_dwordx4 v[40:43], v[32:33], off
	global_load_dwordx2 v[48:49], v[110:111], off
	v_add_u32_e32 v158, v117, v119
	v_lshl_add_u64 v[32:33], v[158:159], 2, s[90:91]
	global_load_dwordx4 v[36:39], v[32:33], off
	v_add_u32_e32 v158, v117, v118
	v_lshl_add_u64 v[32:33], v[158:159], 2, s[90:91]
	global_load_dwordx4 v[32:35], v[32:33], off
	v_add_u32_e32 v158, 0x40080, v148
	s_waitcnt vmcnt(0)
; #define PG8_WAIT_V(n) asm volatile("s_waitcnt vmcnt(" #n ")" ::: "memory")
; #define PG8_BAR __builtin_amdgcn_s_barrier()
; template <class Epi>
; DI void gemm_phase(LAS unsigned char* lds, const Gemm g, const StaticOrder& S, const Epi& E) {
;     ...
;         E(acc, cur, wr, wc, fr, fq);
;         if (!has_next) break;
; #pragma unroll
;         for (int a = 0; a < 2; ++a)
; #pragma unroll
;             for (int b = 0; b < 2; ++b)
; #pragma unroll
;                 for (int m = 0; m < 4; ++m)
; #pragma unroll
;                     for (int n = 0; n < 2; ++n) acc[a][b][m][n] = (f32x4){0.f, 0.f, 0.f, 0.f};
;         cur = nxt; cA = nA; cB = nB; ++ui;
;     }
;     PG8_WAIT_V(0);
;     if (wr == 0) PG8_BAR;
;     template <bool LN, int BJ, int LO, int HI> DI void batch(const f32x4 (&acc)[2][2][4][2], unsigned row0, unsigned col0, const f32x4 (&gv)[2], const f32x4 (&bv)[2]) const {
;         f32x4 r[HI - LO]; float mean[(HI - LO) / 2], rstd[(HI - LO) / 2];
; #pragma unroll
;         for (int i = LO; i < HI; ++i) { const int ai = i >> 3, m = (i >> 1) & 3, n = i & 1; const unsigned row = row0 + ai * HALF + m * 16;
;             if (n == 0) { mean[(i - LO) >> 1] = 0.f; rstd[(i - LO) >> 1] = 1.f;
;                 if (LN) { const float2 st = *(const float2*)(stats + row * 2u); mean[(i - LO) >> 1] = st.x; rstd[(i - LO) >> 1] = st.y; } }
;             r[i - LO] = *(const f32x4*)(src + (row * (unsigned)DM + col0 + BJ * HALF + n * 16)); }
; #pragma unroll
;         for (int i = LO; i < HI; ++i) { const int ai = i >> 3, m = (i >> 1) & 3, n = i & 1; const unsigned row = row0 + ai * HALF + m * 16;
;             *(f32x4*)(Y + (row * (unsigned)DM + col0 + BJ * HALF + n * 16)) = acc[ai][BJ][m][n] + ((r[i - LO] - mean[(i - LO) >> 1]) * rstd[(i - LO) >> 1]) * gv[n] + bv[n]; }
	v_sub_f32_e32 v55, v55, v62
	v_sub_f32_e32 v54, v54, v62
	v_sub_f32_e32 v57, v57, v62
	v_sub_f32_e32 v56, v56, v62
	v_pk_mul_f32 v[56:57], v[62:63], v[56:57] op_sel:[1,0]
	v_pk_mul_f32 v[54:55], v[62:63], v[54:55] op_sel:[1,0]
	v_pk_fma_f32 v[30:31], v[96:97], v[56:57], v[30:31]
	v_pk_fma_f32 v[28:29], v[98:99], v[54:55], v[28:29]
	v_pk_fma_f32 v[30:31], v[70:71], s[78:79], v[30:31] op_sel_hi:[1,0,1]
	v_pk_fma_f32 v[28:29], v[68:69], s[78:79], v[28:29] op_sel_hi:[1,0,1]
	v_lshl_add_u64 v[54:55], v[158:159], 2, s[88:89]
	global_store_dwordx4 v[54:55], v[28:31], off
	v_add_u32_e32 v158, 0x40090, v148
	s_nop 0
	v_sub_f32_e32 v29, v59, v62
	v_sub_f32_e32 v28, v58, v62
	v_sub_f32_e32 v31, v61, v62
	v_sub_f32_e32 v30, v60, v62
	v_pk_mul_f32 v[30:31], v[62:63], v[30:31] op_sel:[1,0]
	v_pk_mul_f32 v[28:29], v[62:63], v[28:29] op_sel:[1,0]
	v_pk_fma_f32 v[26:27], v[92:93], v[30:31], v[26:27]
	v_pk_fma_f32 v[24:25], v[94:95], v[28:29], v[24:25]
	v_pk_fma_f32 v[26:27], v[66:67], s[78:79], v[26:27] op_sel_hi:[1,0,1]
	v_pk_fma_f32 v[24:25], v[64:65], s[78:79], v[24:25] op_sel_hi:[1,0,1]
	v_lshl_add_u64 v[28:29], v[158:159], 2, s[88:89]
	global_store_dwordx4 v[28:29], v[24:27], off
	v_add_u32_e32 v158, 0x48080, v148
	s_nop 0
	v_sub_f32_e32 v25, v73, v52
	v_sub_f32_e32 v24, v72, v52
	v_sub_f32_e32 v27, v75, v52
	v_sub_f32_e32 v26, v74, v52
	v_pk_mul_f32 v[26:27], v[52:53], v[26:27] op_sel:[1,0]
	v_pk_mul_f32 v[24:25], v[52:53], v[24:25] op_sel:[1,0]
	v_pk_fma_f32 v[22:23], v[96:97], v[26:27], v[22:23]
	v_pk_fma_f32 v[20:21], v[98:99], v[24:25], v[20:21]
	v_pk_fma_f32 v[22:23], v[70:71], s[78:79], v[22:23] op_sel_hi:[1,0,1]
	v_pk_fma_f32 v[20:21], v[68:69], s[78:79], v[20:21] op_sel_hi:[1,0,1]
	v_lshl_add_u64 v[24:25], v[158:159], 2, s[88:89]
	global_store_dwordx4 v[24:25], v[20:23], off
	v_add_u32_e32 v158, 0x48090, v148
	s_nop 0
	v_sub_f32_e32 v21, v77, v52
	v_sub_f32_e32 v20, v76, v52
	v_sub_f32_e32 v23, v79, v52
	v_sub_f32_e32 v22, v78, v52
	v_pk_mul_f32 v[22:23], v[52:53], v[22:23] op_sel:[1,0]
	v_pk_mul_f32 v[20:21], v[52:53], v[20:21] op_sel:[1,0]
	v_pk_fma_f32 v[18:19], v[92:93], v[22:23], v[18:19]
	v_pk_fma_f32 v[16:17], v[94:95], v[20:21], v[16:17]
	v_pk_fma_f32 v[18:19], v[66:67], s[78:79], v[18:19] op_sel_hi:[1,0,1]
	v_pk_fma_f32 v[16:17], v[64:65], s[78:79], v[16:17] op_sel_hi:[1,0,1]
	v_lshl_add_u64 v[20:21], v[158:159], 2, s[88:89]
	global_store_dwordx4 v[20:21], v[16:19], off
	v_add_u32_e32 v158, 0x50080, v148
	s_nop 0
	v_sub_f32_e32 v17, v45, v50
	v_sub_f32_e32 v16, v44, v50
	v_sub_f32_e32 v19, v47, v50
	v_sub_f32_e32 v18, v46, v50
	v_pk_mul_f32 v[18:19], v[50:51], v[18:19] op_sel:[1,0]
	v_pk_mul_f32 v[16:17], v[50:51], v[16:17] op_sel:[1,0]
	v_pk_fma_f32 v[14:15], v[96:97], v[18:19], v[14:15]
	v_pk_fma_f32 v[12:13], v[98:99], v[16:17], v[12:13]
	v_pk_fma_f32 v[14:15], v[70:71], s[78:79], v[14:15] op_sel_hi:[1,0,1]
	v_pk_fma_f32 v[12:13], v[68:69], s[78:79], v[12:13] op_sel_hi:[1,0,1]
	v_lshl_add_u64 v[16:17], v[158:159], 2, s[88:89]
	global_store_dwordx4 v[16:17], v[12:15], off
	v_add_u32_e32 v158, 0x50090, v148
	s_nop 0
	v_sub_f32_e32 v13, v41, v50
	v_sub_f32_e32 v12, v40, v50
	v_sub_f32_e32 v15, v43, v50
	v_sub_f32_e32 v14, v42, v50
	v_pk_mul_f32 v[14:15], v[50:51], v[14:15] op_sel:[1,0]
	v_pk_mul_f32 v[12:13], v[50:51], v[12:13] op_sel:[1,0]
	v_pk_fma_f32 v[10:11], v[92:93], v[14:15], v[10:11]
	v_pk_fma_f32 v[8:9], v[94:95], v[12:13], v[8:9]
	v_pk_fma_f32 v[10:11], v[66:67], s[78:79], v[10:11] op_sel_hi:[1,0,1]
	v_pk_fma_f32 v[8:9], v[64:65], s[78:79], v[8:9] op_sel_hi:[1,0,1]
	v_lshl_add_u64 v[12:13], v[158:159], 2, s[88:89]
	global_store_dwordx4 v[12:13], v[8:11], off
	v_add_u32_e32 v158, 0x58080, v148
	s_nop 0
	v_sub_f32_e32 v9, v37, v48
	v_sub_f32_e32 v8, v36, v48
	v_sub_f32_e32 v11, v39, v48
	v_sub_f32_e32 v10, v38, v48
	v_pk_mul_f32 v[10:11], v[48:49], v[10:11] op_sel:[1,0]
	v_pk_mul_f32 v[8:9], v[48:49], v[8:9] op_sel:[1,0]
	v_pk_fma_f32 v[6:7], v[96:97], v[10:11], v[6:7]
	v_pk_fma_f32 v[4:5], v[98:99], v[8:9], v[4:5]
	v_pk_fma_f32 v[6:7], v[70:71], s[78:79], v[6:7] op_sel_hi:[1,0,1]
	v_pk_fma_f32 v[4:5], v[68:69], s[78:79], v[4:5] op_sel_hi:[1,0,1]
	v_lshl_add_u64 v[8:9], v[158:159], 2, s[88:89]
	global_store_dwordx4 v[8:9], v[4:7], off
	v_add_u32_e32 v158, 0x58090, v148
	s_nop 0
	v_sub_f32_e32 v5, v33, v48
	v_sub_f32_e32 v4, v32, v48
	v_sub_f32_e32 v7, v35, v48
	v_sub_f32_e32 v6, v34, v48
	v_pk_mul_f32 v[6:7], v[48:49], v[6:7] op_sel:[1,0]
	v_pk_mul_f32 v[4:5], v[48:49], v[4:5] op_sel:[1,0]
	v_pk_fma_f32 v[2:3], v[92:93], v[6:7], v[2:3]
	v_pk_fma_f32 v[0:1], v[94:95], v[4:5], v[0:1]
	v_pk_fma_f32 v[2:3], v[66:67], s[78:79], v[2:3] op_sel_hi:[1,0,1]
	v_pk_fma_f32 v[0:1], v[64:65], s[78:79], v[0:1] op_sel_hi:[1,0,1]
	v_lshl_add_u64 v[4:5], v[158:159], 2, s[88:89]
	global_store_dwordx4 v[4:5], v[0:3], off
	s_and_b64 vcc, exec, s[6:7]
	s_mov_b32 s2, s37
	s_mov_b32 s3, s38
	s_mov_b64 s[18:19], s[10:11]
	s_mov_b64 s[16:17], s[8:9]
	v_readlane_b32 s33, v255, 39
	s_cbranch_vccz .LBB0_123
	s_waitcnt vmcnt(0)
	s_cmpk_gt_u32 s24, 0xff
	s_cbranch_scc1 .LBB0_138
	s_barrier

; #define PG8_STAGE(bufoff, gbase) do { _Pragma("unroll") for (int _i = 0; _i < 2; ++_i) \
;         __builtin_amdgcn_global_load_lds((const unsigned*)((const char*)(gbase) + voff[_i]), (LAS unsigned*)(lds + (bufoff) + ldsw + _i * 8192), 16, 0, 0); } while (0)
; #define PG8_LDA(dst, b, h) do { _Pragma("unroll") for (int m = 0; m < 4; ++m) _Pragma("unroll") for (int k = 0; k < 2; ++k) dst[m][k] = *(const LAS bf16x8*)(lds + PG8_SA(b, h) + aoff + m * 2048 + k * 1024); } while (0)
; #define PG8_LDB(dst, b, h) do { _Pragma("unroll") for (int n = 0; n < 2; ++n) _Pragma("unroll") for (int k = 0; k < 2; ++k) dst[n][k] = *(const LAS bf16x8*)(lds + PG8_SB(b, h) + boff + n * 2048 + k * 1024); } while (0)
; #define PG8_MMA(ai, bj, At, Bt) do { __builtin_amdgcn_s_setprio(1); _Pragma("unroll") for (int m = 0; m < 4; ++m) _Pragma("unroll") for (int n = 0; n < 2; ++n) _Pragma("unroll") for (int k = 0; k < 2; ++k) \
;         acc[ai][bj][m][n] = __builtin_amdgcn_mfma_f32_16x16x32_bf16(Bt[n][k], At[m][k], acc[ai][bj][m][n], 0, 0, 0); __builtin_amdgcn_s_setprio(0); } while (0)
; #define PG8_WAIT_L(n) asm volatile("s_waitcnt lgkmcnt(" #n ")" ::: "memory")
; #define PG8_BAR __builtin_amdgcn_s_barrier()
; #define PG8_SCHED __builtin_amdgcn_sched_barrier(0)
; template <class Epi>
; DI void gemm_phase(LAS unsigned char* lds, const Gemm g, const StaticOrder& S, const Epi& E) {
;     ...
;             const bool last = (t == nt - 2);
;             const char* a1 = cA + (size_t)(t + 1) * kstep;
;             const char* a2 = last ? nA : cA + (size_t)(t + 2) * kstep; const char* b2 = last ? nB : cB + (size_t)(t + 2) * kstep;
;             const char* a3 = a2 + kstep; const char* b3 = b2 + kstep;
;             PG8_LDB(B0, 0, 0); PG8_SCHED; PG8_LDA(At, 0, 0); PG8_STAGE(PG8_SA(1, 1), a1 + hstep);
;             PG8_WAIT_L(8); PG8_BAR; PG8_WAIT_L(0); PG8_MMA(0, 0, At, B0); PG8_BAR; PG8_SCHED;
;             PG8_LDB(B1, 0, 1); PG8_STAGE(PG8_SB(0, 0), b2);
;             PG8_BAR; PG8_WAIT_L(0); PG8_MMA(0, 1, At, B1); PG8_BAR;
;             PG8_LDA(At, 0, 1); PG8_STAGE(PG8_SA(0, 0), a2);
;             PG8_BAR; PG8_WAIT_L(0); PG8_MMA(1, 0, At, B0); PG8_BAR; PG8_SCHED;
.LBB0_202:
	s_add_u32 s18, s8, 0xfff80080
	s_addc_u32 s19, s9, -1
	s_add_i32 s37, 0, 0x10000
	v_add_u32_e32 v140, s37, v187
	s_waitcnt lgkmcnt(0)
	ds_read_b128 v[128:131], v140
	ds_read_b128 v[132:135], v140 offset:1024
	ds_read_b128 v[136:139], v140 offset:2048
	ds_read_b128 v[190:193], v140 offset:3072
	s_cmp_eq_u32 s36, 28
	s_cselect_b32 s21, s4, s19
	s_cselect_b32 s20, s5, s18
	s_cselect_b32 s19, s11, s35
	s_cselect_b32 s18, s13, s33
	v_lshl_add_u64 v[140:141], s[8:9], 0, v[150:151]
	s_add_i32 m0, s26, 0xc000
	ds_read_b128 v[194:197], v189
	ds_read_b128 v[198:201], v189 offset:1024
	ds_read_b128 v[202:205], v189 offset:2048
	ds_read_b128 v[206:209], v189 offset:3072
	ds_read_b128 v[210:213], v189 offset:4096
	ds_read_b128 v[214:217], v189 offset:5120
	ds_read_b128 v[226:229], v189 offset:6144
	ds_read_b128 v[230:233], v189 offset:7168
	global_load_lds_dwordx4 v[140:141], off
	v_lshl_add_u64 v[140:141], s[8:9], 0, v[152:153]
	s_add_i32 m0, s26, 0xe000
	s_nop 0
	global_load_lds_dwordx4 v[140:141], off
	s_waitcnt lgkmcnt(8)
	s_setprio 1
	s_barrier
	s_waitcnt lgkmcnt(0)
	v_mfma_f32_16x16x32_bf16 v[124:127], v[128:131], v[194:197], v[124:127]
	v_mfma_f32_16x16x32_bf16 v[120:123], v[136:139], v[194:197], v[120:123]
	s_add_i32 s40, 0, 0x14000
	v_mfma_f32_16x16x32_bf16 v[108:111], v[128:131], v[202:205], v[108:111]
	v_add_u32_e32 v140, s40, v187
	v_mfma_f32_16x16x32_bf16 v[104:107], v[136:139], v[202:205], v[104:107]
	s_add_i32 s37, s37, s25
	v_mfma_f32_16x16x32_bf16 v[92:95], v[128:131], v[210:213], v[92:95]
	v_mfma_f32_16x16x32_bf16 v[88:91], v[136:139], v[210:213], v[88:91]
	v_mfma_f32_16x16x32_bf16 v[76:79], v[128:131], v[226:229], v[76:79]
	v_mfma_f32_16x16x32_bf16 v[72:75], v[136:139], v[226:229], v[72:75]
	v_mfma_f32_16x16x32_bf16 v[124:127], v[132:135], v[198:201], v[124:127]
	v_mfma_f32_16x16x32_bf16 v[120:123], v[190:193], v[198:201], v[120:123]
	v_mfma_f32_16x16x32_bf16 v[108:111], v[132:135], v[206:209], v[108:111]
	v_mfma_f32_16x16x32_bf16 v[104:107], v[190:193], v[206:209], v[104:107]
	v_mfma_f32_16x16x32_bf16 v[92:95], v[132:135], v[214:217], v[92:95]
	v_mfma_f32_16x16x32_bf16 v[88:91], v[190:193], v[214:217], v[88:91]
	v_mfma_f32_16x16x32_bf16 v[76:79], v[132:135], v[230:233], v[76:79]
	v_mfma_f32_16x16x32_bf16 v[72:75], v[190:193], v[230:233], v[72:75]
	s_setprio 0
	s_barrier
	ds_read_b128 v[234:237], v140
	ds_read_b128 v[238:241], v140 offset:1024
	ds_read_b128 v[242:245], v140 offset:2048
	ds_read_b128 v[246:249], v140 offset:3072
	v_lshl_add_u64 v[140:141], s[18:19], 0, v[144:145]
	s_mov_b32 m0, s37
	v_lshl_add_u64 v[154:155], s[18:19], 0, v[142:143]
	global_load_lds_dwordx4 v[140:141], off
	s_add_i32 m0, s37, 0x2000
	s_nop 0
	global_load_lds_dwordx4 v[154:155], off
	s_waitcnt lgkmcnt(0)
	s_setprio 1
	s_barrier
	v_mfma_f32_16x16x32_bf16 v[116:119], v[234:237], v[194:197], v[116:119]
	v_mfma_f32_16x16x32_bf16 v[112:115], v[242:245], v[194:197], v[112:115]
	v_mfma_f32_16x16x32_bf16 v[100:103], v[234:237], v[202:205], v[100:103]
	v_mfma_f32_16x16x32_bf16 v[96:99], v[242:245], v[202:205], v[96:99]
	v_mfma_f32_16x16x32_bf16 v[84:87], v[234:237], v[210:213], v[84:87]
	v_mfma_f32_16x16x32_bf16 v[80:83], v[242:245], v[210:213], v[80:83]
	v_mfma_f32_16x16x32_bf16 v[68:71], v[234:237], v[226:229], v[68:71]
	v_mfma_f32_16x16x32_bf16 v[64:67], v[242:245], v[226:229], v[64:67]
	v_mfma_f32_16x16x32_bf16 v[116:119], v[238:241], v[198:201], v[116:119]
	s_mov_b32 m0, s26
	v_mfma_f32_16x16x32_bf16 v[112:115], v[246:249], v[198:201], v[112:115]
	v_lshl_add_u64 v[218:219], s[20:21], 0, v[144:145]
	v_mfma_f32_16x16x32_bf16 v[100:103], v[238:241], v[206:209], v[100:103]
	v_mfma_f32_16x16x32_bf16 v[96:99], v[246:249], v[206:209], v[96:99]
	v_mfma_f32_16x16x32_bf16 v[84:87], v[238:241], v[214:217], v[84:87]
	v_mfma_f32_16x16x32_bf16 v[80:83], v[246:249], v[214:217], v[80:83]
	v_mfma_f32_16x16x32_bf16 v[68:71], v[238:241], v[230:233], v[68:71]
	v_mfma_f32_16x16x32_bf16 v[64:67], v[246:249], v[230:233], v[64:67]
	s_setprio 0
	s_barrier
	ds_read_b128 v[194:197], v189 offset:16384
	ds_read_b128 v[198:201], v189 offset:17408
	ds_read_b128 v[202:205], v189 offset:18432
	ds_read_b128 v[206:209], v189 offset:19456
	ds_read_b128 v[210:213], v189 offset:20480
	ds_read_b128 v[214:217], v189 offset:21504
	ds_read_b128 v[226:229], v189 offset:22528
	ds_read_b128 v[230:233], v189 offset:23552
	global_load_lds_dwordx4 v[218:219], off
	v_lshl_add_u64 v[250:251], s[20:21], 0, v[142:143]
	s_mov_b32 m0, s27
	s_nop 0
	global_load_lds_dwordx4 v[250:251], off
	s_waitcnt lgkmcnt(0)
	s_setprio 1
	s_barrier
	v_mfma_f32_16x16x32_bf16 v[60:63], v[128:131], v[194:197], v[60:63]
	v_mfma_f32_16x16x32_bf16 v[56:59], v[136:139], v[194:197], v[56:59]
	s_add_u32 s38, s18, 0x80000
	v_mfma_f32_16x16x32_bf16 v[44:47], v[128:131], v[202:205], v[44:47]
	s_addc_u32 s39, s19, 0
	v_mfma_f32_16x16x32_bf16 v[40:43], v[136:139], v[202:205], v[40:43]
	s_add_i32 s37, s40, s25
	v_mfma_f32_16x16x32_bf16 v[28:31], v[128:131], v[210:213], v[28:31]
	v_mfma_f32_16x16x32_bf16 v[24:27], v[136:139], v[210:213], v[24:27]
	v_mfma_f32_16x16x32_bf16 v[12:15], v[128:131], v[226:229], v[12:15]
	v_mfma_f32_16x16x32_bf16 v[8:11], v[136:139], v[226:229], v[8:11]
	v_mfma_f32_16x16x32_bf16 v[60:63], v[132:135], v[198:201], v[60:63]
	v_mfma_f32_16x16x32_bf16 v[56:59], v[190:193], v[198:201], v[56:59]
	v_mfma_f32_16x16x32_bf16 v[44:47], v[132:135], v[206:209], v[44:47]
	v_mfma_f32_16x16x32_bf16 v[40:43], v[190:193], v[206:209], v[40:43]
	v_mfma_f32_16x16x32_bf16 v[28:31], v[132:135], v[214:217], v[28:31]
	v_mfma_f32_16x16x32_bf16 v[24:27], v[190:193], v[214:217], v[24:27]
	v_mfma_f32_16x16x32_bf16 v[12:15], v[132:135], v[230:233], v[12:15]
	v_mfma_f32_16x16x32_bf16 v[8:11], v[190:193], v[230:233], v[8:11]
	s_setprio 0
	s_barrier
; #define PG8_STAGE(bufoff, gbase) do { _Pragma("unroll") for (int _i = 0; _i < 2; ++_i) \
;         __builtin_amdgcn_global_load_lds((const unsigned*)((const char*)(gbase) + voff[_i]), (LAS unsigned*)(lds + (bufoff) + ldsw + _i * 8192), 16, 0, 0); } while (0)
; #define PG8_LDA(dst, b, h) do { _Pragma("unroll") for (int m = 0; m < 4; ++m) _Pragma("unroll") for (int k = 0; k < 2; ++k) dst[m][k] = *(const LAS bf16x8*)(lds + PG8_SA(b, h) + aoff + m * 2048 + k * 1024); } while (0)
; #define PG8_LDB(dst, b, h) do { _Pragma("unroll") for (int n = 0; n < 2; ++n) _Pragma("unroll") for (int k = 0; k < 2; ++k) dst[n][k] = *(const LAS bf16x8*)(lds + PG8_SB(b, h) + boff + n * 2048 + k * 1024); } while (0)
; #define PG8_MMA(ai, bj, At, Bt) do { __builtin_amdgcn_s_setprio(1); _Pragma("unroll") for (int m = 0; m < 4; ++m) _Pragma("unroll") for (int n = 0; n < 2; ++n) _Pragma("unroll") for (int k = 0; k < 2; ++k) \
;         acc[ai][bj][m][n] = __builtin_amdgcn_mfma_f32_16x16x32_bf16(Bt[n][k], At[m][k], acc[ai][bj][m][n], 0, 0, 0); __builtin_amdgcn_s_setprio(0); } while (0)
; #define PG8_WAIT_V(n) asm volatile("s_waitcnt vmcnt(" #n ")" ::: "memory")
; #define PG8_WAIT_L(n) asm volatile("s_waitcnt lgkmcnt(" #n ")" ::: "memory")
; #define PG8_BAR __builtin_amdgcn_s_barrier()
; #define PG8_SCHED __builtin_amdgcn_sched_barrier(0)
; template <class Epi>
; DI void gemm_phase(LAS unsigned char* lds, const Gemm g, const StaticOrder& S, const Epi& E) {
;     ...
;             PG8_STAGE(PG8_SB(0, 1), b2 + hstep);
;             PG8_WAIT_V(6); PG8_BAR; PG8_MMA(1, 1, At, B1); PG8_BAR;
;             PG8_LDB(B0, 1, 0); PG8_SCHED; PG8_LDA(At, 1, 0); PG8_STAGE(PG8_SA(0, 1), a2 + hstep);
;             PG8_WAIT_L(8); PG8_BAR; PG8_WAIT_L(0); PG8_MMA(0, 0, At, B0); PG8_BAR; PG8_SCHED;
;             PG8_LDB(B1, 1, 1); PG8_STAGE(PG8_SB(1, 0), b3);
;             PG8_BAR; PG8_WAIT_L(0); PG8_MMA(0, 1, At, B1); PG8_BAR;
;             PG8_LDA(At, 1, 1); PG8_STAGE(PG8_SA(1, 0), a3);
	v_lshl_add_u64 v[128:129], s[38:39], 0, v[144:145]
	s_mov_b32 m0, s37
	s_nop 0
	global_load_lds_dwordx4 v[128:129], off
	v_lshl_add_u64 v[128:129], s[38:39], 0, v[142:143]
	s_add_i32 m0, s37, 0x2000
	s_nop 0
	global_load_lds_dwordx4 v[128:129], off
	s_waitcnt vmcnt(6)
	s_setprio 1
	s_barrier
	v_mfma_f32_16x16x32_bf16 v[52:55], v[234:237], v[194:197], v[52:55]
	v_mfma_f32_16x16x32_bf16 v[48:51], v[242:245], v[194:197], v[48:51]
	v_mfma_f32_16x16x32_bf16 v[36:39], v[234:237], v[202:205], v[36:39]
	v_mfma_f32_16x16x32_bf16 v[32:35], v[242:245], v[202:205], v[32:35]
	v_mfma_f32_16x16x32_bf16 v[20:23], v[234:237], v[210:213], v[20:23]
	v_mfma_f32_16x16x32_bf16 v[16:19], v[242:245], v[210:213], v[16:19]
	v_mfma_f32_16x16x32_bf16 v[4:7], v[234:237], v[226:229], v[4:7]
	v_mfma_f32_16x16x32_bf16 v[0:3], v[242:245], v[226:229], v[0:3]
	v_mfma_f32_16x16x32_bf16 v[52:55], v[238:241], v[198:201], v[52:55]
	s_add_i32 s37, 0, 0x18000
	v_mfma_f32_16x16x32_bf16 v[48:51], v[246:249], v[198:201], v[48:51]
	v_add_u32_e32 v158, s37, v187
	v_mfma_f32_16x16x32_bf16 v[36:39], v[238:241], v[206:209], v[36:39]
	v_mfma_f32_16x16x32_bf16 v[32:35], v[246:249], v[206:209], v[32:35]
	v_mfma_f32_16x16x32_bf16 v[20:23], v[238:241], v[214:217], v[20:23]
	v_mfma_f32_16x16x32_bf16 v[16:19], v[246:249], v[214:217], v[16:19]
	v_mfma_f32_16x16x32_bf16 v[4:7], v[238:241], v[230:233], v[4:7]
	v_mfma_f32_16x16x32_bf16 v[0:3], v[246:249], v[230:233], v[0:3]
	s_setprio 0
	s_barrier
	ds_read_b128 v[128:131], v158
	ds_read_b128 v[132:135], v158 offset:1024
	ds_read_b128 v[136:139], v158 offset:2048
	ds_read_b128 v[190:193], v158 offset:3072
	s_add_u32 s20, s20, 0x80000
	s_addc_u32 s21, s21, 0
	s_mov_b32 m0, s28
	v_lshl_add_u64 v[234:235], s[20:21], 0, v[144:145]
	ds_read_b128 v[194:197], v189 offset:32768
	ds_read_b128 v[198:201], v189 offset:33792
	ds_read_b128 v[202:205], v189 offset:34816
	ds_read_b128 v[206:209], v189 offset:35840
	ds_read_b128 v[210:213], v189 offset:36864
	ds_read_b128 v[214:217], v189 offset:37888
	ds_read_b128 v[226:229], v189 offset:38912
	ds_read_b128 v[230:233], v189 offset:39936
	global_load_lds_dwordx4 v[234:235], off
	v_lshl_add_u64 v[234:235], s[20:21], 0, v[142:143]
	s_mov_b32 m0, s29
	s_nop 0
	global_load_lds_dwordx4 v[234:235], off
	s_waitcnt lgkmcnt(8)
	s_setprio 1
	s_barrier
	s_waitcnt lgkmcnt(0)
	v_mfma_f32_16x16x32_bf16 v[124:127], v[128:131], v[194:197], v[124:127]
	v_mfma_f32_16x16x32_bf16 v[120:123], v[136:139], v[194:197], v[120:123]
	s_add_i32 s20, 0, 0x1c000
	v_mfma_f32_16x16x32_bf16 v[108:111], v[128:131], v[202:205], v[108:111]
	s_add_i32 s21, s37, s25
	v_mfma_f32_16x16x32_bf16 v[104:107], v[136:139], v[202:205], v[104:107]
	v_add_u32_e32 v158, s20, v187
	v_mfma_f32_16x16x32_bf16 v[92:95], v[128:131], v[210:213], v[92:95]
	v_lshl_add_u64 v[140:141], v[140:141], 0, s[94:95]
	v_mfma_f32_16x16x32_bf16 v[88:91], v[136:139], v[210:213], v[88:91]
	s_mov_b32 m0, s21
	v_mfma_f32_16x16x32_bf16 v[76:79], v[128:131], v[226:229], v[76:79]
	v_mfma_f32_16x16x32_bf16 v[72:75], v[136:139], v[226:229], v[72:75]
	v_mfma_f32_16x16x32_bf16 v[124:127], v[132:135], v[198:201], v[124:127]
	v_mfma_f32_16x16x32_bf16 v[120:123], v[190:193], v[198:201], v[120:123]
	v_mfma_f32_16x16x32_bf16 v[108:111], v[132:135], v[206:209], v[108:111]
	v_mfma_f32_16x16x32_bf16 v[104:107], v[190:193], v[206:209], v[104:107]
	v_mfma_f32_16x16x32_bf16 v[92:95], v[132:135], v[214:217], v[92:95]
	v_mfma_f32_16x16x32_bf16 v[88:91], v[190:193], v[214:217], v[88:91]
	v_mfma_f32_16x16x32_bf16 v[76:79], v[132:135], v[230:233], v[76:79]
	v_mfma_f32_16x16x32_bf16 v[72:75], v[190:193], v[230:233], v[72:75]
	s_setprio 0
	s_barrier
	ds_read_b128 v[234:237], v158
	ds_read_b128 v[238:241], v158 offset:1024
	ds_read_b128 v[242:245], v158 offset:2048
	ds_read_b128 v[246:249], v158 offset:3072
	global_load_lds_dwordx4 v[140:141], off
	v_lshl_add_u64 v[140:141], v[154:155], 0, s[94:95]
	s_add_i32 m0, s21, 0x2000
	s_nop 0
	global_load_lds_dwordx4 v[140:141], off
	s_waitcnt lgkmcnt(0)
	s_setprio 1
	s_barrier
; #define PG8_STAGE(bufoff, gbase) do { _Pragma("unroll") for (int _i = 0; _i < 2; ++_i) \
;         __builtin_amdgcn_global_load_lds((const unsigned*)((const char*)(gbase) + voff[_i]), (LAS unsigned*)(lds + (bufoff) + ldsw + _i * 8192), 16, 0, 0); } while (0)
; #define PG8_LDA(dst, b, h) do { _Pragma("unroll") for (int m = 0; m < 4; ++m) _Pragma("unroll") for (int k = 0; k < 2; ++k) dst[m][k] = *(const LAS bf16x8*)(lds + PG8_SA(b, h) + aoff + m * 2048 + k * 1024); } while (0)
; #define PG8_MMA(ai, bj, At, Bt) do { __builtin_amdgcn_s_setprio(1); _Pragma("unroll") for (int m = 0; m < 4; ++m) _Pragma("unroll") for (int n = 0; n < 2; ++n) _Pragma("unroll") for (int k = 0; k < 2; ++k) \
;         acc[ai][bj][m][n] = __builtin_amdgcn_mfma_f32_16x16x32_bf16(Bt[n][k], At[m][k], acc[ai][bj][m][n], 0, 0, 0); __builtin_amdgcn_s_setprio(0); } while (0)
; #define PG8_WAIT_V(n) asm volatile("s_waitcnt vmcnt(" #n ")" ::: "memory")
; #define PG8_WAIT_L(n) asm volatile("s_waitcnt lgkmcnt(" #n ")" ::: "memory")
; #define PG8_BAR __builtin_amdgcn_s_barrier()
; #define PG8_SCHED __builtin_amdgcn_sched_barrier(0)
; template <class Epi>
; DI void gemm_phase(LAS unsigned char* lds, const Gemm g, const StaticOrder& S, const Epi& E) {
;     ...
;             PG8_BAR; PG8_WAIT_L(0); PG8_MMA(0, 1, At, B1); PG8_BAR;
;             PG8_LDA(At, 1, 1); PG8_STAGE(PG8_SA(1, 0), a3);
;             PG8_BAR; PG8_WAIT_L(0); PG8_MMA(1, 0, At, B0); PG8_BAR; PG8_SCHED;
;             PG8_STAGE(PG8_SB(1, 1), b3 + hstep);
;             PG8_WAIT_V(6); PG8_BAR; PG8_MMA(1, 1, At, B1); PG8_BAR;
;     DI void operator()(const f32x4 (&acc)[2][2][4][2], const Unit& u, int wr, int wc, int fr, int fq) const {
;         const int row0 = u.pm * BM + wr * 64 + fr, col0 = u.pn * BM + wc * 16 + 4 * fq;
;         const bool rot = u.pn < 18;
; #pragma unroll
;         for (int ai = 0; ai < 2; ++ai)
; #pragma unroll
;             for (int m = 0; m < 4; ++m) { const int row = row0 + ai * HALF + m * 16; u16* rowp = O + (size_t)row * NQKV_DIL + col0;
;                 f32x4 c4 = (f32x4){1.f, 1.f, 1.f, 1.f}, s4 = (f32x4){0.f, 0.f, 0.f, 0.f};
;                 if (rot) { const int pos = row & (SEQ - 1); c4 = *(const f32x4*)(cs + pos * 64 + wc * 16 + 4 * fq); s4 = *(const f32x4*)(sn + pos * 64 + wc * 16 + 4 * fq); }
	v_mfma_f32_16x16x32_bf16 v[116:119], v[234:237], v[194:197], v[116:119]
	v_mfma_f32_16x16x32_bf16 v[112:115], v[242:245], v[194:197], v[112:115]
	v_mfma_f32_16x16x32_bf16 v[100:103], v[234:237], v[202:205], v[100:103]
	v_mfma_f32_16x16x32_bf16 v[96:99], v[242:245], v[202:205], v[96:99]
	v_mfma_f32_16x16x32_bf16 v[84:87], v[234:237], v[210:213], v[84:87]
	v_mfma_f32_16x16x32_bf16 v[80:83], v[242:245], v[210:213], v[80:83]
	v_mfma_f32_16x16x32_bf16 v[68:71], v[234:237], v[226:229], v[68:71]
	v_mfma_f32_16x16x32_bf16 v[64:67], v[242:245], v[226:229], v[64:67]
	v_mfma_f32_16x16x32_bf16 v[116:119], v[238:241], v[198:201], v[116:119]
	s_mov_b32 m0, s30
	v_mfma_f32_16x16x32_bf16 v[112:115], v[246:249], v[198:201], v[112:115]
	v_lshl_add_u64 v[140:141], v[218:219], 0, s[94:95]
	v_mfma_f32_16x16x32_bf16 v[100:103], v[238:241], v[206:209], v[100:103]
	v_mfma_f32_16x16x32_bf16 v[96:99], v[246:249], v[206:209], v[96:99]
	v_mfma_f32_16x16x32_bf16 v[84:87], v[238:241], v[214:217], v[84:87]
	v_mfma_f32_16x16x32_bf16 v[80:83], v[246:249], v[214:217], v[80:83]
	v_mfma_f32_16x16x32_bf16 v[68:71], v[238:241], v[230:233], v[68:71]
	v_mfma_f32_16x16x32_bf16 v[64:67], v[246:249], v[230:233], v[64:67]
	s_setprio 0
	s_barrier
	ds_read_b128 v[194:197], v189 offset:49152
	ds_read_b128 v[198:201], v189 offset:50176
	ds_read_b128 v[202:205], v189 offset:51200
	ds_read_b128 v[206:209], v189 offset:52224
	ds_read_b128 v[210:213], v189 offset:53248
	ds_read_b128 v[214:217], v189 offset:54272
	ds_read_b128 v[226:229], v189 offset:55296
	ds_read_b128 v[230:233], v189 offset:56320
	global_load_lds_dwordx4 v[140:141], off
	v_lshl_add_u64 v[140:141], v[250:251], 0, s[94:95]
	s_mov_b32 m0, s31
	s_nop 0
	global_load_lds_dwordx4 v[140:141], off
	s_waitcnt lgkmcnt(0)
	s_setprio 1
	s_barrier
	v_mfma_f32_16x16x32_bf16 v[60:63], v[128:131], v[194:197], v[60:63]
	v_mfma_f32_16x16x32_bf16 v[56:59], v[136:139], v[194:197], v[56:59]
	s_add_u32 s18, s18, 0x80080
	v_mfma_f32_16x16x32_bf16 v[44:47], v[128:131], v[202:205], v[44:47]
	s_addc_u32 s19, s19, 0
	v_mfma_f32_16x16x32_bf16 v[40:43], v[136:139], v[202:205], v[40:43]
	s_add_i32 s20, s20, s25
	v_mfma_f32_16x16x32_bf16 v[28:31], v[128:131], v[210:213], v[28:31]
	v_mfma_f32_16x16x32_bf16 v[24:27], v[136:139], v[210:213], v[24:27]
	v_mfma_f32_16x16x32_bf16 v[12:15], v[128:131], v[226:229], v[12:15]
	v_mfma_f32_16x16x32_bf16 v[8:11], v[136:139], v[226:229], v[8:11]
	v_mfma_f32_16x16x32_bf16 v[60:63], v[132:135], v[198:201], v[60:63]
	v_mfma_f32_16x16x32_bf16 v[56:59], v[190:193], v[198:201], v[56:59]
	v_mfma_f32_16x16x32_bf16 v[44:47], v[132:135], v[206:209], v[44:47]
	v_mfma_f32_16x16x32_bf16 v[40:43], v[190:193], v[206:209], v[40:43]
	v_mfma_f32_16x16x32_bf16 v[28:31], v[132:135], v[214:217], v[28:31]
	v_mfma_f32_16x16x32_bf16 v[24:27], v[190:193], v[214:217], v[24:27]
	v_mfma_f32_16x16x32_bf16 v[12:15], v[132:135], v[230:233], v[12:15]
	v_mfma_f32_16x16x32_bf16 v[8:11], v[190:193], v[230:233], v[8:11]
	s_setprio 0
	s_barrier
	v_lshl_add_u64 v[128:129], s[18:19], 0, v[144:145]
	s_mov_b32 m0, s20
	s_nop 0
	global_load_lds_dwordx4 v[128:129], off
	v_lshl_add_u64 v[128:129], s[18:19], 0, v[142:143]
	s_add_i32 m0, s20, 0x2000
	s_nop 0
	global_load_lds_dwordx4 v[128:129], off
	s_waitcnt vmcnt(6)
	s_setprio 1
	s_barrier
	v_mfma_f32_16x16x32_bf16 v[52:55], v[234:237], v[194:197], v[52:55]
	v_mfma_f32_16x16x32_bf16 v[48:51], v[242:245], v[194:197], v[48:51]
	v_mfma_f32_16x16x32_bf16 v[36:39], v[234:237], v[202:205], v[36:39]
	v_mfma_f32_16x16x32_bf16 v[32:35], v[242:245], v[202:205], v[32:35]
	v_mfma_f32_16x16x32_bf16 v[20:23], v[234:237], v[210:213], v[20:23]
	v_mfma_f32_16x16x32_bf16 v[16:19], v[242:245], v[210:213], v[16:19]
	v_mfma_f32_16x16x32_bf16 v[4:7], v[234:237], v[226:229], v[4:7]
	v_mfma_f32_16x16x32_bf16 v[0:3], v[242:245], v[226:229], v[0:3]
	v_mfma_f32_16x16x32_bf16 v[52:55], v[238:241], v[198:201], v[52:55]
	s_add_i32 s36, s36, 2
	v_mfma_f32_16x16x32_bf16 v[48:51], v[246:249], v[198:201], v[48:51]
	s_add_u32 s8, s8, 0x100
	v_mfma_f32_16x16x32_bf16 v[36:39], v[238:241], v[206:209], v[36:39]
	s_addc_u32 s9, s9, 0
	v_mfma_f32_16x16x32_bf16 v[32:35], v[246:249], v[206:209], v[32:35]
	s_add_u32 s33, s33, 0x100
	v_mfma_f32_16x16x32_bf16 v[20:23], v[238:241], v[214:217], v[20:23]
	s_addc_u32 s35, s35, 0
	v_mfma_f32_16x16x32_bf16 v[16:19], v[246:249], v[214:217], v[16:19]
	s_cmp_gt_u32 s36, 29
	v_mfma_f32_16x16x32_bf16 v[4:7], v[238:241], v[230:233], v[4:7]
	v_mfma_f32_16x16x32_bf16 v[0:3], v[246:249], v[230:233], v[0:3]
	s_setprio 0
	s_barrier
	s_cbranch_scc0 .LBB0_202
	s_cmp_lt_i32 s2, 18
	v_lshl_add_u32 v190, s3, 8, v186
	v_mov_b32_e32 v128, 1.0
	v_mov_b32_e32 v132, 0
	s_cselect_b64 s[18:19], -1, 0
	s_cmp_gt_i32 s2, 17
	v_mov_b32_e32 v134, 0
	v_mov_b32_e32 v135, 0
	v_mov_b32_e32 v136, 0
	v_mov_b32_e32 v137, 0
	v_mov_b32_e32 v138, 1.0
	v_mov_b32_e32 v139, 1.0
	v_mov_b32_e32 v140, 1.0
	v_mov_b32_e32 v141, 1.0
	s_cbranch_scc1 .LBB0_205
	v_lshlrev_b32_e32 v129, 8, v190
	v_and_b32_e32 v158, 0xfcf00, v129
	v_lshl_add_u64 v[130:131], v[146:147], 0, v[158:159]
	v_lshl_add_u64 v[134:135], v[148:149], 0, v[158:159]
	global_load_dwordx4 v[138:141], v[130:131], off
	s_nop 0
	global_load_dwordx4 v[134:137], v[134:135], off

; #define PG8_STAGE(bufoff, gbase) do { _Pragma("unroll") for (int _i = 0; _i < 2; ++_i) \
;         __builtin_amdgcn_global_load_lds((const unsigned*)((const char*)(gbase) + voff[_i]), (LAS unsigned*)(lds + (bufoff) + ldsw + _i * 8192), 16, 0, 0); } while (0)
; #define PG8_LDA(dst, b, h) do { _Pragma("unroll") for (int m = 0; m < 4; ++m) _Pragma("unroll") for (int k = 0; k < 2; ++k) dst[m][k] = *(const LAS bf16x8*)(lds + PG8_SA(b, h) + aoff + m * 2048 + k * 1024); } while (0)
; #define PG8_LDB(dst, b, h) do { _Pragma("unroll") for (int n = 0; n < 2; ++n) _Pragma("unroll") for (int k = 0; k < 2; ++k) dst[n][k] = *(const LAS bf16x8*)(lds + PG8_SB(b, h) + boff + n * 2048 + k * 1024); } while (0)
; #define PG8_MMA(ai, bj, At, Bt) do { __builtin_amdgcn_s_setprio(1); _Pragma("unroll") for (int m = 0; m < 4; ++m) _Pragma("unroll") for (int n = 0; n < 2; ++n) _Pragma("unroll") for (int k = 0; k < 2; ++k) \
;         acc[ai][bj][m][n] = __builtin_amdgcn_mfma_f32_16x16x32_bf16(Bt[n][k], At[m][k], acc[ai][bj][m][n], 0, 0, 0); __builtin_amdgcn_s_setprio(0); } while (0)
; #define PG8_WAIT_L(n) asm volatile("s_waitcnt lgkmcnt(" #n ")" ::: "memory")
; #define PG8_BAR __builtin_amdgcn_s_barrier()
; #define PG8_SCHED __builtin_amdgcn_sched_barrier(0)
; template <class Epi>
; DI void gemm_phase(LAS unsigned char* lds, const Gemm g, const StaticOrder& S, const Epi& E) {
;     ...
;             const bool last = (t == nt - 2);
;             const char* a1 = cA + (size_t)(t + 1) * kstep;
;             const char* a2 = last ? nA : cA + (size_t)(t + 2) * kstep; const char* b2 = last ? nB : cB + (size_t)(t + 2) * kstep;
;             const char* a3 = a2 + kstep; const char* b3 = b2 + kstep;
;             PG8_LDB(B0, 0, 0); PG8_SCHED; PG8_LDA(At, 0, 0); PG8_STAGE(PG8_SA(1, 1), a1 + hstep);
;             PG8_WAIT_L(8); PG8_BAR; PG8_WAIT_L(0); PG8_MMA(0, 0, At, B0); PG8_BAR; PG8_SCHED;
;             PG8_LDB(B1, 0, 1); PG8_STAGE(PG8_SB(0, 0), b2);
;             PG8_BAR; PG8_WAIT_L(0); PG8_MMA(0, 1, At, B1); PG8_BAR;
;             PG8_LDA(At, 0, 1); PG8_STAGE(PG8_SA(0, 0), a2);
;             PG8_BAR; PG8_WAIT_L(0); PG8_MMA(1, 0, At, B0); PG8_BAR; PG8_SCHED;
.LBB0_231:
	s_add_u32 s18, s16, 0xfff80080
	s_addc_u32 s19, s17, -1
	s_add_i32 s37, 0, 0x10000
	v_add_u32_e32 v150, s37, v135
	ds_read_b128 v[138:141], v150
	ds_read_b128 v[142:145], v150 offset:1024
	ds_read_b128 v[146:149], v150 offset:2048
	ds_read_b128 v[150:153], v150 offset:3072
	s_cmp_eq_u32 s36, 28
	s_cselect_b32 s21, s4, s19
	s_cselect_b32 s20, s5, s18
	s_cselect_b32 s19, s9, s35
	s_cselect_b32 s18, s11, s34
	v_lshl_add_u64 v[154:155], s[16:17], 0, v[130:131]
	s_add_i32 m0, s24, 0xc000
	ds_read_b128 v[186:189], v137
	ds_read_b128 v[190:193], v137 offset:1024
	ds_read_b128 v[194:197], v137 offset:2048
	ds_read_b128 v[198:201], v137 offset:3072
	ds_read_b128 v[202:205], v137 offset:4096
	ds_read_b128 v[206:209], v137 offset:5120
	ds_read_b128 v[210:213], v137 offset:6144
	ds_read_b128 v[214:217], v137 offset:7168
	global_load_lds_dwordx4 v[154:155], off
	v_lshl_add_u64 v[154:155], s[16:17], 0, v[132:133]
	s_add_i32 m0, s24, 0xe000
	s_nop 0
	global_load_lds_dwordx4 v[154:155], off
	s_waitcnt lgkmcnt(8)
	s_setprio 1
	s_barrier
	s_waitcnt lgkmcnt(0)
	v_mfma_f32_16x16x32_bf16 v[124:127], v[138:141], v[186:189], v[124:127]
	v_mfma_f32_16x16x32_bf16 v[120:123], v[146:149], v[186:189], v[120:123]
	s_add_i32 s40, 0, 0x14000
	v_mfma_f32_16x16x32_bf16 v[116:119], v[138:141], v[194:197], v[116:119]
	v_add_u32_e32 v154, s40, v135
	v_mfma_f32_16x16x32_bf16 v[112:115], v[146:149], v[194:197], v[112:115]
	s_add_i32 s37, s37, s23
	v_mfma_f32_16x16x32_bf16 v[100:103], v[138:141], v[202:205], v[100:103]
	v_mfma_f32_16x16x32_bf16 v[96:99], v[146:149], v[202:205], v[96:99]
	v_mfma_f32_16x16x32_bf16 v[84:87], v[138:141], v[210:213], v[84:87]
	v_mfma_f32_16x16x32_bf16 v[80:83], v[146:149], v[210:213], v[80:83]
	v_mfma_f32_16x16x32_bf16 v[124:127], v[142:145], v[190:193], v[124:127]
	v_mfma_f32_16x16x32_bf16 v[120:123], v[150:153], v[190:193], v[120:123]
	v_mfma_f32_16x16x32_bf16 v[116:119], v[142:145], v[198:201], v[116:119]
	v_mfma_f32_16x16x32_bf16 v[112:115], v[150:153], v[198:201], v[112:115]
	v_mfma_f32_16x16x32_bf16 v[100:103], v[142:145], v[206:209], v[100:103]
	v_mfma_f32_16x16x32_bf16 v[96:99], v[150:153], v[206:209], v[96:99]
	v_mfma_f32_16x16x32_bf16 v[84:87], v[142:145], v[214:217], v[84:87]
	v_mfma_f32_16x16x32_bf16 v[80:83], v[150:153], v[214:217], v[80:83]
	s_setprio 0
	s_barrier
	ds_read_b128 v[226:229], v154
	ds_read_b128 v[230:233], v154 offset:1024
	ds_read_b128 v[234:237], v154 offset:2048
	ds_read_b128 v[238:241], v154 offset:3072
	v_lshl_add_u64 v[154:155], s[18:19], 0, v[158:159]
	s_mov_b32 m0, s37
	v_lshl_add_u64 v[218:219], s[18:19], 0, v[128:129]
	global_load_lds_dwordx4 v[154:155], off
	s_add_i32 m0, s37, 0x2000
	s_nop 0
	global_load_lds_dwordx4 v[218:219], off
	s_waitcnt lgkmcnt(0)
	s_setprio 1
	s_barrier
	v_mfma_f32_16x16x32_bf16 v[108:111], v[226:229], v[186:189], v[108:111]
	v_mfma_f32_16x16x32_bf16 v[104:107], v[234:237], v[186:189], v[104:107]
	v_mfma_f32_16x16x32_bf16 v[92:95], v[226:229], v[194:197], v[92:95]
	v_mfma_f32_16x16x32_bf16 v[88:91], v[234:237], v[194:197], v[88:91]
	v_mfma_f32_16x16x32_bf16 v[76:79], v[226:229], v[202:205], v[76:79]
	v_mfma_f32_16x16x32_bf16 v[72:75], v[234:237], v[202:205], v[72:75]
	v_mfma_f32_16x16x32_bf16 v[68:71], v[226:229], v[210:213], v[68:71]
	v_mfma_f32_16x16x32_bf16 v[64:67], v[234:237], v[210:213], v[64:67]
	v_mfma_f32_16x16x32_bf16 v[108:111], v[230:233], v[190:193], v[108:111]
	s_mov_b32 m0, s24
	v_mfma_f32_16x16x32_bf16 v[104:107], v[238:241], v[190:193], v[104:107]
	v_lshl_add_u64 v[242:243], s[20:21], 0, v[158:159]
	v_mfma_f32_16x16x32_bf16 v[92:95], v[230:233], v[198:201], v[92:95]
	v_mfma_f32_16x16x32_bf16 v[88:91], v[238:241], v[198:201], v[88:91]
	v_mfma_f32_16x16x32_bf16 v[76:79], v[230:233], v[206:209], v[76:79]
	v_mfma_f32_16x16x32_bf16 v[72:75], v[238:241], v[206:209], v[72:75]
	v_mfma_f32_16x16x32_bf16 v[68:71], v[230:233], v[214:217], v[68:71]
	v_mfma_f32_16x16x32_bf16 v[64:67], v[238:241], v[214:217], v[64:67]
	s_setprio 0
	s_barrier
	ds_read_b128 v[186:189], v137 offset:16384
	ds_read_b128 v[190:193], v137 offset:17408
	ds_read_b128 v[194:197], v137 offset:18432
	ds_read_b128 v[198:201], v137 offset:19456
	ds_read_b128 v[202:205], v137 offset:20480
	ds_read_b128 v[206:209], v137 offset:21504
	ds_read_b128 v[210:213], v137 offset:22528
	ds_read_b128 v[214:217], v137 offset:23552
	global_load_lds_dwordx4 v[242:243], off
	v_lshl_add_u64 v[244:245], s[20:21], 0, v[128:129]
	s_mov_b32 m0, s25
	s_nop 0
	global_load_lds_dwordx4 v[244:245], off
	s_waitcnt lgkmcnt(0)
	s_setprio 1
	s_barrier
	v_mfma_f32_16x16x32_bf16 v[60:63], v[138:141], v[186:189], v[60:63]
	v_mfma_f32_16x16x32_bf16 v[56:59], v[146:149], v[186:189], v[56:59]
	s_add_u32 s38, s18, 0x80000
	v_mfma_f32_16x16x32_bf16 v[52:55], v[138:141], v[194:197], v[52:55]
	s_addc_u32 s39, s19, 0
	v_mfma_f32_16x16x32_bf16 v[48:51], v[146:149], v[194:197], v[48:51]
	s_add_i32 s37, s40, s23
	v_mfma_f32_16x16x32_bf16 v[36:39], v[138:141], v[202:205], v[36:39]
	v_mfma_f32_16x16x32_bf16 v[32:35], v[146:149], v[202:205], v[32:35]
	v_mfma_f32_16x16x32_bf16 v[20:23], v[138:141], v[210:213], v[20:23]
	v_mfma_f32_16x16x32_bf16 v[16:19], v[146:149], v[210:213], v[16:19]
	v_mfma_f32_16x16x32_bf16 v[60:63], v[142:145], v[190:193], v[60:63]
	v_mfma_f32_16x16x32_bf16 v[56:59], v[150:153], v[190:193], v[56:59]
	v_mfma_f32_16x16x32_bf16 v[52:55], v[142:145], v[198:201], v[52:55]
	v_mfma_f32_16x16x32_bf16 v[48:51], v[150:153], v[198:201], v[48:51]
	v_mfma_f32_16x16x32_bf16 v[36:39], v[142:145], v[206:209], v[36:39]
	v_mfma_f32_16x16x32_bf16 v[32:35], v[150:153], v[206:209], v[32:35]
	v_mfma_f32_16x16x32_bf16 v[20:23], v[142:145], v[214:217], v[20:23]
	v_mfma_f32_16x16x32_bf16 v[16:19], v[150:153], v[214:217], v[16:19]
	s_setprio 0
	s_barrier
; #define PG8_STAGE(bufoff, gbase) do { _Pragma("unroll") for (int _i = 0; _i < 2; ++_i) \
;         __builtin_amdgcn_global_load_lds((const unsigned*)((const char*)(gbase) + voff[_i]), (LAS unsigned*)(lds + (bufoff) + ldsw + _i * 8192), 16, 0, 0); } while (0)
; #define PG8_LDA(dst, b, h) do { _Pragma("unroll") for (int m = 0; m < 4; ++m) _Pragma("unroll") for (int k = 0; k < 2; ++k) dst[m][k] = *(const LAS bf16x8*)(lds + PG8_SA(b, h) + aoff + m * 2048 + k * 1024); } while (0)
; #define PG8_LDB(dst, b, h) do { _Pragma("unroll") for (int n = 0; n < 2; ++n) _Pragma("unroll") for (int k = 0; k < 2; ++k) dst[n][k] = *(const LAS bf16x8*)(lds + PG8_SB(b, h) + boff + n * 2048 + k * 1024); } while (0)
; #define PG8_MMA(ai, bj, At, Bt) do { __builtin_amdgcn_s_setprio(1); _Pragma("unroll") for (int m = 0; m < 4; ++m) _Pragma("unroll") for (int n = 0; n < 2; ++n) _Pragma("unroll") for (int k = 0; k < 2; ++k) \
;         acc[ai][bj][m][n] = __builtin_amdgcn_mfma_f32_16x16x32_bf16(Bt[n][k], At[m][k], acc[ai][bj][m][n], 0, 0, 0); __builtin_amdgcn_s_setprio(0); } while (0)
; #define PG8_WAIT_V(n) asm volatile("s_waitcnt vmcnt(" #n ")" ::: "memory")
; #define PG8_WAIT_L(n) asm volatile("s_waitcnt lgkmcnt(" #n ")" ::: "memory")
; #define PG8_BAR __builtin_amdgcn_s_barrier()
; #define PG8_SCHED __builtin_amdgcn_sched_barrier(0)
; template <class Epi>
; DI void gemm_phase(LAS unsigned char* lds, const Gemm g, const StaticOrder& S, const Epi& E) {
;     ...
;             PG8_STAGE(PG8_SB(0, 1), b2 + hstep);
;             PG8_WAIT_V(6); PG8_BAR; PG8_MMA(1, 1, At, B1); PG8_BAR;
;             PG8_LDB(B0, 1, 0); PG8_SCHED; PG8_LDA(At, 1, 0); PG8_STAGE(PG8_SA(0, 1), a2 + hstep);
;             PG8_WAIT_L(8); PG8_BAR; PG8_WAIT_L(0); PG8_MMA(0, 0, At, B0); PG8_BAR; PG8_SCHED;
;             PG8_LDB(B1, 1, 1); PG8_STAGE(PG8_SB(1, 0), b3);
;             PG8_BAR; PG8_WAIT_L(0); PG8_MMA(0, 1, At, B1); PG8_BAR;
;             PG8_LDA(At, 1, 1); PG8_STAGE(PG8_SA(1, 0), a3);
	v_lshl_add_u64 v[138:139], s[38:39], 0, v[158:159]
	s_mov_b32 m0, s37
	s_nop 0
	global_load_lds_dwordx4 v[138:139], off
	v_lshl_add_u64 v[138:139], s[38:39], 0, v[128:129]
	s_add_i32 m0, s37, 0x2000
	s_nop 0
	global_load_lds_dwordx4 v[138:139], off
	s_waitcnt vmcnt(6)
	s_setprio 1
	s_barrier
	v_mfma_f32_16x16x32_bf16 v[44:47], v[226:229], v[186:189], v[44:47]
	v_mfma_f32_16x16x32_bf16 v[40:43], v[234:237], v[186:189], v[40:43]
	v_mfma_f32_16x16x32_bf16 v[28:31], v[226:229], v[194:197], v[28:31]
	v_mfma_f32_16x16x32_bf16 v[24:27], v[234:237], v[194:197], v[24:27]
	v_mfma_f32_16x16x32_bf16 v[12:15], v[226:229], v[202:205], v[12:15]
	v_mfma_f32_16x16x32_bf16 v[8:11], v[234:237], v[202:205], v[8:11]
	v_mfma_f32_16x16x32_bf16 v[4:7], v[226:229], v[210:213], v[4:7]
	v_mfma_f32_16x16x32_bf16 v[0:3], v[234:237], v[210:213], v[0:3]
	v_mfma_f32_16x16x32_bf16 v[44:47], v[230:233], v[190:193], v[44:47]
	s_add_i32 s37, 0, 0x18000
	v_mfma_f32_16x16x32_bf16 v[40:43], v[238:241], v[190:193], v[40:43]
	v_add_u32_e32 v150, s37, v135
	v_mfma_f32_16x16x32_bf16 v[28:31], v[230:233], v[198:201], v[28:31]
	v_mfma_f32_16x16x32_bf16 v[24:27], v[238:241], v[198:201], v[24:27]
	v_mfma_f32_16x16x32_bf16 v[12:15], v[230:233], v[206:209], v[12:15]
	v_mfma_f32_16x16x32_bf16 v[8:11], v[238:241], v[206:209], v[8:11]
	v_mfma_f32_16x16x32_bf16 v[4:7], v[230:233], v[214:217], v[4:7]
	v_mfma_f32_16x16x32_bf16 v[0:3], v[238:241], v[214:217], v[0:3]
	s_setprio 0
	s_barrier
	ds_read_b128 v[138:141], v150
	ds_read_b128 v[142:145], v150 offset:1024
	ds_read_b128 v[146:149], v150 offset:2048
	ds_read_b128 v[150:153], v150 offset:3072
	s_add_u32 s20, s20, 0x80000
	s_addc_u32 s21, s21, 0
	s_mov_b32 m0, s26
	v_lshl_add_u64 v[226:227], s[20:21], 0, v[158:159]
	ds_read_b128 v[186:189], v137 offset:32768
	ds_read_b128 v[190:193], v137 offset:33792
	ds_read_b128 v[194:197], v137 offset:34816
	ds_read_b128 v[198:201], v137 offset:35840
	ds_read_b128 v[202:205], v137 offset:36864
	ds_read_b128 v[206:209], v137 offset:37888
	ds_read_b128 v[210:213], v137 offset:38912
	ds_read_b128 v[214:217], v137 offset:39936
	global_load_lds_dwordx4 v[226:227], off
	v_lshl_add_u64 v[226:227], s[20:21], 0, v[128:129]
	s_mov_b32 m0, s27
	s_nop 0
	global_load_lds_dwordx4 v[226:227], off
	s_waitcnt lgkmcnt(8)
	s_setprio 1
	s_barrier
	s_waitcnt lgkmcnt(0)
	v_mfma_f32_16x16x32_bf16 v[124:127], v[138:141], v[186:189], v[124:127]
	v_mfma_f32_16x16x32_bf16 v[120:123], v[146:149], v[186:189], v[120:123]
	s_add_i32 s20, 0, 0x1c000
	v_mfma_f32_16x16x32_bf16 v[116:119], v[138:141], v[194:197], v[116:119]
	s_add_i32 s21, s37, s23
	v_mfma_f32_16x16x32_bf16 v[112:115], v[146:149], v[194:197], v[112:115]
	v_add_u32_e32 v220, s20, v135
	v_mfma_f32_16x16x32_bf16 v[100:103], v[138:141], v[202:205], v[100:103]
	v_lshl_add_u64 v[154:155], v[154:155], 0, s[94:95]
	v_mfma_f32_16x16x32_bf16 v[96:99], v[146:149], v[202:205], v[96:99]
	s_mov_b32 m0, s21
	v_mfma_f32_16x16x32_bf16 v[84:87], v[138:141], v[210:213], v[84:87]
	v_mfma_f32_16x16x32_bf16 v[80:83], v[146:149], v[210:213], v[80:83]
	v_mfma_f32_16x16x32_bf16 v[124:127], v[142:145], v[190:193], v[124:127]
	v_mfma_f32_16x16x32_bf16 v[120:123], v[150:153], v[190:193], v[120:123]
	v_mfma_f32_16x16x32_bf16 v[116:119], v[142:145], v[198:201], v[116:119]
	v_mfma_f32_16x16x32_bf16 v[112:115], v[150:153], v[198:201], v[112:115]
	v_mfma_f32_16x16x32_bf16 v[100:103], v[142:145], v[206:209], v[100:103]
	v_mfma_f32_16x16x32_bf16 v[96:99], v[150:153], v[206:209], v[96:99]
	v_mfma_f32_16x16x32_bf16 v[84:87], v[142:145], v[214:217], v[84:87]
	v_mfma_f32_16x16x32_bf16 v[80:83], v[150:153], v[214:217], v[80:83]
	s_setprio 0
	s_barrier
	ds_read_b128 v[226:229], v220
	ds_read_b128 v[230:233], v220 offset:1024
	ds_read_b128 v[234:237], v220 offset:2048
	ds_read_b128 v[238:241], v220 offset:3072
	global_load_lds_dwordx4 v[154:155], off
	v_lshl_add_u64 v[154:155], v[218:219], 0, s[94:95]
	s_add_i32 m0, s21, 0x2000
	s_nop 0
	global_load_lds_dwordx4 v[154:155], off
	s_waitcnt lgkmcnt(0)
	s_setprio 1
	s_barrier
	v_mfma_f32_16x16x32_bf16 v[108:111], v[226:229], v[186:189], v[108:111]
	v_mfma_f32_16x16x32_bf16 v[104:107], v[234:237], v[186:189], v[104:107]
	v_mfma_f32_16x16x32_bf16 v[92:95], v[226:229], v[194:197], v[92:95]
	v_mfma_f32_16x16x32_bf16 v[88:91], v[234:237], v[194:197], v[88:91]
	v_mfma_f32_16x16x32_bf16 v[76:79], v[226:229], v[202:205], v[76:79]
	v_mfma_f32_16x16x32_bf16 v[72:75], v[234:237], v[202:205], v[72:75]
	v_mfma_f32_16x16x32_bf16 v[68:71], v[226:229], v[210:213], v[68:71]
	v_mfma_f32_16x16x32_bf16 v[64:67], v[234:237], v[210:213], v[64:67]
	v_mfma_f32_16x16x32_bf16 v[108:111], v[230:233], v[190:193], v[108:111]
	s_mov_b32 m0, s28
	v_mfma_f32_16x16x32_bf16 v[104:107], v[238:241], v[190:193], v[104:107]
	v_lshl_add_u64 v[154:155], v[242:243], 0, s[94:95]
	v_mfma_f32_16x16x32_bf16 v[92:95], v[230:233], v[198:201], v[92:95]
	v_mfma_f32_16x16x32_bf16 v[88:91], v[238:241], v[198:201], v[88:91]
	v_mfma_f32_16x16x32_bf16 v[76:79], v[230:233], v[206:209], v[76:79]
	v_mfma_f32_16x16x32_bf16 v[72:75], v[238:241], v[206:209], v[72:75]
	v_mfma_f32_16x16x32_bf16 v[68:71], v[230:233], v[214:217], v[68:71]
	v_mfma_f32_16x16x32_bf16 v[64:67], v[238:241], v[214:217], v[64:67]
	s_setprio 0
	s_barrier
	ds_read_b128 v[186:189], v137 offset:49152
	ds_read_b128 v[190:193], v137 offset:50176
	ds_read_b128 v[194:197], v137 offset:51200
	ds_read_b128 v[198:201], v137 offset:52224
	ds_read_b128 v[202:205], v137 offset:53248
	ds_read_b128 v[206:209], v137 offset:54272
	ds_read_b128 v[210:213], v137 offset:55296
	ds_read_b128 v[214:217], v137 offset:56320
	global_load_lds_dwordx4 v[154:155], off
	v_lshl_add_u64 v[154:155], v[244:245], 0, s[94:95]
	s_mov_b32 m0, s29
	s_nop 0
	global_load_lds_dwordx4 v[154:155], off
	s_waitcnt lgkmcnt(0)
	s_setprio 1
	s_barrier
; #define PG8_STAGE(bufoff, gbase) do { _Pragma("unroll") for (int _i = 0; _i < 2; ++_i) \
;         __builtin_amdgcn_global_load_lds((const unsigned*)((const char*)(gbase) + voff[_i]), (LAS unsigned*)(lds + (bufoff) + ldsw + _i * 8192), 16, 0, 0); } while (0)
; #define PG8_MMA(ai, bj, At, Bt) do { __builtin_amdgcn_s_setprio(1); _Pragma("unroll") for (int m = 0; m < 4; ++m) _Pragma("unroll") for (int n = 0; n < 2; ++n) _Pragma("unroll") for (int k = 0; k < 2; ++k) \
;         acc[ai][bj][m][n] = __builtin_amdgcn_mfma_f32_16x16x32_bf16(Bt[n][k], At[m][k], acc[ai][bj][m][n], 0, 0, 0); __builtin_amdgcn_s_setprio(0); } while (0)
; #define PG8_WAIT_V(n) asm volatile("s_waitcnt vmcnt(" #n ")" ::: "memory")
; #define PG8_WAIT_L(n) asm volatile("s_waitcnt lgkmcnt(" #n ")" ::: "memory")
; #define PG8_BAR __builtin_amdgcn_s_barrier()
; #define PG8_SCHED __builtin_amdgcn_sched_barrier(0)
; template <class Epi>
; DI void gemm_phase(LAS unsigned char* lds, const Gemm g, const StaticOrder& S, const Epi& E) {
;     ...
;             PG8_BAR; PG8_WAIT_L(0); PG8_MMA(1, 0, At, B0); PG8_BAR; PG8_SCHED;
;             PG8_STAGE(PG8_SB(1, 1), b3 + hstep);
;             PG8_WAIT_V(6); PG8_BAR; PG8_MMA(1, 1, At, B1); PG8_BAR;
	v_mfma_f32_16x16x32_bf16 v[60:63], v[138:141], v[186:189], v[60:63]
	v_mfma_f32_16x16x32_bf16 v[56:59], v[146:149], v[186:189], v[56:59]
	s_add_u32 s18, s18, 0x80080
	v_mfma_f32_16x16x32_bf16 v[52:55], v[138:141], v[194:197], v[52:55]
	s_addc_u32 s19, s19, 0
	v_mfma_f32_16x16x32_bf16 v[48:51], v[146:149], v[194:197], v[48:51]
	s_add_i32 s20, s20, s23
	v_mfma_f32_16x16x32_bf16 v[36:39], v[138:141], v[202:205], v[36:39]
	v_mfma_f32_16x16x32_bf16 v[32:35], v[146:149], v[202:205], v[32:35]
	v_mfma_f32_16x16x32_bf16 v[20:23], v[138:141], v[210:213], v[20:23]
	v_mfma_f32_16x16x32_bf16 v[16:19], v[146:149], v[210:213], v[16:19]
	v_mfma_f32_16x16x32_bf16 v[60:63], v[142:145], v[190:193], v[60:63]
	v_mfma_f32_16x16x32_bf16 v[56:59], v[150:153], v[190:193], v[56:59]
	v_mfma_f32_16x16x32_bf16 v[52:55], v[142:145], v[198:201], v[52:55]
	v_mfma_f32_16x16x32_bf16 v[48:51], v[150:153], v[198:201], v[48:51]
	v_mfma_f32_16x16x32_bf16 v[36:39], v[142:145], v[206:209], v[36:39]
	v_mfma_f32_16x16x32_bf16 v[32:35], v[150:153], v[206:209], v[32:35]
	v_mfma_f32_16x16x32_bf16 v[20:23], v[142:145], v[214:217], v[20:23]
	v_mfma_f32_16x16x32_bf16 v[16:19], v[150:153], v[214:217], v[16:19]
	s_setprio 0
	s_barrier
	v_lshl_add_u64 v[138:139], s[18:19], 0, v[158:159]
	s_mov_b32 m0, s20
	s_nop 0
	global_load_lds_dwordx4 v[138:139], off
	v_lshl_add_u64 v[138:139], s[18:19], 0, v[128:129]
	s_add_i32 m0, s20, 0x2000
	s_nop 0
	global_load_lds_dwordx4 v[138:139], off
	s_waitcnt vmcnt(6)
	s_setprio 1
	s_barrier
	v_mfma_f32_16x16x32_bf16 v[44:47], v[226:229], v[186:189], v[44:47]
	v_mfma_f32_16x16x32_bf16 v[40:43], v[234:237], v[186:189], v[40:43]
	v_mfma_f32_16x16x32_bf16 v[28:31], v[226:229], v[194:197], v[28:31]
	v_mfma_f32_16x16x32_bf16 v[24:27], v[234:237], v[194:197], v[24:27]
	v_mfma_f32_16x16x32_bf16 v[12:15], v[226:229], v[202:205], v[12:15]
	v_mfma_f32_16x16x32_bf16 v[8:11], v[234:237], v[202:205], v[8:11]
	v_mfma_f32_16x16x32_bf16 v[4:7], v[226:229], v[210:213], v[4:7]
	v_mfma_f32_16x16x32_bf16 v[0:3], v[234:237], v[210:213], v[0:3]
	v_mfma_f32_16x16x32_bf16 v[44:47], v[230:233], v[190:193], v[44:47]
	s_add_i32 s36, s36, 2
	v_mfma_f32_16x16x32_bf16 v[40:43], v[238:241], v[190:193], v[40:43]
	s_add_u32 s16, s16, 0x100
	v_mfma_f32_16x16x32_bf16 v[28:31], v[230:233], v[198:201], v[28:31]
	s_addc_u32 s17, s17, 0
	v_mfma_f32_16x16x32_bf16 v[24:27], v[238:241], v[198:201], v[24:27]
	s_add_u32 s34, s34, 0x100
	v_mfma_f32_16x16x32_bf16 v[12:15], v[230:233], v[206:209], v[12:15]
	s_addc_u32 s35, s35, 0
	v_mfma_f32_16x16x32_bf16 v[8:11], v[238:241], v[206:209], v[8:11]
	s_cmp_gt_u32 s36, 29
	v_mfma_f32_16x16x32_bf16 v[4:7], v[230:233], v[214:217], v[4:7]
	v_mfma_f32_16x16x32_bf16 v[0:3], v[238:241], v[214:217], v[0:3]
	s_setprio 0
	s_barrier
	s_cbranch_scc0 .LBB0_231
; #define PG8_WAIT_V(n) asm volatile("s_waitcnt vmcnt(" #n ")" ::: "memory")
; #define PG8_BAR __builtin_amdgcn_s_barrier()
; template <class Epi>
; DI void gemm_phase(LAS unsigned char* lds, const Gemm g, const StaticOrder& S, const Epi& E) {
;     ...
;         E(acc, cur, wr, wc, fr, fq);
;         if (!has_next) break;
; #pragma unroll
;         for (int a = 0; a < 2; ++a)
; #pragma unroll
;             for (int b = 0; b < 2; ++b)
; #pragma unroll
;                 for (int m = 0; m < 4; ++m)
; #pragma unroll
;                     for (int n = 0; n < 2; ++n) acc[a][b][m][n] = (f32x4){0.f, 0.f, 0.f, 0.f};
;         cur = nxt; cA = nA; cB = nB; ++ui;
;     }
;     PG8_WAIT_V(0);
;     if (wr == 0) PG8_BAR;
;     PG8_BAR;
;     DI void operator()(const f32x4 (&acc)[2][2][4][2], const Unit& u, int wr, int wc, int fr, int fq) const {
;         const int row0 = u.pm * BM + wr * 64 + fr, col0 = u.pn * BM + wc * 32 + 8 * fq;
; #pragma unroll
;         for (int ai = 0; ai < 2; ++ai)
; #pragma unroll
;             for (int m = 0; m < 4; ++m) { u16* rowp = O + (size_t)(row0 + ai * HALF + m * 16) * ldc + col0;
; #pragma unroll
;                 for (int bj = 0; bj < 2; ++bj) { const f32x4 v0 = acc[ai][bj][m][0], v1 = acc[ai][bj][m][1];
;                     *(u32x4*)(rowp + bj * HALF) = (u32x4){pk(v0[0], v0[1]), pk(v0[2], v0[3]), pk(v1[0], v1[1]), pk(v1[2], v1[3])}; } }
	v_lshl_add_u32 v144, s33, 8, v134
	v_lshl_or_b32 v138, s31, 8, v136
	v_ashrrev_i32_e32 v139, 31, v138
	v_mov_b64_e32 v[140:141], s[50:51]
	s_movk_i32 s9, 0x3000
	v_cvt_pk_bf16_f32 v68, v68, v69
	v_cvt_pk_bf16_f32 v69, v70, v71
	v_cvt_pk_bf16_f32 v70, v64, v65
	v_add_u32_e32 v64, 0x80, v144
	v_mad_i64_i32 v[142:143], s[4:5], v144, s9, v[140:141]
	v_lshlrev_b64 v[138:139], 1, v[138:139]
	v_cvt_pk_bf16_f32 v108, v108, v109
	v_cvt_pk_bf16_f32 v109, v110, v111
	v_cvt_pk_bf16_f32 v110, v104, v105
	v_or_b32_e32 v104, 16, v144
	v_mad_i64_i32 v[64:65], s[4:5], v64, s9, v[140:141]
	v_cvt_pk_bf16_f32 v44, v44, v45
	v_cvt_pk_bf16_f32 v45, v46, v47
	v_cvt_pk_bf16_f32 v46, v40, v41
	v_add_u32_e32 v40, 0x90, v144
	v_lshl_add_u64 v[142:143], v[142:143], 0, v[138:139]
	v_cvt_pk_bf16_f32 v111, v106, v107
	v_mad_i64_i32 v[104:105], s[4:5], v104, s9, v[140:141]
	v_cvt_pk_bf16_f32 v92, v92, v93
	v_cvt_pk_bf16_f32 v93, v94, v95
	v_cvt_pk_bf16_f32 v94, v88, v89
	v_or_b32_e32 v88, 32, v144
	v_lshl_add_u64 v[64:65], v[64:65], 0, v[138:139]
	v_cvt_pk_bf16_f32 v47, v42, v43
	v_mad_i64_i32 v[40:41], s[4:5], v40, s9, v[140:141]
	v_cvt_pk_bf16_f32 v28, v28, v29
	v_cvt_pk_bf16_f32 v29, v30, v31
	v_cvt_pk_bf16_f32 v30, v24, v25
	v_add_u32_e32 v24, 0xa0, v144
	global_store_dwordx4 v[142:143], v[108:111], off offset:256
	v_cvt_pk_bf16_f32 v95, v90, v91
	v_mad_i64_i32 v[88:89], s[4:5], v88, s9, v[140:141]
	v_lshl_add_u64 v[108:109], v[104:105], 0, v[138:139]
	v_cvt_pk_bf16_f32 v76, v76, v77
	v_cvt_pk_bf16_f32 v77, v78, v79
	v_cvt_pk_bf16_f32 v78, v72, v73
	v_or_b32_e32 v72, 48, v144
	global_store_dwordx4 v[64:65], v[44:47], off offset:256
	v_cvt_pk_bf16_f32 v31, v26, v27
	v_mad_i64_i32 v[24:25], s[4:5], v24, s9, v[140:141]
	v_lshl_add_u64 v[44:45], v[40:41], 0, v[138:139]
	v_cvt_pk_bf16_f32 v12, v12, v13
	v_cvt_pk_bf16_f32 v13, v14, v15
	v_cvt_pk_bf16_f32 v14, v8, v9
	v_add_u32_e32 v8, 0xb0, v144
	global_store_dwordx4 v[108:109], v[92:95], off offset:256
	v_cvt_pk_bf16_f32 v79, v74, v75
	v_mad_i64_i32 v[72:73], s[4:5], v72, s9, v[140:141]
	v_lshl_add_u64 v[92:93], v[88:89], 0, v[138:139]
	global_store_dwordx4 v[44:45], v[28:31], off offset:256
	v_cvt_pk_bf16_f32 v15, v10, v11
	v_mad_i64_i32 v[8:9], s[4:5], v8, s9, v[140:141]
	v_lshl_add_u64 v[28:29], v[24:25], 0, v[138:139]
	v_cvt_pk_bf16_f32 v124, v124, v125
	v_cvt_pk_bf16_f32 v125, v126, v127
	v_cvt_pk_bf16_f32 v126, v120, v121
	v_cvt_pk_bf16_f32 v127, v122, v123
	v_cvt_pk_bf16_f32 v104, v116, v117
	v_cvt_pk_bf16_f32 v105, v118, v119
	v_cvt_pk_bf16_f32 v106, v112, v113
	v_cvt_pk_bf16_f32 v107, v114, v115
	v_cvt_pk_bf16_f32 v88, v100, v101
	v_cvt_pk_bf16_f32 v89, v102, v103
	v_cvt_pk_bf16_f32 v90, v96, v97
	v_cvt_pk_bf16_f32 v91, v98, v99
	global_store_dwordx4 v[92:93], v[76:79], off offset:256
	v_cvt_pk_bf16_f32 v74, v80, v81
	v_cvt_pk_bf16_f32 v75, v82, v83
	v_lshl_add_u64 v[76:77], v[72:73], 0, v[138:139]
	v_cvt_pk_bf16_f32 v72, v84, v85
	v_cvt_pk_bf16_f32 v73, v86, v87
	v_cvt_pk_bf16_f32 v71, v66, v67
	v_cvt_pk_bf16_f32 v60, v60, v61
	v_cvt_pk_bf16_f32 v61, v62, v63
	v_cvt_pk_bf16_f32 v62, v56, v57
	v_cvt_pk_bf16_f32 v63, v58, v59
	v_cvt_pk_bf16_f32 v40, v52, v53
	v_cvt_pk_bf16_f32 v41, v54, v55
	v_cvt_pk_bf16_f32 v42, v48, v49
	v_cvt_pk_bf16_f32 v43, v50, v51
	v_cvt_pk_bf16_f32 v24, v36, v37
	v_cvt_pk_bf16_f32 v25, v38, v39
	v_cvt_pk_bf16_f32 v26, v32, v33
	v_cvt_pk_bf16_f32 v27, v34, v35
	global_store_dwordx4 v[28:29], v[12:15], off offset:256
	v_cvt_pk_bf16_f32 v10, v16, v17
	v_cvt_pk_bf16_f32 v11, v18, v19
	v_lshl_add_u64 v[12:13], v[8:9], 0, v[138:139]
	v_cvt_pk_bf16_f32 v8, v20, v21
	v_cvt_pk_bf16_f32 v9, v22, v23
	v_cvt_pk_bf16_f32 v4, v4, v5
	v_cvt_pk_bf16_f32 v5, v6, v7
	v_cvt_pk_bf16_f32 v6, v0, v1
	v_cvt_pk_bf16_f32 v7, v2, v3
	s_and_b64 vcc, exec, s[6:7]
	s_mov_b32 s31, s8
	s_mov_b32 s33, s10
	s_mov_b64 s[18:19], s[14:15]
	s_mov_b64 s[16:17], s[12:13]
	global_store_dwordx4 v[142:143], v[124:127], off
	global_store_dwordx4 v[108:109], v[104:107], off
	global_store_dwordx4 v[92:93], v[88:91], off
	global_store_dwordx4 v[76:77], v[72:75], off
	global_store_dwordx4 v[76:77], v[68:71], off offset:256
	global_store_dwordx4 v[64:65], v[60:63], off
	global_store_dwordx4 v[44:45], v[40:43], off
	global_store_dwordx4 v[28:29], v[24:27], off
	global_store_dwordx4 v[12:13], v[8:11], off
	global_store_dwordx4 v[12:13], v[4:7], off offset:256
	s_cbranch_vccz .LBB0_228
	s_waitcnt vmcnt(0)
	s_cmpk_gt_u32 s2, 0xff
	s_cbranch_scc1 .LBB0_235
	s_barrier

; #define PG8_STAGE(bufoff, gbase) do { _Pragma("unroll") for (int _i = 0; _i < 2; ++_i) \
;         __builtin_amdgcn_global_load_lds((const unsigned*)((const char*)(gbase) + voff[_i]), (LAS unsigned*)(lds + (bufoff) + ldsw + _i * 8192), 16, 0, 0); } while (0)
; #define PG8_LDA(dst, b, h) do { _Pragma("unroll") for (int m = 0; m < 4; ++m) _Pragma("unroll") for (int k = 0; k < 2; ++k) dst[m][k] = *(const LAS bf16x8*)(lds + PG8_SA(b, h) + aoff + m * 2048 + k * 1024); } while (0)
; #define PG8_LDB(dst, b, h) do { _Pragma("unroll") for (int n = 0; n < 2; ++n) _Pragma("unroll") for (int k = 0; k < 2; ++k) dst[n][k] = *(const LAS bf16x8*)(lds + PG8_SB(b, h) + boff + n * 2048 + k * 1024); } while (0)
; #define PG8_MMA(ai, bj, At, Bt) do { __builtin_amdgcn_s_setprio(1); _Pragma("unroll") for (int m = 0; m < 4; ++m) _Pragma("unroll") for (int n = 0; n < 2; ++n) _Pragma("unroll") for (int k = 0; k < 2; ++k) \
;         acc[ai][bj][m][n] = __builtin_amdgcn_mfma_f32_16x16x32_bf16(Bt[n][k], At[m][k], acc[ai][bj][m][n], 0, 0, 0); __builtin_amdgcn_s_setprio(0); } while (0)
; #define PG8_WAIT_L(n) asm volatile("s_waitcnt lgkmcnt(" #n ")" ::: "memory")
; #define PG8_BAR __builtin_amdgcn_s_barrier()
; #define PG8_SCHED __builtin_amdgcn_sched_barrier(0)
; template <class Epi>
; DI void gemm_phase(LAS unsigned char* lds, const Gemm g, const StaticOrder& S, const Epi& E) {
;     ...
;             PG8_LDB(B0, 0, 0); PG8_SCHED; PG8_LDA(At, 0, 0); PG8_STAGE(PG8_SA(1, 1), a1 + hstep);
;             PG8_WAIT_L(8); PG8_BAR; PG8_WAIT_L(0); PG8_MMA(0, 0, At, B0); PG8_BAR; PG8_SCHED;
;             PG8_LDB(B1, 0, 1); PG8_STAGE(PG8_SB(0, 0), b2);
;             PG8_BAR; PG8_WAIT_L(0); PG8_MMA(0, 1, At, B1); PG8_BAR;
;             PG8_LDA(At, 0, 1); PG8_STAGE(PG8_SA(0, 0), a2);
;             PG8_BAR; PG8_WAIT_L(0); PG8_MMA(1, 0, At, B0); PG8_BAR; PG8_SCHED;
;             PG8_STAGE(PG8_SB(0, 1), b2 + hstep);
.LBB0_320:
	s_add_u32 s26, s24, 0x100
	s_addc_u32 s27, s25, 0
	s_add_i32 s47, 0, 0x10000
	v_add_u32_e32 v140, s47, v226
	ds_read_b128 v[128:131], v140
	ds_read_b128 v[132:135], v140 offset:1024
	ds_read_b128 v[136:139], v140 offset:2048
	ds_read_b128 v[140:143], v140 offset:3072
	s_cmp_eq_u32 s46, 28
	s_cselect_b32 s31, s4, s27
	s_cselect_b32 s30, s5, s26
	s_cselect_b32 s29, s9, s45
	s_cselect_b32 s28, s11, s33
	v_lshl_add_u64 v[214:215], s[24:25], 0, v[190:191]
	s_add_i32 m0, s38, 0xc000
	ds_read_b128 v[144:147], v228
	ds_read_b128 v[148:151], v228 offset:1024
	ds_read_b128 v[152:155], v228 offset:2048
	ds_read_b128 v[194:197], v228 offset:3072
	ds_read_b128 v[198:201], v228 offset:4096
	ds_read_b128 v[202:205], v228 offset:5120
	ds_read_b128 v[206:209], v228 offset:6144
	ds_read_b128 v[210:213], v228 offset:7168
	global_load_lds_dwordx4 v[214:215], off
	v_lshl_add_u64 v[214:215], s[24:25], 0, v[192:193]
	s_add_i32 m0, s38, 0xe000
	s_nop 0
	global_load_lds_dwordx4 v[214:215], off
	s_waitcnt lgkmcnt(8)
	s_setprio 1
	s_barrier
	s_waitcnt lgkmcnt(0)
	v_mfma_f32_16x16x32_bf16 v[124:127], v[128:131], v[144:147], v[124:127]
	v_mfma_f32_16x16x32_bf16 v[120:123], v[136:139], v[144:147], v[120:123]
	s_add_i32 s48, 0, 0x14000
	v_mfma_f32_16x16x32_bf16 v[116:119], v[128:131], v[152:155], v[116:119]
	s_add_i32 s24, s47, s37
	v_mfma_f32_16x16x32_bf16 v[112:115], v[136:139], v[152:155], v[112:115]
	v_add_u32_e32 v158, s48, v226
	v_mfma_f32_16x16x32_bf16 v[108:111], v[128:131], v[198:201], v[108:111]
	v_lshl_add_u64 v[218:219], s[28:29], 0, v[188:189]
	v_mfma_f32_16x16x32_bf16 v[104:107], v[136:139], v[198:201], v[104:107]
	s_mov_b32 m0, s24
	v_mfma_f32_16x16x32_bf16 v[100:103], v[128:131], v[206:209], v[100:103]
	v_mfma_f32_16x16x32_bf16 v[96:99], v[136:139], v[206:209], v[96:99]
	v_mfma_f32_16x16x32_bf16 v[124:127], v[132:135], v[148:151], v[124:127]
	v_mfma_f32_16x16x32_bf16 v[120:123], v[140:143], v[148:151], v[120:123]
	v_mfma_f32_16x16x32_bf16 v[116:119], v[132:135], v[194:197], v[116:119]
	v_mfma_f32_16x16x32_bf16 v[112:115], v[140:143], v[194:197], v[112:115]
	v_mfma_f32_16x16x32_bf16 v[108:111], v[132:135], v[202:205], v[108:111]
	v_mfma_f32_16x16x32_bf16 v[104:107], v[140:143], v[202:205], v[104:107]
	v_mfma_f32_16x16x32_bf16 v[100:103], v[132:135], v[210:213], v[100:103]
	v_mfma_f32_16x16x32_bf16 v[96:99], v[140:143], v[210:213], v[96:99]
	s_setprio 0
	s_barrier
	ds_read_b128 v[214:217], v158
	ds_read_b128 v[230:233], v158 offset:1024
	ds_read_b128 v[234:237], v158 offset:2048
	ds_read_b128 v[238:241], v158 offset:3072
	global_load_lds_dwordx4 v[218:219], off
	v_lshl_add_u64 v[220:221], s[28:29], 0, v[186:187]
	s_add_i32 m0, s24, 0x2000
	s_nop 0
	global_load_lds_dwordx4 v[220:221], off
	s_waitcnt lgkmcnt(0)
	s_setprio 1
	s_barrier
	v_mfma_f32_16x16x32_bf16 v[60:63], v[214:217], v[144:147], v[60:63]
	v_mfma_f32_16x16x32_bf16 v[56:59], v[234:237], v[144:147], v[56:59]
	v_mfma_f32_16x16x32_bf16 v[52:55], v[214:217], v[152:155], v[52:55]
	v_mfma_f32_16x16x32_bf16 v[48:51], v[234:237], v[152:155], v[48:51]
	v_mfma_f32_16x16x32_bf16 v[44:47], v[214:217], v[198:201], v[44:47]
	v_mfma_f32_16x16x32_bf16 v[40:43], v[234:237], v[198:201], v[40:43]
	v_mfma_f32_16x16x32_bf16 v[36:39], v[214:217], v[206:209], v[36:39]
	v_mfma_f32_16x16x32_bf16 v[32:35], v[234:237], v[206:209], v[32:35]
	v_mfma_f32_16x16x32_bf16 v[60:63], v[230:233], v[148:151], v[60:63]
	s_mov_b32 m0, s38
	v_mfma_f32_16x16x32_bf16 v[56:59], v[238:241], v[148:151], v[56:59]
	v_lshl_add_u64 v[242:243], s[30:31], 0, v[188:189]
	v_mfma_f32_16x16x32_bf16 v[52:55], v[230:233], v[194:197], v[52:55]
	v_mfma_f32_16x16x32_bf16 v[48:51], v[238:241], v[194:197], v[48:51]
	v_mfma_f32_16x16x32_bf16 v[44:47], v[230:233], v[202:205], v[44:47]
	v_mfma_f32_16x16x32_bf16 v[40:43], v[238:241], v[202:205], v[40:43]
	v_mfma_f32_16x16x32_bf16 v[36:39], v[230:233], v[210:213], v[36:39]
	v_mfma_f32_16x16x32_bf16 v[32:35], v[238:241], v[210:213], v[32:35]
	s_setprio 0
	s_barrier
	ds_read_b128 v[144:147], v228 offset:16384
	ds_read_b128 v[148:151], v228 offset:17408
	ds_read_b128 v[152:155], v228 offset:18432
	ds_read_b128 v[194:197], v228 offset:19456
	ds_read_b128 v[198:201], v228 offset:20480
	ds_read_b128 v[202:205], v228 offset:21504
	ds_read_b128 v[206:209], v228 offset:22528
	ds_read_b128 v[210:213], v228 offset:23552
	global_load_lds_dwordx4 v[242:243], off
	v_lshl_add_u64 v[244:245], s[30:31], 0, v[186:187]
	s_mov_b32 m0, s39
	s_nop 0
	global_load_lds_dwordx4 v[244:245], off
	s_waitcnt lgkmcnt(0)
	s_setprio 1
	s_barrier
	v_mfma_f32_16x16x32_bf16 v[92:95], v[128:131], v[144:147], v[92:95]
	v_mfma_f32_16x16x32_bf16 v[88:91], v[136:139], v[144:147], v[88:91]
	s_add_u32 s24, s28, 0x80000
	v_mfma_f32_16x16x32_bf16 v[84:87], v[128:131], v[152:155], v[84:87]
	s_addc_u32 s25, s29, 0
	v_mfma_f32_16x16x32_bf16 v[80:83], v[136:139], v[152:155], v[80:83]
	s_add_i32 s47, s48, s37
	v_mfma_f32_16x16x32_bf16 v[76:79], v[128:131], v[198:201], v[76:79]
	v_mfma_f32_16x16x32_bf16 v[72:75], v[136:139], v[198:201], v[72:75]
	v_mfma_f32_16x16x32_bf16 v[68:71], v[128:131], v[206:209], v[68:71]
	v_mfma_f32_16x16x32_bf16 v[64:67], v[136:139], v[206:209], v[64:67]
	v_mfma_f32_16x16x32_bf16 v[92:95], v[132:135], v[148:151], v[92:95]
	v_mfma_f32_16x16x32_bf16 v[88:91], v[140:143], v[148:151], v[88:91]
	v_mfma_f32_16x16x32_bf16 v[84:87], v[132:135], v[194:197], v[84:87]
	v_mfma_f32_16x16x32_bf16 v[80:83], v[140:143], v[194:197], v[80:83]
	v_mfma_f32_16x16x32_bf16 v[76:79], v[132:135], v[202:205], v[76:79]
	v_mfma_f32_16x16x32_bf16 v[72:75], v[140:143], v[202:205], v[72:75]
	v_mfma_f32_16x16x32_bf16 v[68:71], v[132:135], v[210:213], v[68:71]
	v_mfma_f32_16x16x32_bf16 v[64:67], v[140:143], v[210:213], v[64:67]
	s_setprio 0
	s_barrier
; #define PG8_STAGE(bufoff, gbase) do { _Pragma("unroll") for (int _i = 0; _i < 2; ++_i) \
;         __builtin_amdgcn_global_load_lds((const unsigned*)((const char*)(gbase) + voff[_i]), (LAS unsigned*)(lds + (bufoff) + ldsw + _i * 8192), 16, 0, 0); } while (0)
; #define PG8_LDA(dst, b, h) do { _Pragma("unroll") for (int m = 0; m < 4; ++m) _Pragma("unroll") for (int k = 0; k < 2; ++k) dst[m][k] = *(const LAS bf16x8*)(lds + PG8_SA(b, h) + aoff + m * 2048 + k * 1024); } while (0)
; #define PG8_LDB(dst, b, h) do { _Pragma("unroll") for (int n = 0; n < 2; ++n) _Pragma("unroll") for (int k = 0; k < 2; ++k) dst[n][k] = *(const LAS bf16x8*)(lds + PG8_SB(b, h) + boff + n * 2048 + k * 1024); } while (0)
; #define PG8_MMA(ai, bj, At, Bt) do { __builtin_amdgcn_s_setprio(1); _Pragma("unroll") for (int m = 0; m < 4; ++m) _Pragma("unroll") for (int n = 0; n < 2; ++n) _Pragma("unroll") for (int k = 0; k < 2; ++k) \
;         acc[ai][bj][m][n] = __builtin_amdgcn_mfma_f32_16x16x32_bf16(Bt[n][k], At[m][k], acc[ai][bj][m][n], 0, 0, 0); __builtin_amdgcn_s_setprio(0); } while (0)
; #define PG8_WAIT_V(n) asm volatile("s_waitcnt vmcnt(" #n ")" ::: "memory")
; #define PG8_WAIT_L(n) asm volatile("s_waitcnt lgkmcnt(" #n ")" ::: "memory")
; #define PG8_BAR __builtin_amdgcn_s_barrier()
; #define PG8_SCHED __builtin_amdgcn_sched_barrier(0)
; template <class Epi>
; DI void gemm_phase(LAS unsigned char* lds, const Gemm g, const StaticOrder& S, const Epi& E) {
;     ...
;             PG8_STAGE(PG8_SB(0, 1), b2 + hstep);
;             PG8_WAIT_V(6); PG8_BAR; PG8_MMA(1, 1, At, B1); PG8_BAR;
;             PG8_LDB(B0, 1, 0); PG8_SCHED; PG8_LDA(At, 1, 0); PG8_STAGE(PG8_SA(0, 1), a2 + hstep);
;             PG8_WAIT_L(8); PG8_BAR; PG8_WAIT_L(0); PG8_MMA(0, 0, At, B0); PG8_BAR; PG8_SCHED;
;             PG8_LDB(B1, 1, 1); PG8_STAGE(PG8_SB(1, 0), b3);
;             PG8_BAR; PG8_WAIT_L(0); PG8_MMA(0, 1, At, B1); PG8_BAR;
;             PG8_LDA(At, 1, 1); PG8_STAGE(PG8_SA(1, 0), a3);
;             PG8_BAR; PG8_WAIT_L(0); PG8_MMA(1, 0, At, B0); PG8_BAR; PG8_SCHED;
	v_lshl_add_u64 v[128:129], s[24:25], 0, v[188:189]
	s_mov_b32 m0, s47
	s_nop 0
	global_load_lds_dwordx4 v[128:129], off
	v_lshl_add_u64 v[128:129], s[24:25], 0, v[186:187]
	s_add_i32 m0, s47, 0x2000
	s_nop 0
	global_load_lds_dwordx4 v[128:129], off
	s_waitcnt vmcnt(6)
	s_setprio 1
	s_barrier
	v_mfma_f32_16x16x32_bf16 v[28:31], v[214:217], v[144:147], v[28:31]
	v_mfma_f32_16x16x32_bf16 v[24:27], v[234:237], v[144:147], v[24:27]
	v_mfma_f32_16x16x32_bf16 v[20:23], v[214:217], v[152:155], v[20:23]
	v_mfma_f32_16x16x32_bf16 v[16:19], v[234:237], v[152:155], v[16:19]
	v_mfma_f32_16x16x32_bf16 v[12:15], v[214:217], v[198:201], v[12:15]
	v_mfma_f32_16x16x32_bf16 v[8:11], v[234:237], v[198:201], v[8:11]
	v_mfma_f32_16x16x32_bf16 v[4:7], v[214:217], v[206:209], v[4:7]
	v_mfma_f32_16x16x32_bf16 v[0:3], v[234:237], v[206:209], v[0:3]
	v_mfma_f32_16x16x32_bf16 v[28:31], v[230:233], v[148:151], v[28:31]
	s_add_i32 s47, 0, 0x18000
	v_mfma_f32_16x16x32_bf16 v[24:27], v[238:241], v[148:151], v[24:27]
	v_add_u32_e32 v140, s47, v226
	v_mfma_f32_16x16x32_bf16 v[20:23], v[230:233], v[194:197], v[20:23]
	v_mfma_f32_16x16x32_bf16 v[16:19], v[238:241], v[194:197], v[16:19]
	v_mfma_f32_16x16x32_bf16 v[12:15], v[230:233], v[202:205], v[12:15]
	v_mfma_f32_16x16x32_bf16 v[8:11], v[238:241], v[202:205], v[8:11]
	v_mfma_f32_16x16x32_bf16 v[4:7], v[230:233], v[210:213], v[4:7]
	v_mfma_f32_16x16x32_bf16 v[0:3], v[238:241], v[210:213], v[0:3]
	s_setprio 0
	s_barrier
	ds_read_b128 v[128:131], v140
	ds_read_b128 v[132:135], v140 offset:1024
	ds_read_b128 v[136:139], v140 offset:2048
	ds_read_b128 v[140:143], v140 offset:3072
	s_add_u32 s24, s30, 0x80000
	s_addc_u32 s25, s31, 0
	s_mov_b32 m0, s40
	v_lshl_add_u64 v[214:215], s[24:25], 0, v[188:189]
	ds_read_b128 v[144:147], v228 offset:32768
	ds_read_b128 v[148:151], v228 offset:33792
	ds_read_b128 v[152:155], v228 offset:34816
	ds_read_b128 v[194:197], v228 offset:35840
	ds_read_b128 v[198:201], v228 offset:36864
	ds_read_b128 v[202:205], v228 offset:37888
	ds_read_b128 v[206:209], v228 offset:38912
	ds_read_b128 v[210:213], v228 offset:39936
	global_load_lds_dwordx4 v[214:215], off
	v_lshl_add_u64 v[214:215], s[24:25], 0, v[186:187]
	s_mov_b32 m0, s41
	s_nop 0
	global_load_lds_dwordx4 v[214:215], off
	s_waitcnt lgkmcnt(8)
	s_setprio 1
	s_barrier
	s_waitcnt lgkmcnt(0)
	v_mfma_f32_16x16x32_bf16 v[124:127], v[128:131], v[144:147], v[124:127]
	v_mfma_f32_16x16x32_bf16 v[120:123], v[136:139], v[144:147], v[120:123]
	s_add_i32 s30, 0, 0x1c000
	v_mfma_f32_16x16x32_bf16 v[116:119], v[128:131], v[152:155], v[116:119]
	s_add_i32 s24, s47, s37
	v_mfma_f32_16x16x32_bf16 v[112:115], v[136:139], v[152:155], v[112:115]
	v_add_u32_e32 v158, s30, v226
	v_mfma_f32_16x16x32_bf16 v[108:111], v[128:131], v[198:201], v[108:111]
	v_lshl_add_u64 v[218:219], v[218:219], 0, s[94:95]
	v_mfma_f32_16x16x32_bf16 v[104:107], v[136:139], v[198:201], v[104:107]
	s_mov_b32 m0, s24
	v_mfma_f32_16x16x32_bf16 v[100:103], v[128:131], v[206:209], v[100:103]
	v_mfma_f32_16x16x32_bf16 v[96:99], v[136:139], v[206:209], v[96:99]
	v_mfma_f32_16x16x32_bf16 v[124:127], v[132:135], v[148:151], v[124:127]
	v_mfma_f32_16x16x32_bf16 v[120:123], v[140:143], v[148:151], v[120:123]
	v_mfma_f32_16x16x32_bf16 v[116:119], v[132:135], v[194:197], v[116:119]
	v_mfma_f32_16x16x32_bf16 v[112:115], v[140:143], v[194:197], v[112:115]
	v_mfma_f32_16x16x32_bf16 v[108:111], v[132:135], v[202:205], v[108:111]
	v_mfma_f32_16x16x32_bf16 v[104:107], v[140:143], v[202:205], v[104:107]
	v_mfma_f32_16x16x32_bf16 v[100:103], v[132:135], v[210:213], v[100:103]
	v_mfma_f32_16x16x32_bf16 v[96:99], v[140:143], v[210:213], v[96:99]
	s_setprio 0
	s_barrier
	ds_read_b128 v[214:217], v158
	ds_read_b128 v[230:233], v158 offset:1024
	ds_read_b128 v[234:237], v158 offset:2048
	ds_read_b128 v[238:241], v158 offset:3072
	global_load_lds_dwordx4 v[218:219], off
	v_lshl_add_u64 v[218:219], v[220:221], 0, s[94:95]
	s_add_i32 m0, s24, 0x2000
	s_nop 0
	global_load_lds_dwordx4 v[218:219], off
	s_waitcnt lgkmcnt(0)
	s_setprio 1
	s_barrier
	v_mfma_f32_16x16x32_bf16 v[60:63], v[214:217], v[144:147], v[60:63]
	v_mfma_f32_16x16x32_bf16 v[56:59], v[234:237], v[144:147], v[56:59]
	v_mfma_f32_16x16x32_bf16 v[52:55], v[214:217], v[152:155], v[52:55]
	v_mfma_f32_16x16x32_bf16 v[48:51], v[234:237], v[152:155], v[48:51]
	v_mfma_f32_16x16x32_bf16 v[44:47], v[214:217], v[198:201], v[44:47]
	v_mfma_f32_16x16x32_bf16 v[40:43], v[234:237], v[198:201], v[40:43]
	v_mfma_f32_16x16x32_bf16 v[36:39], v[214:217], v[206:209], v[36:39]
	v_mfma_f32_16x16x32_bf16 v[32:35], v[234:237], v[206:209], v[32:35]
	v_mfma_f32_16x16x32_bf16 v[60:63], v[230:233], v[148:151], v[60:63]
	s_mov_b32 m0, s42
	v_mfma_f32_16x16x32_bf16 v[56:59], v[238:241], v[148:151], v[56:59]
	v_lshl_add_u64 v[218:219], v[242:243], 0, s[94:95]
	v_mfma_f32_16x16x32_bf16 v[52:55], v[230:233], v[194:197], v[52:55]
	v_mfma_f32_16x16x32_bf16 v[48:51], v[238:241], v[194:197], v[48:51]
	v_mfma_f32_16x16x32_bf16 v[44:47], v[230:233], v[202:205], v[44:47]
	v_mfma_f32_16x16x32_bf16 v[40:43], v[238:241], v[202:205], v[40:43]
	v_mfma_f32_16x16x32_bf16 v[36:39], v[230:233], v[210:213], v[36:39]
	v_mfma_f32_16x16x32_bf16 v[32:35], v[238:241], v[210:213], v[32:35]
	s_setprio 0
	s_barrier
	ds_read_b128 v[144:147], v228 offset:49152
	ds_read_b128 v[148:151], v228 offset:50176
	ds_read_b128 v[152:155], v228 offset:51200
	ds_read_b128 v[194:197], v228 offset:52224
	ds_read_b128 v[198:201], v228 offset:53248
	ds_read_b128 v[202:205], v228 offset:54272
	ds_read_b128 v[206:209], v228 offset:55296
	ds_read_b128 v[210:213], v228 offset:56320
	global_load_lds_dwordx4 v[218:219], off
	v_lshl_add_u64 v[218:219], v[244:245], 0, s[94:95]
	s_mov_b32 m0, s43
	s_nop 0
	global_load_lds_dwordx4 v[218:219], off
	s_waitcnt lgkmcnt(0)
	s_setprio 1
	s_barrier
; #define PG8_WAIT_V(n) asm volatile("s_waitcnt vmcnt(" #n ")" ::: "memory")
; #define PG8_WAIT_L(n) asm volatile("s_waitcnt lgkmcnt(" #n ")" ::: "memory")
; #define PG8_BAR __builtin_amdgcn_s_barrier()
; template <class Epi>
; DI void gemm_phase(LAS unsigned char* lds, const Gemm g, const StaticOrder& S, const Epi& E) {
;     ...
;             PG8_BAR; PG8_WAIT_L(0); PG8_MMA(1, 0, At, B0); PG8_BAR; PG8_SCHED;
;             PG8_STAGE(PG8_SB(1, 1), b3 + hstep);
;             PG8_WAIT_V(6); PG8_BAR; PG8_MMA(1, 1, At, B1); PG8_BAR;
;     template <bool LN, int BJ, int LO, int HI> DI void batch(const f32x4 (&acc)[2][2][4][2], unsigned row0, unsigned col0, const f32x4 (&gv)[2], const f32x4 (&bv)[2]) const {
;         f32x4 r[HI - LO]; float mean[(HI - LO) / 2], rstd[(HI - LO) / 2];
; #pragma unroll
;         for (int i = LO; i < HI; ++i) { const int ai = i >> 3, m = (i >> 1) & 3, n = i & 1; const unsigned row = row0 + ai * HALF + m * 16;
;             if (n == 0) { mean[(i - LO) >> 1] = 0.f; rstd[(i - LO) >> 1] = 1.f;
;                 if (LN) { const float2 st = *(const float2*)(stats + row * 2u); mean[(i - LO) >> 1] = st.x; rstd[(i - LO) >> 1] = st.y; } }
;             r[i - LO] = *(const f32x4*)(src + (row * (unsigned)DM + col0 + BJ * HALF + n * 16)); }
; #pragma unroll
;         for (int i = LO; i < HI; ++i) { const int ai = i >> 3, m = (i >> 1) & 3, n = i & 1; const unsigned row = row0 + ai * HALF + m * 16;
;             *(f32x4*)(Y + (row * (unsigned)DM + col0 + BJ * HALF + n * 16)) = acc[ai][BJ][m][n] + ((r[i - LO] - mean[(i - LO) >> 1]) * rstd[(i - LO) >> 1]) * gv[n] + bv[n]; }
;         __builtin_amdgcn_sched_barrier(0);
;     }
;     template <bool LN, int BJ> DI void load_gb(unsigned col0, f32x4 (&gv)[2], f32x4 (&bv)[2]) const {
; #pragma unroll
;         for (int n = 0; n < 2; ++n) {
;             if (LN) { gv[n] = *(const f32x4*)(gam + col0 + BJ * HALF + n * 16) * ALPHA; bv[n] = *(const f32x4*)(bet + col0 + BJ * HALF + n * 16) * ALPHA; }
;             else { gv[n] = (f32x4){ALPHA, ALPHA, ALPHA, ALPHA}; bv[n] = (f32x4){0.f, 0.f, 0.f, 0.f}; }
;         }
;     }
;     template <bool LN> DI void run(const f32x4 (&acc)[2][2][4][2], const Unit& u, int wr, int wc, int fr, int fq) const {
;         const unsigned row0 = u.pm * BM + wr * 64 + fr, col0 = u.pn * BM + wc * 32 + 4 * fq;
;         f32x4 gv[2], bv[2];
;         load_gb<LN, 0>(col0, gv, bv);
	v_mfma_f32_16x16x32_bf16 v[92:95], v[128:131], v[144:147], v[92:95]
	v_mfma_f32_16x16x32_bf16 v[88:91], v[136:139], v[144:147], v[88:91]
	s_add_u32 s24, s28, 0x80080
	v_mfma_f32_16x16x32_bf16 v[84:87], v[128:131], v[152:155], v[84:87]
	s_addc_u32 s25, s29, 0
	v_mfma_f32_16x16x32_bf16 v[80:83], v[136:139], v[152:155], v[80:83]
	s_add_i32 s28, s30, s37
	v_mfma_f32_16x16x32_bf16 v[76:79], v[128:131], v[198:201], v[76:79]
	v_mfma_f32_16x16x32_bf16 v[72:75], v[136:139], v[198:201], v[72:75]
	v_mfma_f32_16x16x32_bf16 v[68:71], v[128:131], v[206:209], v[68:71]
	v_mfma_f32_16x16x32_bf16 v[64:67], v[136:139], v[206:209], v[64:67]
	v_mfma_f32_16x16x32_bf16 v[92:95], v[132:135], v[148:151], v[92:95]
	v_mfma_f32_16x16x32_bf16 v[88:91], v[140:143], v[148:151], v[88:91]
	v_mfma_f32_16x16x32_bf16 v[84:87], v[132:135], v[194:197], v[84:87]
	v_mfma_f32_16x16x32_bf16 v[80:83], v[140:143], v[194:197], v[80:83]
	v_mfma_f32_16x16x32_bf16 v[76:79], v[132:135], v[202:205], v[76:79]
	v_mfma_f32_16x16x32_bf16 v[72:75], v[140:143], v[202:205], v[72:75]
	v_mfma_f32_16x16x32_bf16 v[68:71], v[132:135], v[210:213], v[68:71]
	v_mfma_f32_16x16x32_bf16 v[64:67], v[140:143], v[210:213], v[64:67]
	s_setprio 0
	s_barrier
	v_lshl_add_u64 v[128:129], s[24:25], 0, v[188:189]
	s_mov_b32 m0, s28
	s_nop 0
	global_load_lds_dwordx4 v[128:129], off
	v_lshl_add_u64 v[128:129], s[24:25], 0, v[186:187]
	s_add_i32 m0, s28, 0x2000
	s_nop 0
	global_load_lds_dwordx4 v[128:129], off
	s_waitcnt vmcnt(6)
	s_setprio 1
	s_barrier
	v_mfma_f32_16x16x32_bf16 v[28:31], v[214:217], v[144:147], v[28:31]
	v_mfma_f32_16x16x32_bf16 v[24:27], v[234:237], v[144:147], v[24:27]
	v_mfma_f32_16x16x32_bf16 v[20:23], v[214:217], v[152:155], v[20:23]
	v_mfma_f32_16x16x32_bf16 v[16:19], v[234:237], v[152:155], v[16:19]
	v_mfma_f32_16x16x32_bf16 v[12:15], v[214:217], v[198:201], v[12:15]
	v_mfma_f32_16x16x32_bf16 v[8:11], v[234:237], v[198:201], v[8:11]
	v_mfma_f32_16x16x32_bf16 v[4:7], v[214:217], v[206:209], v[4:7]
	v_mfma_f32_16x16x32_bf16 v[0:3], v[234:237], v[206:209], v[0:3]
	v_mfma_f32_16x16x32_bf16 v[28:31], v[230:233], v[148:151], v[28:31]
	s_add_i32 s46, s46, 2
	v_mfma_f32_16x16x32_bf16 v[24:27], v[238:241], v[148:151], v[24:27]
	s_add_u32 s33, s33, 0x100
	v_mfma_f32_16x16x32_bf16 v[20:23], v[230:233], v[194:197], v[20:23]
	s_addc_u32 s45, s45, 0
	v_mfma_f32_16x16x32_bf16 v[16:19], v[238:241], v[194:197], v[16:19]
	s_cmp_gt_u32 s46, 29
	v_mfma_f32_16x16x32_bf16 v[12:15], v[230:233], v[202:205], v[12:15]
	s_mov_b64 s[24:25], s[26:27]
	v_mfma_f32_16x16x32_bf16 v[8:11], v[238:241], v[202:205], v[8:11]
	v_mfma_f32_16x16x32_bf16 v[4:7], v[230:233], v[210:213], v[4:7]
	v_mfma_f32_16x16x32_bf16 v[0:3], v[238:241], v[210:213], v[0:3]
	s_setprio 0
	s_barrier
	s_cbranch_scc0 .LBB0_320
	v_lshl_add_u32 v206, s3, 8, v225
	v_lshl_or_b32 v158, s2, 8, v227
	v_lshlrev_b32_e32 v232, 11, v206
	s_andn2_b64 vcc, exec, s[14:15]
	v_or_b32_e32 v231, 16, v158
	v_add_u32_e32 v194, v232, v158
	v_or_b32_e32 v230, 0x80, v158
	v_or_b32_e32 v229, 0x90, v158
	s_cbranch_vccnz .LBB0_323
	v_lshlrev_b64 v[132:133], 2, v[158:159]
	v_lshl_add_u64 v[140:141], s[16:17], 0, v[132:133]
	global_load_dwordx4 v[128:131], v[140:141], off
	v_lshl_add_u64 v[142:143], s[18:19], 0, v[132:133]
	v_readlane_b32 s2, v253, 8
	v_mov_b32_e32 v195, v159
	v_lshlrev_b32_e32 v136, 1, v206
	v_mov_b32_e32 v137, v159
	v_readlane_b32 s3, v253, 9
	v_lshlrev_b64 v[212:213], 2, v[194:195]
	v_add_u32_e32 v146, v232, v231
	v_lshl_add_u64 v[144:145], v[136:137], 2, s[2:3]
	v_lshl_add_u64 v[136:137], s[88:89], 0, v[212:213]
	v_mov_b32_e32 v147, v159
	v_lshl_add_u64 v[146:147], v[146:147], 2, s[88:89]
	v_or_b32_e32 v195, 16, v206
	v_mov_b32_e32 v201, v159
	v_mov_b32_e32 v209, v159
	v_lshl_add_u64 v[212:213], s[90:91], 0, v[212:213]
	s_waitcnt vmcnt(0)
	v_pk_mul_f32 v[152:153], v[130:131], s[78:79] op_sel_hi:[1,0]
	v_pk_mul_f32 v[154:155], v[128:129], s[78:79] op_sel_hi:[1,0]
	global_load_dwordx4 v[132:135], v[142:143], off
	global_load_dwordx4 v[128:131], v[140:141], off offset:64
	global_load_dwordx2 v[204:205], v[144:145], off
	global_load_dwordx4 v[196:199], v[146:147], off
	v_lshlrev_b32_e32 v146, 1, v195
	global_load_dwordx4 v[136:139], v[136:137], off
	v_lshlrev_b32_e32 v195, 11, v195
	v_mov_b32_e32 v147, v159
	v_add_u32_e32 v200, v195, v158
	v_lshl_add_u64 v[146:147], v[146:147], 2, s[2:3]
	v_lshl_add_u64 v[200:201], v[200:201], 2, s[88:89]
	global_load_dwordx2 v[214:215], v[146:147], off
	v_add_u32_e32 v208, v195, v231
	global_load_dwordx4 v[200:203], v[200:201], off
	v_lshl_add_u64 v[208:209], v[208:209], 2, s[88:89]
	global_load_dwordx4 v[208:211], v[208:209], off
	s_waitcnt vmcnt(0)
	v_pk_mul_f32 v[148:149], v[130:131], s[78:79] op_sel_hi:[1,0]
	v_pk_mul_f32 v[150:151], v[128:129], s[78:79] op_sel_hi:[1,0]
	global_load_dwordx4 v[128:131], v[142:143], off offset:64
	v_sub_f32_e32 v137, v137, v204
	v_sub_f32_e32 v136, v136, v204
	v_sub_f32_e32 v139, v139, v204
	v_sub_f32_e32 v138, v138, v204
	v_pk_mul_f32 v[138:139], v[204:205], v[138:139] op_sel:[1,0]
	v_pk_mul_f32 v[136:137], v[204:205], v[136:137] op_sel:[1,0]
	v_pk_fma_f32 v[138:139], v[152:153], v[138:139], v[126:127]
	v_pk_fma_f32 v[136:137], v[154:155], v[136:137], v[124:125]
	v_pk_fma_f32 v[138:139], v[134:135], s[78:79], v[138:139] op_sel_hi:[1,0,1]
	v_pk_fma_f32 v[136:137], v[132:133], s[78:79], v[136:137] op_sel_hi:[1,0,1]
	global_store_dwordx4 v[212:213], v[136:139], off
	s_nop 1
	v_sub_f32_e32 v137, v197, v204
	v_sub_f32_e32 v136, v196, v204
	v_sub_f32_e32 v139, v199, v204
	v_sub_f32_e32 v138, v198, v204
	v_pk_mul_f32 v[138:139], v[204:205], v[138:139] op_sel:[1,0]
	v_pk_mul_f32 v[136:137], v[204:205], v[136:137] op_sel:[1,0]
	v_pk_fma_f32 v[138:139], v[148:149], v[138:139], v[122:123]
	v_pk_fma_f32 v[136:137], v[150:151], v[136:137], v[120:121]
	v_or_b32_e32 v196, 16, v194
	v_mov_b32_e32 v197, v159
	v_lshl_add_u64 v[196:197], v[196:197], 2, s[90:91]
	s_waitcnt vmcnt(0)
;     template <bool LN, int BJ, int LO, int HI> DI void batch(const f32x4 (&acc)[2][2][4][2], unsigned row0, unsigned col0, const f32x4 (&gv)[2], const f32x4 (&bv)[2]) const {
;         f32x4 r[HI - LO]; float mean[(HI - LO) / 2], rstd[(HI - LO) / 2];
; #pragma unroll
;         for (int i = LO; i < HI; ++i) { const int ai = i >> 3, m = (i >> 1) & 3, n = i & 1; const unsigned row = row0 + ai * HALF + m * 16;
;             if (n == 0) { mean[(i - LO) >> 1] = 0.f; rstd[(i - LO) >> 1] = 1.f;
;                 if (LN) { const float2 st = *(const float2*)(stats + row * 2u); mean[(i - LO) >> 1] = st.x; rstd[(i - LO) >> 1] = st.y; } }
;             r[i - LO] = *(const f32x4*)(src + (row * (unsigned)DM + col0 + BJ * HALF + n * 16)); }
; #pragma unroll
;         for (int i = LO; i < HI; ++i) { const int ai = i >> 3, m = (i >> 1) & 3, n = i & 1; const unsigned row = row0 + ai * HALF + m * 16;
;             *(f32x4*)(Y + (row * (unsigned)DM + col0 + BJ * HALF + n * 16)) = acc[ai][BJ][m][n] + ((r[i - LO] - mean[(i - LO) >> 1]) * rstd[(i - LO) >> 1]) * gv[n] + bv[n]; }
;         __builtin_amdgcn_sched_barrier(0);
;     }
;     template <bool LN, int BJ> DI void load_gb(unsigned col0, f32x4 (&gv)[2], f32x4 (&bv)[2]) const {
; #pragma unroll
;         for (int n = 0; n < 2; ++n) {
;             if (LN) { gv[n] = *(const f32x4*)(gam + col0 + BJ * HALF + n * 16) * ALPHA; bv[n] = *(const f32x4*)(bet + col0 + BJ * HALF + n * 16) * ALPHA; }
;             else { gv[n] = (f32x4){ALPHA, ALPHA, ALPHA, ALPHA}; bv[n] = (f32x4){0.f, 0.f, 0.f, 0.f}; }
;         }
;     }
;     template <bool LN> DI void run(const f32x4 (&acc)[2][2][4][2], const Unit& u, int wr, int wc, int fr, int fq) const {
;         const unsigned row0 = u.pm * BM + wr * 64 + fr, col0 = u.pn * BM + wc * 32 + 4 * fq;
;         f32x4 gv[2], bv[2];
;         load_gb<LN, 0>(col0, gv, bv);
;         batch<LN, 0, 0, 4>(acc, row0, col0, gv, bv);
;         batch<LN, 0, 4, 8>(acc, row0, col0, gv, bv);
;         batch<LN, 0, 8, 12>(acc, row0, col0, gv, bv);
;         batch<LN, 0, 12, 16>(acc, row0, col0, gv, bv);
	v_pk_fma_f32 v[138:139], v[130:131], s[78:79], v[138:139] op_sel_hi:[1,0,1]
	v_pk_fma_f32 v[136:137], v[128:129], s[78:79], v[136:137] op_sel_hi:[1,0,1]
	global_store_dwordx4 v[196:197], v[136:139], off
	v_add_u32_e32 v196, 0x8000, v194
	v_mov_b32_e32 v197, v159
	v_sub_f32_e32 v137, v201, v214
	v_sub_f32_e32 v136, v200, v214
	v_sub_f32_e32 v139, v203, v214
	v_sub_f32_e32 v138, v202, v214
	v_pk_mul_f32 v[138:139], v[214:215], v[138:139] op_sel:[1,0]
	v_pk_mul_f32 v[136:137], v[214:215], v[136:137] op_sel:[1,0]
	v_pk_fma_f32 v[138:139], v[152:153], v[138:139], v[118:119]
	v_pk_fma_f32 v[136:137], v[154:155], v[136:137], v[116:117]
	v_pk_fma_f32 v[138:139], v[134:135], s[78:79], v[138:139] op_sel_hi:[1,0,1]
	v_pk_fma_f32 v[136:137], v[132:133], s[78:79], v[136:137] op_sel_hi:[1,0,1]
	v_lshl_add_u64 v[196:197], v[196:197], 2, s[90:91]
	global_store_dwordx4 v[196:197], v[136:139], off
	v_add_u32_e32 v196, 0x8010, v194
	v_mov_b32_e32 v197, v159
	v_sub_f32_e32 v137, v209, v214
	v_sub_f32_e32 v136, v208, v214
	v_sub_f32_e32 v139, v211, v214
	v_sub_f32_e32 v138, v210, v214
	v_pk_mul_f32 v[138:139], v[214:215], v[138:139] op_sel:[1,0]
	v_pk_mul_f32 v[136:137], v[214:215], v[136:137] op_sel:[1,0]
	v_pk_fma_f32 v[138:139], v[148:149], v[138:139], v[114:115]
	v_pk_fma_f32 v[136:137], v[150:151], v[136:137], v[112:113]
	v_pk_fma_f32 v[138:139], v[130:131], s[78:79], v[138:139] op_sel_hi:[1,0,1]
	v_pk_fma_f32 v[136:137], v[128:129], s[78:79], v[136:137] op_sel_hi:[1,0,1]
	v_lshl_add_u64 v[196:197], v[196:197], 2, s[90:91]
	global_store_dwordx4 v[196:197], v[136:139], off
	s_nop 1
	v_or_b32_e32 v138, 32, v206
	v_lshlrev_b32_e32 v136, 1, v138
	v_mov_b32_e32 v137, v159
	v_lshlrev_b32_e32 v236, 11, v138
	v_lshl_add_u64 v[200:201], v[136:137], 2, s[2:3]
	v_add_u32_e32 v136, v236, v158
	v_lshl_add_u64 v[136:137], v[136:137], 2, s[88:89]
	global_load_dwordx2 v[204:205], v[200:201], off
	v_add_u32_e32 v196, v236, v231
	global_load_dwordx4 v[136:139], v[136:137], off
	v_mov_b32_e32 v197, v159
	v_lshl_add_u64 v[196:197], v[196:197], 2, s[88:89]
	global_load_dwordx4 v[196:199], v[196:197], off
	v_or_b32_e32 v207, 48, v206
	v_lshlrev_b32_e32 v235, 11, v207
	v_lshlrev_b32_e32 v202, 1, v207
	v_mov_b32_e32 v203, v159
	v_add_u32_e32 v208, v235, v158
	v_mov_b32_e32 v209, v159
	v_lshl_add_u64 v[202:203], v[202:203], 2, s[2:3]
	v_lshl_add_u64 v[208:209], v[208:209], 2, s[88:89]
	global_load_dwordx2 v[216:217], v[202:203], off
	v_add_u32_e32 v212, v235, v231
	global_load_dwordx4 v[208:211], v[208:209], off
	v_mov_b32_e32 v213, v159
	v_lshl_add_u64 v[212:213], v[212:213], 2, s[88:89]
	global_load_dwordx4 v[212:215], v[212:213], off
	v_add_u32_e32 v218, 0x10000, v194
	v_mov_b32_e32 v219, v159
	v_lshl_add_u64 v[218:219], v[218:219], 2, s[90:91]
	s_waitcnt vmcnt(0)
	v_sub_f32_e32 v137, v137, v204
	v_sub_f32_e32 v136, v136, v204
	v_sub_f32_e32 v139, v139, v204
	v_sub_f32_e32 v138, v138, v204
	v_pk_mul_f32 v[138:139], v[204:205], v[138:139] op_sel:[1,0]
	v_pk_mul_f32 v[136:137], v[204:205], v[136:137] op_sel:[1,0]
	v_pk_fma_f32 v[138:139], v[152:153], v[138:139], v[110:111]
	v_pk_fma_f32 v[136:137], v[154:155], v[136:137], v[108:109]
	v_pk_fma_f32 v[138:139], v[134:135], s[78:79], v[138:139] op_sel_hi:[1,0,1]
	v_pk_fma_f32 v[136:137], v[132:133], s[78:79], v[136:137] op_sel_hi:[1,0,1]
	global_store_dwordx4 v[218:219], v[136:139], off
	s_nop 1
	v_sub_f32_e32 v137, v197, v204
	v_sub_f32_e32 v136, v196, v204
	v_sub_f32_e32 v139, v199, v204
	v_sub_f32_e32 v138, v198, v204
	v_pk_mul_f32 v[138:139], v[204:205], v[138:139] op_sel:[1,0]
	v_pk_mul_f32 v[136:137], v[204:205], v[136:137] op_sel:[1,0]
	v_pk_fma_f32 v[138:139], v[148:149], v[138:139], v[106:107]
	v_pk_fma_f32 v[136:137], v[150:151], v[136:137], v[104:105]
	v_add_u32_e32 v196, 0x10010, v194
	v_mov_b32_e32 v197, v159
	v_pk_fma_f32 v[138:139], v[130:131], s[78:79], v[138:139] op_sel_hi:[1,0,1]
	v_pk_fma_f32 v[136:137], v[128:129], s[78:79], v[136:137] op_sel_hi:[1,0,1]
	v_lshl_add_u64 v[196:197], v[196:197], 2, s[90:91]
	global_store_dwordx4 v[196:197], v[136:139], off
	v_add_u32_e32 v196, 0x18000, v194
	v_mov_b32_e32 v197, v159
	v_sub_f32_e32 v137, v209, v216
	v_sub_f32_e32 v136, v208, v216
	v_sub_f32_e32 v139, v211, v216
	v_sub_f32_e32 v138, v210, v216
	v_pk_mul_f32 v[138:139], v[216:217], v[138:139] op_sel:[1,0]
	v_pk_mul_f32 v[136:137], v[216:217], v[136:137] op_sel:[1,0]
	v_pk_fma_f32 v[138:139], v[152:153], v[138:139], v[102:103]
	v_pk_fma_f32 v[136:137], v[154:155], v[136:137], v[100:101]
	v_pk_fma_f32 v[138:139], v[134:135], s[78:79], v[138:139] op_sel_hi:[1,0,1]
	v_pk_fma_f32 v[136:137], v[132:133], s[78:79], v[136:137] op_sel_hi:[1,0,1]
	v_lshl_add_u64 v[196:197], v[196:197], 2, s[90:91]
	global_store_dwordx4 v[196:197], v[136:139], off
	v_add_u32_e32 v196, 0x18010, v194
	v_mov_b32_e32 v197, v159
	v_sub_f32_e32 v137, v213, v216
	v_sub_f32_e32 v136, v212, v216
	v_sub_f32_e32 v139, v215, v216
	v_sub_f32_e32 v138, v214, v216
	v_pk_mul_f32 v[138:139], v[216:217], v[138:139] op_sel:[1,0]
	v_pk_mul_f32 v[136:137], v[216:217], v[136:137] op_sel:[1,0]
	v_pk_fma_f32 v[138:139], v[148:149], v[138:139], v[98:99]
	v_pk_fma_f32 v[136:137], v[150:151], v[136:137], v[96:97]
	v_pk_fma_f32 v[138:139], v[130:131], s[78:79], v[138:139] op_sel_hi:[1,0,1]
	v_pk_fma_f32 v[136:137], v[128:129], s[78:79], v[136:137] op_sel_hi:[1,0,1]
	v_lshl_add_u64 v[196:197], v[196:197], 2, s[90:91]
	global_store_dwordx4 v[196:197], v[136:139], off
	s_nop 1
	v_add_u32_e32 v138, 0x80, v206
	v_lshlrev_b32_e32 v136, 1, v138
	v_mov_b32_e32 v137, v159
	v_lshlrev_b32_e32 v233, 11, v138
	v_lshl_add_u64 v[196:197], v[136:137], 2, s[2:3]
	v_add_u32_e32 v136, v233, v158
	v_lshl_add_u64 v[136:137], v[136:137], 2, s[88:89]
	global_load_dwordx2 v[204:205], v[196:197], off
	v_add_u32_e32 v198, v233, v231
	global_load_dwordx4 v[136:139], v[136:137], off
	v_mov_b32_e32 v199, v159
	v_add_u32_e32 v207, 0x90, v206
	v_lshl_add_u64 v[198:199], v[198:199], 2, s[88:89]
	v_lshlrev_b32_e32 v234, 11, v207
	global_load_dwordx4 v[208:211], v[198:199], off
	v_add_u32_e32 v212, v234, v158
	v_mov_b32_e32 v213, v159
	v_lshl_add_u64 v[212:213], v[212:213], 2, s[88:89]
	global_load_dwordx4 v[212:215], v[212:213], off
	v_lshlrev_b32_e32 v198, 1, v207
	v_mov_b32_e32 v199, v159
	v_lshl_add_u64 v[198:199], v[198:199], 2, s[2:3]
	global_load_dwordx2 v[238:239], v[198:199], off
	v_add_u32_e32 v216, v234, v231
	v_mov_b32_e32 v217, v159
	v_lshl_add_u64 v[216:217], v[216:217], 2, s[88:89]
	global_load_dwordx4 v[216:219], v[216:217], off
	v_add_u32_e32 v240, 0x40000, v194
	v_mov_b32_e32 v241, v159
	v_lshl_add_u64 v[240:241], v[240:241], 2, s[90:91]
	s_waitcnt vmcnt(0)
;     template <bool LN, int BJ, int LO, int HI> DI void batch(const f32x4 (&acc)[2][2][4][2], unsigned row0, unsigned col0, const f32x4 (&gv)[2], const f32x4 (&bv)[2]) const {
;         f32x4 r[HI - LO]; float mean[(HI - LO) / 2], rstd[(HI - LO) / 2];
; #pragma unroll
;         for (int i = LO; i < HI; ++i) { const int ai = i >> 3, m = (i >> 1) & 3, n = i & 1; const unsigned row = row0 + ai * HALF + m * 16;
;             if (n == 0) { mean[(i - LO) >> 1] = 0.f; rstd[(i - LO) >> 1] = 1.f;
;                 if (LN) { const float2 st = *(const float2*)(stats + row * 2u); mean[(i - LO) >> 1] = st.x; rstd[(i - LO) >> 1] = st.y; } }
;             r[i - LO] = *(const f32x4*)(src + (row * (unsigned)DM + col0 + BJ * HALF + n * 16)); }
; #pragma unroll
;         for (int i = LO; i < HI; ++i) { const int ai = i >> 3, m = (i >> 1) & 3, n = i & 1; const unsigned row = row0 + ai * HALF + m * 16;
;             *(f32x4*)(Y + (row * (unsigned)DM + col0 + BJ * HALF + n * 16)) = acc[ai][BJ][m][n] + ((r[i - LO] - mean[(i - LO) >> 1]) * rstd[(i - LO) >> 1]) * gv[n] + bv[n]; }
;         __builtin_amdgcn_sched_barrier(0);
;     }
;     template <bool LN, int BJ> DI void load_gb(unsigned col0, f32x4 (&gv)[2], f32x4 (&bv)[2]) const {
; #pragma unroll
;         for (int n = 0; n < 2; ++n) {
;             if (LN) { gv[n] = *(const f32x4*)(gam + col0 + BJ * HALF + n * 16) * ALPHA; bv[n] = *(const f32x4*)(bet + col0 + BJ * HALF + n * 16) * ALPHA; }
;             else { gv[n] = (f32x4){ALPHA, ALPHA, ALPHA, ALPHA}; bv[n] = (f32x4){0.f, 0.f, 0.f, 0.f}; }
;         }
;     }
;     template <bool LN> DI void run(const f32x4 (&acc)[2][2][4][2], const Unit& u, int wr, int wc, int fr, int fq) const {
;         const unsigned row0 = u.pm * BM + wr * 64 + fr, col0 = u.pn * BM + wc * 32 + 4 * fq;
;         f32x4 gv[2], bv[2];
;         load_gb<LN, 0>(col0, gv, bv);
;         batch<LN, 0, 0, 4>(acc, row0, col0, gv, bv);
;         batch<LN, 0, 4, 8>(acc, row0, col0, gv, bv);
;         batch<LN, 0, 8, 12>(acc, row0, col0, gv, bv);
;         batch<LN, 0, 12, 16>(acc, row0, col0, gv, bv);
	v_sub_f32_e32 v137, v137, v204
	v_sub_f32_e32 v136, v136, v204
	v_sub_f32_e32 v139, v139, v204
	v_sub_f32_e32 v138, v138, v204
	v_pk_mul_f32 v[138:139], v[204:205], v[138:139] op_sel:[1,0]
	v_pk_mul_f32 v[136:137], v[204:205], v[136:137] op_sel:[1,0]
	v_pk_fma_f32 v[138:139], v[152:153], v[138:139], v[94:95]
	v_pk_fma_f32 v[136:137], v[154:155], v[136:137], v[92:93]
	v_pk_fma_f32 v[138:139], v[134:135], s[78:79], v[138:139] op_sel_hi:[1,0,1]
	v_pk_fma_f32 v[136:137], v[132:133], s[78:79], v[136:137] op_sel_hi:[1,0,1]
	global_store_dwordx4 v[240:241], v[136:139], off
	s_nop 1
	v_sub_f32_e32 v137, v209, v204
	v_sub_f32_e32 v136, v208, v204
	v_sub_f32_e32 v139, v211, v204
	v_sub_f32_e32 v138, v210, v204
	v_pk_mul_f32 v[138:139], v[204:205], v[138:139] op_sel:[1,0]
	v_pk_mul_f32 v[136:137], v[204:205], v[136:137] op_sel:[1,0]
	v_pk_fma_f32 v[138:139], v[148:149], v[138:139], v[90:91]
	v_pk_fma_f32 v[136:137], v[150:151], v[136:137], v[88:89]
	v_add_u32_e32 v204, 0x40010, v194
	v_mov_b32_e32 v205, v159
	v_pk_fma_f32 v[138:139], v[130:131], s[78:79], v[138:139] op_sel_hi:[1,0,1]
	v_pk_fma_f32 v[136:137], v[128:129], s[78:79], v[136:137] op_sel_hi:[1,0,1]
	v_lshl_add_u64 v[204:205], v[204:205], 2, s[90:91]
	global_store_dwordx4 v[204:205], v[136:139], off
	v_add_u32_e32 v204, 0x48000, v194
	v_mov_b32_e32 v205, v159
	v_sub_f32_e32 v137, v213, v238
	v_sub_f32_e32 v136, v212, v238
	v_sub_f32_e32 v139, v215, v238
	v_sub_f32_e32 v138, v214, v238
	v_pk_mul_f32 v[138:139], v[238:239], v[138:139] op_sel:[1,0]
	v_pk_mul_f32 v[136:137], v[238:239], v[136:137] op_sel:[1,0]
	v_pk_fma_f32 v[138:139], v[152:153], v[138:139], v[86:87]
	v_pk_fma_f32 v[136:137], v[154:155], v[136:137], v[84:85]
	v_pk_fma_f32 v[138:139], v[134:135], s[78:79], v[138:139] op_sel_hi:[1,0,1]
	v_pk_fma_f32 v[136:137], v[132:133], s[78:79], v[136:137] op_sel_hi:[1,0,1]
	v_lshl_add_u64 v[204:205], v[204:205], 2, s[90:91]
	global_store_dwordx4 v[204:205], v[136:139], off
	v_add_u32_e32 v204, 0x48010, v194
	v_mov_b32_e32 v205, v159
	v_sub_f32_e32 v137, v217, v238
	v_sub_f32_e32 v136, v216, v238
	v_sub_f32_e32 v139, v219, v238
	v_sub_f32_e32 v138, v218, v238
	v_pk_mul_f32 v[138:139], v[238:239], v[138:139] op_sel:[1,0]
	v_pk_mul_f32 v[136:137], v[238:239], v[136:137] op_sel:[1,0]
	v_pk_fma_f32 v[138:139], v[148:149], v[138:139], v[82:83]
	v_pk_fma_f32 v[136:137], v[150:151], v[136:137], v[80:81]
	v_pk_fma_f32 v[138:139], v[130:131], s[78:79], v[138:139] op_sel_hi:[1,0,1]
	v_pk_fma_f32 v[136:137], v[128:129], s[78:79], v[136:137] op_sel_hi:[1,0,1]
	v_lshl_add_u64 v[204:205], v[204:205], 2, s[90:91]
	global_store_dwordx4 v[204:205], v[136:139], off
	s_nop 1
	v_add_u32_e32 v138, 0xa0, v206
	v_lshlrev_b32_e32 v136, 1, v138
	v_mov_b32_e32 v137, v159
	v_lshlrev_b32_e32 v237, 11, v138
	v_lshl_add_u64 v[204:205], v[136:137], 2, s[2:3]
	v_add_u32_e32 v136, v237, v158
	v_lshl_add_u64 v[136:137], v[136:137], 2, s[88:89]
	global_load_dwordx2 v[240:241], v[204:205], off
	v_add_u32_e32 v208, v237, v231
	global_load_dwordx4 v[136:139], v[136:137], off
	v_mov_b32_e32 v209, v159
	v_lshl_add_u64 v[208:209], v[208:209], 2, s[88:89]
	global_load_dwordx4 v[212:215], v[208:209], off
	v_add_u32_e32 v208, 0xb0, v206
	v_lshlrev_b32_e32 v206, 1, v208
	v_mov_b32_e32 v207, v159
	v_lshlrev_b32_e32 v238, 11, v208
	v_lshl_add_u64 v[210:211], v[206:207], 2, s[2:3]
	v_add_u32_e32 v206, v238, v158
	v_lshl_add_u64 v[206:207], v[206:207], 2, s[88:89]
	global_load_dwordx2 v[242:243], v[210:211], off
	v_add_u32_e32 v216, v238, v231
	global_load_dwordx4 v[206:209], v[206:207], off
	v_mov_b32_e32 v217, v159
	v_lshl_add_u64 v[216:217], v[216:217], 2, s[88:89]
	global_load_dwordx4 v[216:219], v[216:217], off
	v_add_u32_e32 v244, 0x50000, v194
	v_mov_b32_e32 v245, v159
	v_lshl_add_u64 v[244:245], v[244:245], 2, s[90:91]
	s_waitcnt vmcnt(0)
	v_sub_f32_e32 v137, v137, v240
	v_sub_f32_e32 v136, v136, v240
	v_sub_f32_e32 v139, v139, v240
	v_sub_f32_e32 v138, v138, v240
	v_pk_mul_f32 v[138:139], v[240:241], v[138:139] op_sel:[1,0]
	v_pk_mul_f32 v[136:137], v[240:241], v[136:137] op_sel:[1,0]
	v_pk_fma_f32 v[138:139], v[152:153], v[138:139], v[78:79]
	v_pk_fma_f32 v[136:137], v[154:155], v[136:137], v[76:77]
	v_pk_fma_f32 v[138:139], v[134:135], s[78:79], v[138:139] op_sel_hi:[1,0,1]
	v_pk_fma_f32 v[136:137], v[132:133], s[78:79], v[136:137] op_sel_hi:[1,0,1]
	global_store_dwordx4 v[244:245], v[136:139], off
	s_nop 1
	v_sub_f32_e32 v137, v213, v240
	v_sub_f32_e32 v136, v212, v240
	v_sub_f32_e32 v139, v215, v240
	v_sub_f32_e32 v138, v214, v240
	v_pk_mul_f32 v[138:139], v[240:241], v[138:139] op_sel:[1,0]
	v_pk_mul_f32 v[136:137], v[240:241], v[136:137] op_sel:[1,0]
	v_pk_fma_f32 v[138:139], v[148:149], v[138:139], v[74:75]
	v_pk_fma_f32 v[136:137], v[150:151], v[136:137], v[72:73]
	v_add_u32_e32 v212, 0x50010, v194
	v_mov_b32_e32 v213, v159
	v_pk_fma_f32 v[138:139], v[130:131], s[78:79], v[138:139] op_sel_hi:[1,0,1]
	v_pk_fma_f32 v[136:137], v[128:129], s[78:79], v[136:137] op_sel_hi:[1,0,1]
	v_lshl_add_u64 v[212:213], v[212:213], 2, s[90:91]
	global_store_dwordx4 v[212:213], v[136:139], off
	s_nop 1
	v_sub_f32_e32 v137, v207, v242
	v_sub_f32_e32 v136, v206, v242
	v_sub_f32_e32 v139, v209, v242
	v_sub_f32_e32 v138, v208, v242
	v_pk_mul_f32 v[136:137], v[242:243], v[136:137] op_sel:[1,0]
	v_pk_mul_f32 v[138:139], v[242:243], v[138:139] op_sel:[1,0]
	v_pk_fma_f32 v[136:137], v[154:155], v[136:137], v[68:69]
	v_pk_fma_f32 v[138:139], v[152:153], v[138:139], v[70:71]
	v_pk_fma_f32 v[132:133], v[132:133], s[78:79], v[136:137] op_sel_hi:[1,0,1]
	v_add_u32_e32 v136, 0x58000, v194
	v_mov_b32_e32 v137, v159
	v_pk_fma_f32 v[134:135], v[134:135], s[78:79], v[138:139] op_sel_hi:[1,0,1]
	v_lshl_add_u64 v[136:137], v[136:137], 2, s[90:91]
	global_store_dwordx4 v[136:137], v[132:135], off
	s_nop 1
	v_sub_f32_e32 v133, v217, v242
	v_sub_f32_e32 v132, v216, v242
	v_sub_f32_e32 v135, v219, v242
	v_sub_f32_e32 v134, v218, v242
	v_pk_mul_f32 v[132:133], v[242:243], v[132:133] op_sel:[1,0]
	v_pk_mul_f32 v[134:135], v[242:243], v[134:135] op_sel:[1,0]
	v_pk_fma_f32 v[132:133], v[150:151], v[132:133], v[64:65]
	v_pk_fma_f32 v[134:135], v[148:149], v[134:135], v[66:67]
	v_pk_fma_f32 v[128:129], v[128:129], s[78:79], v[132:133] op_sel_hi:[1,0,1]
	v_add_u32_e32 v132, 0x58010, v194
	v_mov_b32_e32 v133, v159
	v_pk_fma_f32 v[130:131], v[130:131], s[78:79], v[134:135] op_sel_hi:[1,0,1]
	v_lshl_add_u64 v[132:133], v[132:133], 2, s[90:91]
	global_store_dwordx4 v[132:133], v[128:131], off
	global_load_dwordx4 v[128:131], v[140:141], off offset:512
	v_add_u32_e32 v136, v232, v230
	v_mov_b32_e32 v137, v159
	v_lshl_add_u64 v[136:137], v[136:137], 2, s[88:89]
	s_waitcnt vmcnt(0)
;     template <bool LN, int BJ, int LO, int HI> DI void batch(const f32x4 (&acc)[2][2][4][2], unsigned row0, unsigned col0, const f32x4 (&gv)[2], const f32x4 (&bv)[2]) const {
;         f32x4 r[HI - LO]; float mean[(HI - LO) / 2], rstd[(HI - LO) / 2];
; #pragma unroll
;         for (int i = LO; i < HI; ++i) { const int ai = i >> 3, m = (i >> 1) & 3, n = i & 1; const unsigned row = row0 + ai * HALF + m * 16;
;             if (n == 0) { mean[(i - LO) >> 1] = 0.f; rstd[(i - LO) >> 1] = 1.f;
;                 if (LN) { const float2 st = *(const float2*)(stats + row * 2u); mean[(i - LO) >> 1] = st.x; rstd[(i - LO) >> 1] = st.y; } }
;             r[i - LO] = *(const f32x4*)(src + (row * (unsigned)DM + col0 + BJ * HALF + n * 16)); }
; #pragma unroll
;         for (int i = LO; i < HI; ++i) { const int ai = i >> 3, m = (i >> 1) & 3, n = i & 1; const unsigned row = row0 + ai * HALF + m * 16;
;             *(f32x4*)(Y + (row * (unsigned)DM + col0 + BJ * HALF + n * 16)) = acc[ai][BJ][m][n] + ((r[i - LO] - mean[(i - LO) >> 1]) * rstd[(i - LO) >> 1]) * gv[n] + bv[n]; }
;         __builtin_amdgcn_sched_barrier(0);
;     }
;     template <bool LN, int BJ> DI void load_gb(unsigned col0, f32x4 (&gv)[2], f32x4 (&bv)[2]) const {
; #pragma unroll
;         for (int n = 0; n < 2; ++n) {
;             if (LN) { gv[n] = *(const f32x4*)(gam + col0 + BJ * HALF + n * 16) * ALPHA; bv[n] = *(const f32x4*)(bet + col0 + BJ * HALF + n * 16) * ALPHA; }
;             else { gv[n] = (f32x4){ALPHA, ALPHA, ALPHA, ALPHA}; bv[n] = (f32x4){0.f, 0.f, 0.f, 0.f}; }
;         }
;     }
;     template <bool LN> DI void run(const f32x4 (&acc)[2][2][4][2], const Unit& u, int wr, int wc, int fr, int fq) const {
;         const unsigned row0 = u.pm * BM + wr * 64 + fr, col0 = u.pn * BM + wc * 32 + 4 * fq;
;         f32x4 gv[2], bv[2];
;         load_gb<LN, 0>(col0, gv, bv);
;         batch<LN, 0, 0, 4>(acc, row0, col0, gv, bv);
;         batch<LN, 0, 4, 8>(acc, row0, col0, gv, bv);
;         batch<LN, 0, 8, 12>(acc, row0, col0, gv, bv);
;         batch<LN, 0, 12, 16>(acc, row0, col0, gv, bv);
;         load_gb<LN, 1>(col0, gv, bv);
;         batch<LN, 1, 0, 8>(acc, row0, col0, gv, bv);
;         batch<LN, 1, 8, 16>(acc, row0, col0, gv, bv);
	v_pk_mul_f32 v[212:213], v[130:131], s[78:79] op_sel_hi:[1,0]
	v_pk_mul_f32 v[214:215], v[128:129], s[78:79] op_sel_hi:[1,0]
	global_load_dwordx4 v[132:135], v[142:143], off offset:512
	global_load_dwordx4 v[128:131], v[140:141], off offset:576
	s_waitcnt vmcnt(0)
	v_pk_mul_f32 v[206:207], v[130:131], s[78:79] op_sel_hi:[1,0]
	v_pk_mul_f32 v[208:209], v[128:129], s[78:79] op_sel_hi:[1,0]
	global_load_dwordx4 v[128:131], v[142:143], off offset:576
	global_load_dwordx2 v[220:221], v[144:145], off
	global_load_dwordx4 v[240:243], v[136:137], off
	v_add_u32_e32 v136, v232, v229
	v_mov_b32_e32 v137, v159
	v_lshl_add_u64 v[136:137], v[136:137], 2, s[88:89]
	global_load_dwordx4 v[244:247], v[136:137], off
	global_load_dwordx2 v[218:219], v[146:147], off
	v_add_u32_e32 v136, v195, v230
	v_mov_b32_e32 v137, v159
	v_lshl_add_u64 v[136:137], v[136:137], 2, s[88:89]
	global_load_dwordx4 v[248:251], v[136:137], off
	v_add_u32_e32 v136, v195, v229
	v_mov_b32_e32 v137, v159
	v_lshl_add_u64 v[136:137], v[136:137], 2, s[88:89]
	global_load_dwordx4 v[152:155], v[136:137], off
	global_load_dwordx2 v[216:217], v[200:201], off
	v_add_u32_e32 v136, v236, v230
	v_mov_b32_e32 v137, v159
	v_lshl_add_u64 v[136:137], v[136:137], 2, s[88:89]
	global_load_dwordx4 v[148:151], v[136:137], off
	v_add_u32_e32 v136, v236, v229
	v_mov_b32_e32 v137, v159
	v_lshl_add_u64 v[136:137], v[136:137], 2, s[88:89]
	global_load_dwordx4 v[144:147], v[136:137], off
	global_load_dwordx2 v[200:201], v[202:203], off
	v_add_u32_e32 v136, v235, v230
	v_mov_b32_e32 v137, v159
	v_lshl_add_u64 v[136:137], v[136:137], 2, s[88:89]
	global_load_dwordx4 v[140:143], v[136:137], off
	v_add_u32_e32 v136, v235, v229
	v_mov_b32_e32 v137, v159
	v_lshl_add_u64 v[136:137], v[136:137], 2, s[88:89]
	global_load_dwordx4 v[136:139], v[136:137], off
	v_add_u32_e32 v202, 0x80, v194
	v_mov_b32_e32 v203, v159
	v_lshl_add_u64 v[202:203], v[202:203], 2, s[90:91]
	s_waitcnt vmcnt(0)
	v_sub_f32_e32 v241, v241, v220
	v_sub_f32_e32 v240, v240, v220
	v_sub_f32_e32 v243, v243, v220
	v_sub_f32_e32 v242, v242, v220
	v_pk_mul_f32 v[242:243], v[220:221], v[242:243] op_sel:[1,0]
	v_pk_mul_f32 v[240:241], v[220:221], v[240:241] op_sel:[1,0]
	v_pk_fma_f32 v[242:243], v[212:213], v[242:243], v[62:63]
	v_pk_fma_f32 v[240:241], v[214:215], v[240:241], v[60:61]
	v_pk_fma_f32 v[242:243], v[134:135], s[78:79], v[242:243] op_sel_hi:[1,0,1]
	v_pk_fma_f32 v[240:241], v[132:133], s[78:79], v[240:241] op_sel_hi:[1,0,1]
	global_store_dwordx4 v[202:203], v[240:243], off
	v_sub_f32_e32 v203, v245, v220
	v_sub_f32_e32 v202, v244, v220
	v_sub_f32_e32 v241, v247, v220
	v_sub_f32_e32 v240, v246, v220
	v_pk_mul_f32 v[202:203], v[220:221], v[202:203] op_sel:[1,0]
	v_pk_mul_f32 v[240:241], v[220:221], v[240:241] op_sel:[1,0]
	v_pk_fma_f32 v[202:203], v[208:209], v[202:203], v[56:57]
	v_pk_fma_f32 v[220:221], v[206:207], v[240:241], v[58:59]
	v_pk_fma_f32 v[240:241], v[128:129], s[78:79], v[202:203] op_sel_hi:[1,0,1]
	v_add_u32_e32 v202, 0x90, v194
	v_mov_b32_e32 v203, v159
	v_pk_fma_f32 v[242:243], v[130:131], s[78:79], v[220:221] op_sel_hi:[1,0,1]
	v_lshl_add_u64 v[202:203], v[202:203], 2, s[90:91]
	global_store_dwordx4 v[202:203], v[240:243], off
	v_sub_f32_e32 v203, v249, v218
	v_sub_f32_e32 v202, v248, v218
	v_sub_f32_e32 v221, v251, v218
	v_sub_f32_e32 v220, v250, v218
	v_pk_mul_f32 v[202:203], v[218:219], v[202:203] op_sel:[1,0]
	v_pk_mul_f32 v[220:221], v[218:219], v[220:221] op_sel:[1,0]
	v_pk_fma_f32 v[202:203], v[214:215], v[202:203], v[52:53]
	v_pk_fma_f32 v[220:221], v[212:213], v[220:221], v[54:55]
	v_pk_fma_f32 v[240:241], v[132:133], s[78:79], v[202:203] op_sel_hi:[1,0,1]
	v_add_u32_e32 v202, 0x8080, v194
	v_mov_b32_e32 v203, v159
	v_sub_f32_e32 v153, v153, v218
	v_sub_f32_e32 v152, v152, v218
	v_sub_f32_e32 v155, v155, v218
	v_sub_f32_e32 v154, v154, v218
	v_pk_fma_f32 v[242:243], v[134:135], s[78:79], v[220:221] op_sel_hi:[1,0,1]
	v_lshl_add_u64 v[202:203], v[202:203], 2, s[90:91]
	v_pk_mul_f32 v[154:155], v[218:219], v[154:155] op_sel:[1,0]
	v_pk_mul_f32 v[152:153], v[218:219], v[152:153] op_sel:[1,0]
	global_store_dwordx4 v[202:203], v[240:243], off
	v_pk_fma_f32 v[152:153], v[208:209], v[152:153], v[48:49]
	v_pk_fma_f32 v[154:155], v[206:207], v[154:155], v[50:51]
	v_add_u32_e32 v202, 0x8090, v194
	v_mov_b32_e32 v203, v159
	v_sub_f32_e32 v149, v149, v216
	v_sub_f32_e32 v148, v148, v216
	v_sub_f32_e32 v151, v151, v216
	v_sub_f32_e32 v150, v150, v216
	v_pk_fma_f32 v[154:155], v[130:131], s[78:79], v[154:155] op_sel_hi:[1,0,1]
	v_pk_fma_f32 v[152:153], v[128:129], s[78:79], v[152:153] op_sel_hi:[1,0,1]
	v_lshl_add_u64 v[202:203], v[202:203], 2, s[90:91]
	v_pk_mul_f32 v[150:151], v[216:217], v[150:151] op_sel:[1,0]
	v_pk_mul_f32 v[148:149], v[216:217], v[148:149] op_sel:[1,0]
	global_store_dwordx4 v[202:203], v[152:155], off
	v_pk_fma_f32 v[148:149], v[214:215], v[148:149], v[44:45]
	v_pk_fma_f32 v[150:151], v[212:213], v[150:151], v[46:47]
	v_add_u32_e32 v152, 0x10080, v194
	v_mov_b32_e32 v153, v159
	v_sub_f32_e32 v145, v145, v216
	v_sub_f32_e32 v144, v144, v216
	v_sub_f32_e32 v147, v147, v216
	v_sub_f32_e32 v146, v146, v216
	v_pk_fma_f32 v[150:151], v[134:135], s[78:79], v[150:151] op_sel_hi:[1,0,1]
	v_pk_fma_f32 v[148:149], v[132:133], s[78:79], v[148:149] op_sel_hi:[1,0,1]
	v_lshl_add_u64 v[152:153], v[152:153], 2, s[90:91]
	v_pk_mul_f32 v[146:147], v[216:217], v[146:147] op_sel:[1,0]
	v_pk_mul_f32 v[144:145], v[216:217], v[144:145] op_sel:[1,0]
	global_store_dwordx4 v[152:153], v[148:151], off
	v_pk_fma_f32 v[144:145], v[208:209], v[144:145], v[40:41]
	v_pk_fma_f32 v[146:147], v[206:207], v[146:147], v[42:43]
;     template <bool LN, int BJ, int LO, int HI> DI void batch(const f32x4 (&acc)[2][2][4][2], unsigned row0, unsigned col0, const f32x4 (&gv)[2], const f32x4 (&bv)[2]) const {
;         f32x4 r[HI - LO]; float mean[(HI - LO) / 2], rstd[(HI - LO) / 2];
; #pragma unroll
;         for (int i = LO; i < HI; ++i) { const int ai = i >> 3, m = (i >> 1) & 3, n = i & 1; const unsigned row = row0 + ai * HALF + m * 16;
;             if (n == 0) { mean[(i - LO) >> 1] = 0.f; rstd[(i - LO) >> 1] = 1.f;
;                 if (LN) { const float2 st = *(const float2*)(stats + row * 2u); mean[(i - LO) >> 1] = st.x; rstd[(i - LO) >> 1] = st.y; } }
;             r[i - LO] = *(const f32x4*)(src + (row * (unsigned)DM + col0 + BJ * HALF + n * 16)); }
; #pragma unroll
;         for (int i = LO; i < HI; ++i) { const int ai = i >> 3, m = (i >> 1) & 3, n = i & 1; const unsigned row = row0 + ai * HALF + m * 16;
;             *(f32x4*)(Y + (row * (unsigned)DM + col0 + BJ * HALF + n * 16)) = acc[ai][BJ][m][n] + ((r[i - LO] - mean[(i - LO) >> 1]) * rstd[(i - LO) >> 1]) * gv[n] + bv[n]; }
;         __builtin_amdgcn_sched_barrier(0);
;     }
;     template <bool LN, int BJ> DI void load_gb(unsigned col0, f32x4 (&gv)[2], f32x4 (&bv)[2]) const {
; #pragma unroll
;         for (int n = 0; n < 2; ++n) {
;             if (LN) { gv[n] = *(const f32x4*)(gam + col0 + BJ * HALF + n * 16) * ALPHA; bv[n] = *(const f32x4*)(bet + col0 + BJ * HALF + n * 16) * ALPHA; }
;             else { gv[n] = (f32x4){ALPHA, ALPHA, ALPHA, ALPHA}; bv[n] = (f32x4){0.f, 0.f, 0.f, 0.f}; }
;         }
;     }
;     template <bool LN> DI void run(const f32x4 (&acc)[2][2][4][2], const Unit& u, int wr, int wc, int fr, int fq) const {
;         const unsigned row0 = u.pm * BM + wr * 64 + fr, col0 = u.pn * BM + wc * 32 + 4 * fq;
;         f32x4 gv[2], bv[2];
;         load_gb<LN, 0>(col0, gv, bv);
;         batch<LN, 0, 0, 4>(acc, row0, col0, gv, bv);
;         batch<LN, 0, 4, 8>(acc, row0, col0, gv, bv);
;         batch<LN, 0, 8, 12>(acc, row0, col0, gv, bv);
;         batch<LN, 0, 12, 16>(acc, row0, col0, gv, bv);
;         load_gb<LN, 1>(col0, gv, bv);
;         batch<LN, 1, 0, 8>(acc, row0, col0, gv, bv);
;         batch<LN, 1, 8, 16>(acc, row0, col0, gv, bv);
	v_add_u32_e32 v148, 0x10090, v194
	v_mov_b32_e32 v149, v159
	v_sub_f32_e32 v141, v141, v200
	v_sub_f32_e32 v140, v140, v200
	v_sub_f32_e32 v143, v143, v200
	v_sub_f32_e32 v142, v142, v200
	v_pk_fma_f32 v[146:147], v[130:131], s[78:79], v[146:147] op_sel_hi:[1,0,1]
	v_pk_fma_f32 v[144:145], v[128:129], s[78:79], v[144:145] op_sel_hi:[1,0,1]
	v_lshl_add_u64 v[148:149], v[148:149], 2, s[90:91]
	v_pk_mul_f32 v[142:143], v[200:201], v[142:143] op_sel:[1,0]
	v_pk_mul_f32 v[140:141], v[200:201], v[140:141] op_sel:[1,0]
	global_store_dwordx4 v[148:149], v[144:147], off
	v_pk_fma_f32 v[140:141], v[214:215], v[140:141], v[36:37]
	v_pk_fma_f32 v[142:143], v[212:213], v[142:143], v[38:39]
	v_add_u32_e32 v144, 0x18080, v194
	v_mov_b32_e32 v145, v159
	v_sub_f32_e32 v137, v137, v200
	v_sub_f32_e32 v136, v136, v200
	v_sub_f32_e32 v139, v139, v200
	v_sub_f32_e32 v138, v138, v200
	v_pk_fma_f32 v[142:143], v[134:135], s[78:79], v[142:143] op_sel_hi:[1,0,1]
	v_pk_fma_f32 v[140:141], v[132:133], s[78:79], v[140:141] op_sel_hi:[1,0,1]
	v_lshl_add_u64 v[144:145], v[144:145], 2, s[90:91]
	v_pk_mul_f32 v[138:139], v[200:201], v[138:139] op_sel:[1,0]
	v_pk_mul_f32 v[136:137], v[200:201], v[136:137] op_sel:[1,0]
	global_store_dwordx4 v[144:145], v[140:143], off
	v_pk_fma_f32 v[136:137], v[208:209], v[136:137], v[32:33]
	v_pk_fma_f32 v[138:139], v[206:207], v[138:139], v[34:35]
	v_add_u32_e32 v140, 0x18090, v194
	v_mov_b32_e32 v141, v159
	v_pk_fma_f32 v[138:139], v[130:131], s[78:79], v[138:139] op_sel_hi:[1,0,1]
	v_pk_fma_f32 v[136:137], v[128:129], s[78:79], v[136:137] op_sel_hi:[1,0,1]
	v_lshl_add_u64 v[140:141], v[140:141], 2, s[90:91]
	global_store_dwordx4 v[140:141], v[136:139], off
	s_nop 1
	v_add_u32_e32 v136, v233, v230
	v_mov_b32_e32 v137, v159
	v_lshl_add_u64 v[136:137], v[136:137], 2, s[88:89]
	global_load_dwordx2 v[220:221], v[196:197], off
	global_load_dwordx4 v[216:219], v[136:137], off
	v_add_u32_e32 v136, v233, v229
	v_mov_b32_e32 v137, v159
	v_lshl_add_u64 v[136:137], v[136:137], 2, s[88:89]
	global_load_dwordx4 v[240:243], v[136:137], off
	global_load_dwordx2 v[200:201], v[198:199], off
	v_add_u32_e32 v136, v234, v230
	v_mov_b32_e32 v137, v159
	v_lshl_add_u64 v[136:137], v[136:137], 2, s[88:89]
	global_load_dwordx4 v[244:247], v[136:137], off
	v_add_u32_e32 v136, v234, v229
	v_mov_b32_e32 v137, v159
	v_lshl_add_u64 v[136:137], v[136:137], 2, s[88:89]
	global_load_dwordx4 v[152:155], v[136:137], off
	global_load_dwordx2 v[198:199], v[204:205], off
	v_add_u32_e32 v136, v237, v230
	v_mov_b32_e32 v137, v159
	v_lshl_add_u64 v[136:137], v[136:137], 2, s[88:89]
	global_load_dwordx4 v[148:151], v[136:137], off
	v_add_u32_e32 v136, v237, v229
	v_mov_b32_e32 v137, v159
	v_lshl_add_u64 v[136:137], v[136:137], 2, s[88:89]
	global_load_dwordx4 v[144:147], v[136:137], off
	global_load_dwordx2 v[196:197], v[210:211], off
	v_add_u32_e32 v136, v238, v230
	v_mov_b32_e32 v137, v159
	v_lshl_add_u64 v[136:137], v[136:137], 2, s[88:89]
	global_load_dwordx4 v[140:143], v[136:137], off
	v_add_u32_e32 v136, v238, v229
	v_mov_b32_e32 v137, v159
	v_lshl_add_u64 v[136:137], v[136:137], 2, s[88:89]
	global_load_dwordx4 v[136:139], v[136:137], off
	v_add_u32_e32 v210, 0x40080, v194
	v_mov_b32_e32 v211, v159
	v_lshl_add_u64 v[210:211], v[210:211], 2, s[90:91]
	s_waitcnt vmcnt(0)
;     template <bool LN, int BJ, int LO, int HI> DI void batch(const f32x4 (&acc)[2][2][4][2], unsigned row0, unsigned col0, const f32x4 (&gv)[2], const f32x4 (&bv)[2]) const {
;         f32x4 r[HI - LO]; float mean[(HI - LO) / 2], rstd[(HI - LO) / 2];
; #pragma unroll
;         for (int i = LO; i < HI; ++i) { const int ai = i >> 3, m = (i >> 1) & 3, n = i & 1; const unsigned row = row0 + ai * HALF + m * 16;
;             if (n == 0) { mean[(i - LO) >> 1] = 0.f; rstd[(i - LO) >> 1] = 1.f;
;                 if (LN) { const float2 st = *(const float2*)(stats + row * 2u); mean[(i - LO) >> 1] = st.x; rstd[(i - LO) >> 1] = st.y; } }
;             r[i - LO] = *(const f32x4*)(src + (row * (unsigned)DM + col0 + BJ * HALF + n * 16)); }
; #pragma unroll
;         for (int i = LO; i < HI; ++i) { const int ai = i >> 3, m = (i >> 1) & 3, n = i & 1; const unsigned row = row0 + ai * HALF + m * 16;
;             *(f32x4*)(Y + (row * (unsigned)DM + col0 + BJ * HALF + n * 16)) = acc[ai][BJ][m][n] + ((r[i - LO] - mean[(i - LO) >> 1]) * rstd[(i - LO) >> 1]) * gv[n] + bv[n]; }
;         __builtin_amdgcn_sched_barrier(0);
;     }
;     template <bool LN, int BJ> DI void load_gb(unsigned col0, f32x4 (&gv)[2], f32x4 (&bv)[2]) const {
; #pragma unroll
;         for (int n = 0; n < 2; ++n) {
;             if (LN) { gv[n] = *(const f32x4*)(gam + col0 + BJ * HALF + n * 16) * ALPHA; bv[n] = *(const f32x4*)(bet + col0 + BJ * HALF + n * 16) * ALPHA; }
;             else { gv[n] = (f32x4){ALPHA, ALPHA, ALPHA, ALPHA}; bv[n] = (f32x4){0.f, 0.f, 0.f, 0.f}; }
;         }
;     }
;     template <bool LN> DI void run(const f32x4 (&acc)[2][2][4][2], const Unit& u, int wr, int wc, int fr, int fq) const {
;         const unsigned row0 = u.pm * BM + wr * 64 + fr, col0 = u.pn * BM + wc * 32 + 4 * fq;
;         f32x4 gv[2], bv[2];
;         load_gb<LN, 0>(col0, gv, bv);
;         batch<LN, 0, 0, 4>(acc, row0, col0, gv, bv);
;         batch<LN, 0, 4, 8>(acc, row0, col0, gv, bv);
;         batch<LN, 0, 8, 12>(acc, row0, col0, gv, bv);
;         batch<LN, 0, 12, 16>(acc, row0, col0, gv, bv);
;         load_gb<LN, 1>(col0, gv, bv);
;         batch<LN, 1, 0, 8>(acc, row0, col0, gv, bv);
;         batch<LN, 1, 8, 16>(acc, row0, col0, gv, bv);
;     }
;     DI void operator()(const f32x4 (&acc)[2][2][4][2], const Unit& u, int wr, int wc, int fr, int fq) const {
	v_sub_f32_e32 v203, v217, v220
	v_sub_f32_e32 v202, v216, v220
	v_sub_f32_e32 v205, v219, v220
	v_sub_f32_e32 v204, v218, v220
	v_pk_mul_f32 v[204:205], v[220:221], v[204:205] op_sel:[1,0]
	v_pk_mul_f32 v[202:203], v[220:221], v[202:203] op_sel:[1,0]
	v_pk_fma_f32 v[204:205], v[212:213], v[204:205], v[30:31]
	v_pk_fma_f32 v[202:203], v[214:215], v[202:203], v[28:29]
	v_pk_fma_f32 v[204:205], v[134:135], s[78:79], v[204:205] op_sel_hi:[1,0,1]
	v_pk_fma_f32 v[202:203], v[132:133], s[78:79], v[202:203] op_sel_hi:[1,0,1]
	global_store_dwordx4 v[210:211], v[202:205], off
	v_add_u32_e32 v210, 0x40090, v194
	v_mov_b32_e32 v211, v159
	v_sub_f32_e32 v203, v241, v220
	v_sub_f32_e32 v202, v240, v220
	v_sub_f32_e32 v205, v243, v220
	v_sub_f32_e32 v204, v242, v220
	v_pk_mul_f32 v[204:205], v[220:221], v[204:205] op_sel:[1,0]
	v_pk_mul_f32 v[202:203], v[220:221], v[202:203] op_sel:[1,0]
	v_pk_fma_f32 v[204:205], v[206:207], v[204:205], v[26:27]
	v_pk_fma_f32 v[202:203], v[208:209], v[202:203], v[24:25]
	v_pk_fma_f32 v[204:205], v[130:131], s[78:79], v[204:205] op_sel_hi:[1,0,1]
	v_pk_fma_f32 v[202:203], v[128:129], s[78:79], v[202:203] op_sel_hi:[1,0,1]
	v_lshl_add_u64 v[210:211], v[210:211], 2, s[90:91]
	global_store_dwordx4 v[210:211], v[202:205], off
	v_sub_f32_e32 v149, v149, v198
	v_sub_f32_e32 v148, v148, v198
	v_sub_f32_e32 v203, v245, v200
	v_sub_f32_e32 v202, v244, v200
	v_sub_f32_e32 v141, v141, v196
	v_sub_f32_e32 v140, v140, v196
	v_sub_f32_e32 v205, v247, v200
	v_sub_f32_e32 v204, v246, v200
	v_pk_mul_f32 v[202:203], v[200:201], v[202:203] op_sel:[1,0]
	v_sub_f32_e32 v151, v151, v198
	v_sub_f32_e32 v150, v150, v198
	v_pk_mul_f32 v[148:149], v[198:199], v[148:149] op_sel:[1,0]
	v_sub_f32_e32 v143, v143, v196
	v_sub_f32_e32 v142, v142, v196
	v_pk_mul_f32 v[140:141], v[196:197], v[140:141] op_sel:[1,0]
	v_pk_mul_f32 v[204:205], v[200:201], v[204:205] op_sel:[1,0]
	v_pk_fma_f32 v[202:203], v[214:215], v[202:203], v[20:21]
	v_sub_f32_e32 v153, v153, v200
	v_sub_f32_e32 v152, v152, v200
	v_sub_f32_e32 v155, v155, v200
	v_sub_f32_e32 v154, v154, v200
	v_pk_mul_f32 v[150:151], v[198:199], v[150:151] op_sel:[1,0]
	v_pk_fma_f32 v[148:149], v[214:215], v[148:149], v[12:13]
	v_pk_mul_f32 v[142:143], v[196:197], v[142:143] op_sel:[1,0]
	v_pk_fma_f32 v[140:141], v[214:215], v[140:141], v[4:5]
	v_pk_fma_f32 v[204:205], v[212:213], v[204:205], v[22:23]
	v_pk_fma_f32 v[202:203], v[132:133], s[78:79], v[202:203] op_sel_hi:[1,0,1]
	v_pk_mul_f32 v[154:155], v[200:201], v[154:155] op_sel:[1,0]
	v_pk_mul_f32 v[152:153], v[200:201], v[152:153] op_sel:[1,0]
	v_pk_fma_f32 v[150:151], v[212:213], v[150:151], v[14:15]
	v_pk_fma_f32 v[148:149], v[132:133], s[78:79], v[148:149] op_sel_hi:[1,0,1]
	v_pk_fma_f32 v[142:143], v[212:213], v[142:143], v[6:7]
	v_pk_fma_f32 v[132:133], v[132:133], s[78:79], v[140:141] op_sel_hi:[1,0,1]
	v_add_u32_e32 v140, 0x58080, v194
	v_mov_b32_e32 v141, v159
	v_pk_fma_f32 v[204:205], v[134:135], s[78:79], v[204:205] op_sel_hi:[1,0,1]
	v_pk_fma_f32 v[152:153], v[208:209], v[152:153], v[16:17]
	v_pk_fma_f32 v[154:155], v[206:207], v[154:155], v[18:19]
	v_add_u32_e32 v200, 0x48090, v194
	v_mov_b32_e32 v201, v159
	v_pk_fma_f32 v[150:151], v[134:135], s[78:79], v[150:151] op_sel_hi:[1,0,1]
	v_pk_fma_f32 v[134:135], v[134:135], s[78:79], v[142:143] op_sel_hi:[1,0,1]
	v_lshl_add_u64 v[140:141], v[140:141], 2, s[90:91]
	v_pk_fma_f32 v[154:155], v[130:131], s[78:79], v[154:155] op_sel_hi:[1,0,1]
	v_pk_fma_f32 v[152:153], v[128:129], s[78:79], v[152:153] op_sel_hi:[1,0,1]
	v_lshl_add_u64 v[200:201], v[200:201], 2, s[90:91]
	v_sub_f32_e32 v145, v145, v198
	v_sub_f32_e32 v144, v144, v198
	global_store_dwordx4 v[140:141], v[132:135], off
	global_store_dwordx4 v[200:201], v[152:155], off
	v_sub_f32_e32 v147, v147, v198
	v_sub_f32_e32 v133, v137, v196
	v_sub_f32_e32 v132, v136, v196
	v_add_u32_e32 v152, 0x50080, v194
	v_mov_b32_e32 v153, v159
	v_sub_f32_e32 v146, v146, v198
	v_pk_mul_f32 v[144:145], v[198:199], v[144:145] op_sel:[1,0]
	v_sub_f32_e32 v135, v139, v196
	v_sub_f32_e32 v134, v138, v196
	v_pk_mul_f32 v[132:133], v[196:197], v[132:133] op_sel:[1,0]
	v_lshl_add_u64 v[152:153], v[152:153], 2, s[90:91]
	v_pk_mul_f32 v[146:147], v[198:199], v[146:147] op_sel:[1,0]
	v_pk_fma_f32 v[144:145], v[208:209], v[144:145], v[8:9]
	v_pk_mul_f32 v[134:135], v[196:197], v[134:135] op_sel:[1,0]
	v_pk_fma_f32 v[132:133], v[208:209], v[132:133], v[0:1]
	v_add_u32_e32 v210, 0x48080, v194
	v_mov_b32_e32 v211, v159
	global_store_dwordx4 v[152:153], v[148:151], off
	v_pk_fma_f32 v[146:147], v[206:207], v[146:147], v[10:11]
	v_pk_fma_f32 v[144:145], v[128:129], s[78:79], v[144:145] op_sel_hi:[1,0,1]
	v_add_u32_e32 v148, 0x50090, v194
	v_mov_b32_e32 v149, v159
	v_pk_fma_f32 v[134:135], v[206:207], v[134:135], v[2:3]
	v_pk_fma_f32 v[128:129], v[128:129], s[78:79], v[132:133] op_sel_hi:[1,0,1]
	v_add_u32_e32 v132, 0x58090, v194
	v_mov_b32_e32 v133, v159
	v_lshl_add_u64 v[210:211], v[210:211], 2, s[90:91]
	v_pk_fma_f32 v[146:147], v[130:131], s[78:79], v[146:147] op_sel_hi:[1,0,1]
	v_lshl_add_u64 v[148:149], v[148:149], 2, s[90:91]
	v_pk_fma_f32 v[130:131], v[130:131], s[78:79], v[134:135] op_sel_hi:[1,0,1]
	v_lshl_add_u64 v[132:133], v[132:133], 2, s[90:91]
	global_store_dwordx4 v[210:211], v[202:205], off
	global_store_dwordx4 v[148:149], v[144:147], off
	global_store_dwordx4 v[132:133], v[128:131], off
	s_mov_b64 s[24:25], 0
	s_branch .LBB0_324
